# packed f32 VALU ops split into scalar ops in every phase (P0, SWA prompt, P3, GEMM epilogues, P8 too)
# speedup vs baseline: 1.0010x; 1.0010x over previous
; __device__ __forceinline__ unsigned cvt_pk_bf16(float lo, float hi) { unsigned r; asm volatile("v_cvt_pk_bf16_f32 %0, %1, %2" : "=v"(r) : "v"(lo), "v"(hi)); return r; }
; __device__ __forceinline__ void phase0(const Args& a, unsigned char* lds, int tid) {
;     ...
;     for (int m = gw; m < M; m += NGW) {
;         const float* xr = m < MP ? a.xp + (size_t)m * DM : a.xs + (size_t)(m - MP) * DM;
;         f32x4 v[8]; float s = 0.f;
; #pragma unroll
;         for (int j = 0; j < 8; ++j) { v[j] = ((const f32x4*)xr)[lane + 64 * j]; s += (v[j][0] * v[j][0] + v[j][1] * v[j][1]) + (v[j][2] * v[j][2] + v[j][3] * v[j][3]); }
;         s = wave_sum(s); const float rs1 = rsqrtf(s * (1.0f / DM) + EPS);
;         u32x2* o = (u32x2*)(XB + (size_t)m * DM);
; #pragma unroll
;         for (int j = 0; j < 8; ++j) { u32x2 w; w.x = cvt_pk_bf16(v[j][0] * rs1, v[j][1] * rs1); w.y = cvt_pk_bf16(v[j][2] * rs1, v[j][3] * rs1); o[lane + 64 * j] = w; }
;     }
.LBB0_125:
	s_or_b64 exec, exec, s[16:17]
	v_lshl_add_u64 v[46:47], v[22:23], 0, v[8:9]
	global_load_dwordx4 v[30:33], v[46:47], off nt
	global_load_dwordx4 v[34:37], v[46:47], off offset:1024 nt
	global_load_dwordx4 v[38:41], v[46:47], off offset:2048 nt
	v_lshl_add_u64 v[42:43], v[22:23], 0, v[10:11]
	global_load_dwordx4 v[42:45], v[42:43], off nt
	s_nop 0
	global_load_dwordx4 v[46:49], v[46:47], off offset:3072 nt
	v_lshl_add_u64 v[50:51], v[22:23], 0, v[12:13]
	global_load_dwordx4 v[50:53], v[50:51], off nt
	v_lshl_add_u64 v[54:55], v[22:23], 0, v[16:17]
	v_lshl_add_u64 v[22:23], v[22:23], 0, v[14:15]
	global_load_dwordx4 v[58:61], v[22:23], off nt
	v_lshlrev_b64 v[20:21], 12, v[20:21]
	global_load_dwordx4 v[54:57], v[54:55], off nt
	v_lshl_add_u64 v[20:21], v[4:5], 0, v[20:21]
	v_lshl_add_u64 v[18:19], v[18:19], 0, s[88:89]
	v_lshl_add_u64 v[6:7], v[6:7], 0, s[4:5]
	s_waitcnt vmcnt(7)
	v_mov_b32_e32 v62, v31
	s_waitcnt vmcnt(6)
	v_mov_b32_e32 v63, v35
	v_mov_b32_e32 v66, v33
	v_mov_b32_e32 v67, v37
	v_mov_b32_e32 v22, v30
	v_mov_b32_e32 v23, v34
	v_mov_b32_e32 v64, v32
	v_mov_b32_e32 v65, v36
	s_waitcnt vmcnt(5)
	v_mul_f32_e32 v68, v40, v40
	v_mul_f32_e32 v69, v41, v41
	v_mul_f32_e32 v70, v38, v38
	v_mul_f32_e32 v71, v39, v39
	v_mul_f32_e32 v62, v62, v62
	v_mul_f32_e32 v63, v63, v63
	v_mul_f32_e32 v66, v66, v66
	v_mul_f32_e32 v67, v67, v67
	v_pk_mov_b32 v[82:83], v[70:71], v[68:69] op_sel:[1,0]
	v_mov_b32_e32 v71, v69
	v_fma_f32 v22, v22, v22, v62
	v_fma_f32 v23, v23, v23, v63
	v_fma_f32 v62, v64, v64, v66
	v_fma_f32 v63, v65, v65, v67
	s_waitcnt vmcnt(3)
	v_mul_f32_e32 v2, v47, v47
	v_mul_f32_e32 v72, v49, v49
	v_add_f32_e32 v64, v82, v70
	v_add_f32_e32 v65, v83, v71
	v_add_f32_e32 v22, v22, v62
	v_add_f32_e32 v23, v23, v63
	v_mul_f32_e32 v81, v42, v42
	v_mul_f32_e32 v86, v43, v43
	v_mul_f32_e32 v87, v44, v44
	v_mul_f32_e32 v88, v45, v45
	v_fma_f32 v68, v46, v46, v2
	v_fma_f32 v69, v47, v47, v2
	v_fma_f32 v73, v49, v49, v72
	v_fmac_f32_e32 v72, v48, v48
	v_add_f32_e32 v62, v64, v65
	v_add_f32_e32 v63, v65, v64
	v_pk_add_f32 v[22:23], v[22:23], v[22:23] op_sel:[0,1] op_sel_hi:[1,0]
	s_waitcnt vmcnt(2)
	v_mul_f32_e32 v74, v52, v52
	v_mul_f32_e32 v75, v53, v53
	v_mul_f32_e32 v76, v50, v50
	v_mul_f32_e32 v77, v51, v51
	v_mov_b32_e32 v69, v87
	v_mov_b32_e32 v73, v88
	v_mov_b32_e32 v63, v86
	v_mov_b32_e32 v23, v81
	v_pk_mov_b32 v[84:85], v[76:77], v[74:75] op_sel:[1,0]
	v_mov_b32_e32 v77, v75
	v_add_f32_e32 v64, v68, v72
	v_add_f32_e32 v65, v69, v73
	v_add_f32_e32 v22, v22, v62
	v_add_f32_e32 v23, v23, v63
	s_waitcnt vmcnt(1)
	v_mul_f32_e32 v78, v59, v59
	v_mul_f32_e32 v80, v61, v61
	v_add_f32_e32 v66, v84, v76
	v_add_f32_e32 v67, v85, v77
	v_add_f32_e32 v22, v22, v64
	v_add_f32_e32 v23, v23, v65
	s_waitcnt vmcnt(0)
	v_mul_f32_e32 v89, v54, v54
	v_mul_f32_e32 v90, v55, v55
	v_mul_f32_e32 v91, v56, v56
	v_mul_f32_e32 v92, v57, v57
	v_fma_f32 v74, v58, v58, v78
	v_fma_f32 v75, v59, v59, v78
	v_fma_f32 v78, v60, v60, v80
	v_fma_f32 v79, v61, v61, v80
	v_pk_add_f32 v[66:67], v[66:67], v[66:67] op_sel:[0,1] op_sel_hi:[1,0]
	v_pk_add_f32 v[22:23], v[22:23], v[22:23] op_sel:[0,1] op_sel_hi:[1,0]
	v_mov_b32_e32 v75, v91
	v_mov_b32_e32 v79, v92
	v_mov_b32_e32 v67, v90
	v_mov_b32_e32 v23, v89
	v_add_f32_e32 v68, v74, v78
	v_add_f32_e32 v69, v75, v79
	v_add_f32_e32 v22, v22, v66
	v_add_f32_e32 v23, v23, v67
	s_nop 0
	v_add_f32_e32 v22, v22, v68
	v_add_f32_e32 v23, v23, v69
	s_nop 0
	v_add_f32_e32 v2, v22, v23
	ds_bpermute_b32 v22, v1, v2
	s_waitcnt lgkmcnt(0)
	v_add_f32_e32 v2, v2, v22
	ds_bpermute_b32 v22, v24, v2
	s_waitcnt lgkmcnt(0)
	v_add_f32_e32 v2, v2, v22
	ds_bpermute_b32 v22, v25, v2
	s_waitcnt lgkmcnt(0)
	v_add_f32_e32 v2, v2, v22
	ds_bpermute_b32 v22, v26, v2
	s_waitcnt lgkmcnt(0)
	v_add_f32_e32 v2, v2, v22
	ds_bpermute_b32 v22, v27, v2
	s_waitcnt lgkmcnt(0)
	v_add_f32_e32 v2, v2, v22
	ds_bpermute_b32 v22, v28, v2
	s_waitcnt lgkmcnt(0)
	v_add_f32_e32 v2, v2, v22
	v_fmamk_f32 v2, v2, 0x3a000000, v29
	v_mul_f32_e32 v22, 0x4b800000, v2
	v_cmp_gt_f32_e32 vcc, s18, v2
	s_nop 1
	v_cndmask_b32_e32 v2, v2, v22, vcc
	v_rsq_f32_e32 v2, v2
	s_nop 0
	v_mul_f32_e32 v22, 0x45800000, v2
	v_cndmask_b32_e32 v2, v2, v22, vcc
	v_mul_f32_e32 v22, v30, v2
	v_mul_f32_e32 v23, v31, v2
	v_mul_f32_e32 v30, v32, v2
	v_mul_f32_e32 v31, v33, v2
	v_cvt_pk_bf16_f32 v22, v22, v23
	v_cvt_pk_bf16_f32 v23, v30, v31
	v_mul_f32_e32 v32, v34, v2
	v_mul_f32_e32 v33, v35, v2
	v_mul_f32_e32 v34, v36, v2
	v_mul_f32_e32 v35, v37, v2
	global_store_dwordx2 v[20:21], v[22:23], off
	v_cvt_pk_bf16_f32 v22, v32, v33
	v_cvt_pk_bf16_f32 v23, v34, v35
	v_mul_f32_e32 v36, v38, v2
	v_mul_f32_e32 v37, v39, v2
	v_mul_f32_e32 v38, v40, v2
	v_mul_f32_e32 v39, v41, v2
	global_store_dwordx2 v[20:21], v[22:23], off offset:512
	v_cvt_pk_bf16_f32 v22, v36, v37
	v_cvt_pk_bf16_f32 v23, v38, v39
	v_mul_f32_e32 v40, v46, v2
	v_mul_f32_e32 v41, v47, v2
	v_mul_f32_e32 v46, v48, v2
	v_mul_f32_e32 v47, v49, v2
	global_store_dwordx2 v[20:21], v[22:23], off offset:1024
	v_cvt_pk_bf16_f32 v22, v40, v41
	v_cvt_pk_bf16_f32 v23, v46, v47
	v_mul_f32_e32 v42, v42, v2
	v_mul_f32_e32 v43, v43, v2
	v_mul_f32_e32 v44, v44, v2
	v_mul_f32_e32 v45, v45, v2
	global_store_dwordx2 v[20:21], v[22:23], off offset:1536
	v_cvt_pk_bf16_f32 v22, v42, v43
	v_cvt_pk_bf16_f32 v23, v44, v45
	v_mul_f32_e32 v48, v50, v2
	v_mul_f32_e32 v49, v51, v2
	v_mul_f32_e32 v50, v52, v2
	v_mul_f32_e32 v51, v53, v2
	global_store_dwordx2 v[20:21], v[22:23], off offset:2048
	v_cvt_pk_bf16_f32 v22, v48, v49
	v_cvt_pk_bf16_f32 v23, v50, v51
	v_cmp_lt_i32_e32 vcc, s19, v18
	v_mul_f32_e32 v52, v58, v2
	v_mul_f32_e32 v53, v59, v2
	v_mul_f32_e32 v58, v60, v2
	v_mul_f32_e32 v59, v61, v2
	global_store_dwordx2 v[20:21], v[22:23], off offset:2560
	v_cvt_pk_bf16_f32 v22, v52, v53
	v_cvt_pk_bf16_f32 v23, v58, v59
	s_or_b64 s[6:7], vcc, s[6:7]
	v_mul_f32_e32 v54, v54, v2
	v_mul_f32_e32 v55, v55, v2
	v_mul_f32_e32 v56, v56, v2
	v_mul_f32_e32 v2, v57, v2
	global_store_dwordx2 v[20:21], v[22:23], off offset:3072
	v_cvt_pk_bf16_f32 v22, v54, v55
	v_cvt_pk_bf16_f32 v23, v56, v2
	global_store_dwordx2 v[20:21], v[22:23], off offset:3584
	s_andn2_b64 exec, exec, s[6:7]
	s_cbranch_execz .LBB0_128

; __device__ __forceinline__ unsigned cvt_pk_bf16(float lo, float hi) { unsigned r; asm volatile("v_cvt_pk_bf16_f32 %0, %1, %2" : "=v"(r) : "v"(lo), "v"(hi)); return r; }
; __device__ __forceinline__ float bflo(unsigned w) { return __uint_as_float(w << 16); }
; __device__ __forceinline__ float bfhi(unsigned w) { return __uint_as_float(w & 0xffff0000u); }
; __device__ __forceinline__ void swa_prompt_unit(const Args& a, unsigned char* lds, int unit, int tid) {
;     ...
;         if (c < 2 && valid) { const u32x4 pr = *(const u32x4*)(Z + row * DINP + ZKS + kvh * 64 + (c ^ 1) * 8);
;             float pf[8]; pf[0] = bflo(pr.x); pf[1] = bfhi(pr.x); pf[2] = bflo(pr.y); pf[3] = bfhi(pr.y); pf[4] = bflo(pr.z); pf[5] = bfhi(pr.z); pf[6] = bflo(pr.w); pf[7] = bfhi(pr.w);
;             const f32x2* rp = ROPE + kpos * 8; const float sg = c == 0 ? -1.f : 1.f;
; #pragma unroll
;             for (int d = 0; d < 8; ++d) { const f32x2 cs = rp[d]; kf[d] = kf[d] * cs.x + sg * pf[d] * cs.y; }
;             raw.x = cvt_pk_bf16(kf[0], kf[1]); raw.y = cvt_pk_bf16(kf[2], kf[3]); raw.z = cvt_pk_bf16(kf[4], kf[5]); raw.w = cvt_pk_bf16(kf[6], kf[7]);
.LBB0_260:
	v_mov_b64_e32 v[12:13], s[74:75]
	v_mad_u64_u32 v[12:13], s[28:29], v10, s89, v[12:13]
	v_mad_i32_i24 v13, v11, s89, v13
	s_lshl_b32 s62, s26, 1
	v_lshl_add_u64 v[10:11], v[12:13], 0, s[62:63]
	v_mov_b32_e32 v19, v0
	v_lshl_add_u64 v[10:11], v[10:11], 0, v[18:19]
	v_readlane_b32 s28, v249, 41
	global_load_dwordx4 v[10:13], v[10:11], off offset:2048
	v_lshlrev_b32_e32 v14, 3, v1
	v_mov_b32_e32 v15, v0
	v_readlane_b32 s29, v249, 42
	s_waitcnt vmcnt(2)
	v_lshlrev_b32_e32 v34, 16, v7
	v_and_b32_e32 v36, 0xffff0000, v7
	v_lshl_add_u64 v[28:29], v[14:15], 3, s[28:29]
	global_load_dwordx4 v[14:17], v[28:29], off
	global_load_dwordx4 v[20:23], v[28:29], off offset:16
	global_load_dwordx4 v[24:27], v[28:29], off offset:32
	s_nop 0
	global_load_dwordx4 v[28:31], v[28:29], off offset:48
	v_lshlrev_b32_e32 v40, 16, v9
	v_and_b32_e32 v42, 0xffff0000, v9
	v_lshlrev_b32_e32 v32, 16, v6
	v_and_b32_e32 v6, 0xffff0000, v6
	v_lshlrev_b32_e32 v38, 16, v8
	v_and_b32_e32 v8, 0xffff0000, v8
	s_waitcnt vmcnt(4)
	v_lshlrev_b32_e32 v1, 16, v10
	v_and_b32_e32 v7, 0xffff0000, v10
	v_lshlrev_b32_e32 v9, 16, v11
	v_and_b32_e32 v10, 0xffff0000, v11
	v_lshlrev_b32_e32 v11, 16, v12
	v_and_b32_e32 v12, 0xffff0000, v12
	v_lshlrev_b32_e32 v19, 16, v13
	v_and_b32_e32 v13, 0xffff0000, v13
	v_cndmask_b32_e64 v7, v7, -v7, s[8:9]
	v_cndmask_b32_e64 v35, v9, -v9, s[8:9]
	v_cndmask_b32_e64 v9, v12, -v12, s[8:9]
	v_cndmask_b32_e64 v41, v19, -v19, s[8:9]
	v_cndmask_b32_e64 v33, v1, -v1, s[8:9]
	v_cndmask_b32_e64 v37, v10, -v10, s[8:9]
	v_cndmask_b32_e64 v39, v11, -v11, s[8:9]
	v_cndmask_b32_e64 v43, v13, -v13, s[8:9]
	s_waitcnt vmcnt(3)
	v_mul_f32_e32 v6, v16, v6
	v_mul_f32_e32 v7, v17, v7
	s_waitcnt vmcnt(2)
	v_mul_f32_e32 v12, v20, v34
	v_mul_f32_e32 v13, v21, v35
	s_waitcnt vmcnt(1)
	v_mul_f32_e32 v8, v26, v8
	v_mul_f32_e32 v9, v27, v9
	s_waitcnt vmcnt(0)
	v_mul_f32_e32 v20, v28, v40
	v_mul_f32_e32 v21, v29, v41
	v_mul_f32_e32 v10, v14, v32
	v_mul_f32_e32 v11, v15, v33
	v_mul_f32_e32 v14, v22, v36
	v_mul_f32_e32 v15, v23, v37
	v_mul_f32_e32 v16, v24, v38
	v_mul_f32_e32 v17, v25, v39
	v_mul_f32_e32 v22, v30, v42
	v_mul_f32_e32 v23, v31, v43
	v_add_f32_e32 v6, v6, v7
	v_add_f32_e32 v7, v12, v13
	v_add_f32_e32 v8, v8, v9
	v_add_f32_e32 v9, v20, v21
	v_add_f32_e32 v1, v10, v11
	v_add_f32_e32 v10, v14, v15
	v_add_f32_e32 v11, v16, v17
	v_add_f32_e32 v12, v22, v23
	v_cvt_pk_bf16_f32 v6, v1, v6
	v_cvt_pk_bf16_f32 v7, v7, v10
	v_cvt_pk_bf16_f32 v8, v11, v8
	v_cvt_pk_bf16_f32 v9, v9, v12

; __device__ __forceinline__ unsigned cvt_pk_bf16(float lo, float hi) { unsigned r; asm volatile("v_cvt_pk_bf16_f32 %0, %1, %2" : "=v"(r) : "v"(lo), "v"(hi)); return r; }
; __device__ __forceinline__ float bflo(unsigned w) { return __uint_as_float(w << 16); }
; __device__ __forceinline__ float bfhi(unsigned w) { return __uint_as_float(w & 0xffff0000u); }
; __device__ __forceinline__ void swa_prompt_unit(const Args& a, unsigned char* lds, int unit, int tid) {
;     ...
;         if (valid) { raw = *(const u32x4*)(Z + row * DINP + ZKS + kvh * 64 + c * 8); rawv = *(const u32x4*)(Z + row * DINP + ZVS + kvh * 64 + c * 8); }
;         kf[0] = bflo(raw.x); kf[1] = bfhi(raw.x); kf[2] = bflo(raw.y); kf[3] = bfhi(raw.y); kf[4] = bflo(raw.z); kf[5] = bfhi(raw.z); kf[6] = bflo(raw.w); kf[7] = bfhi(raw.w);
;         if (c < 2 && valid) { const u32x4 pr = *(const u32x4*)(Z + row * DINP + ZKS + kvh * 64 + (c ^ 1) * 8);
;             float pf[8]; pf[0] = bflo(pr.x); pf[1] = bfhi(pr.x); pf[2] = bflo(pr.y); pf[3] = bfhi(pr.y); pf[4] = bflo(pr.z); pf[5] = bfhi(pr.z); pf[6] = bflo(pr.w); pf[7] = bfhi(pr.w);
;             const f32x2* rp = ROPE + kpos * 8; const float sg = c == 0 ? -1.f : 1.f;
; #pragma unroll
;             for (int d = 0; d < 8; ++d) { const f32x2 cs = rp[d]; kf[d] = kf[d] * cs.x + sg * pf[d] * cs.y; }
;             raw.x = cvt_pk_bf16(kf[0], kf[1]); raw.y = cvt_pk_bf16(kf[2], kf[3]); raw.z = cvt_pk_bf16(kf[4], kf[5]); raw.w = cvt_pk_bf16(kf[6], kf[7]);
;             kf[0] = bflo(raw.x); kf[1] = bfhi(raw.x); kf[2] = bflo(raw.y); kf[3] = bfhi(raw.y); kf[4] = bflo(raw.z); kf[5] = bfhi(raw.z); kf[6] = bflo(raw.w); kf[7] = bfhi(raw.w); }
.LBB0_263:
	s_or_b64 exec, exec, s[18:19]
	s_waitcnt vmcnt(1)
	v_lshlrev_b32_e32 v10, 16, v14
	v_and_b32_e32 v11, 0xffff0000, v14
	v_lshlrev_b32_e32 v12, 16, v15
	v_and_b32_e32 v13, 0xffff0000, v15
	v_lshlrev_b32_e32 v6, 16, v16
	v_and_b32_e32 v7, 0xffff0000, v16
	v_lshlrev_b32_e32 v8, 16, v17
	v_and_b32_e32 v9, 0xffff0000, v17
	s_and_b64 s[28:29], s[4:5], vcc
	s_and_saveexec_b64 s[18:19], s[28:29]
	s_cbranch_execz .LBB0_265
	v_mov_b64_e32 v[14:15], s[74:75]
	v_mad_u64_u32 v[14:15], s[28:29], v20, s89, v[14:15]
	v_mad_i32_i24 v15, v21, s89, v15
	s_lshl_b32 s62, s26, 1
	v_lshl_add_u64 v[14:15], v[14:15], 0, s[62:63]
	v_mov_b32_e32 v19, v0
	v_lshl_add_u64 v[14:15], v[14:15], 0, v[18:19]
	v_readlane_b32 s28, v249, 41
	global_load_dwordx4 v[14:17], v[14:15], off offset:2048
	v_lshlrev_b32_e32 v20, 3, v1
	v_mov_b32_e32 v21, v0
	v_readlane_b32 s29, v249, 42
	v_mov_b32_e32 v40, v7
	v_mov_b32_e32 v42, v9
	v_lshl_add_u64 v[32:33], v[20:21], 3, s[28:29]
	global_load_dwordx4 v[20:23], v[32:33], off
	global_load_dwordx4 v[24:27], v[32:33], off offset:16
	global_load_dwordx4 v[28:31], v[32:33], off offset:32
	s_nop 0
	global_load_dwordx4 v[32:35], v[32:33], off offset:48
	v_mov_b32_e32 v36, v11
	v_mov_b32_e32 v38, v13
	s_waitcnt vmcnt(4)
	v_lshlrev_b32_e32 v1, 16, v14
	v_and_b32_e32 v7, 0xffff0000, v14
	v_lshlrev_b32_e32 v9, 16, v15
	v_and_b32_e32 v14, 0xffff0000, v15
	v_lshlrev_b32_e32 v15, 16, v16
	v_and_b32_e32 v16, 0xffff0000, v16
	v_lshlrev_b32_e32 v19, 16, v17
	v_and_b32_e32 v17, 0xffff0000, v17
	v_cndmask_b32_e64 v11, v1, -v1, s[8:9]
	v_cndmask_b32_e64 v37, v7, -v7, s[8:9]
	v_cndmask_b32_e64 v13, v9, -v9, s[8:9]
	v_cndmask_b32_e64 v39, v14, -v14, s[8:9]
	v_cndmask_b32_e64 v7, v15, -v15, s[8:9]
	v_cndmask_b32_e64 v41, v16, -v16, s[8:9]
	v_cndmask_b32_e64 v9, v19, -v19, s[8:9]
	v_cndmask_b32_e64 v43, v17, -v17, s[8:9]
	s_waitcnt vmcnt(3)
	v_mul_f32_e32 v10, v20, v10
	v_mul_f32_e32 v11, v21, v11
	v_mul_f32_e32 v14, v22, v36
	v_mul_f32_e32 v15, v23, v37
	s_waitcnt vmcnt(2)
	v_mul_f32_e32 v12, v24, v12
	v_mul_f32_e32 v13, v25, v13
	v_mul_f32_e32 v16, v26, v38
	v_mul_f32_e32 v17, v27, v39
	s_waitcnt vmcnt(1)
	v_mul_f32_e32 v6, v28, v6
	v_mul_f32_e32 v7, v29, v7
	v_mul_f32_e32 v20, v30, v40
	v_mul_f32_e32 v21, v31, v41
	s_waitcnt vmcnt(0)
	v_mul_f32_e32 v8, v32, v8
	v_mul_f32_e32 v9, v33, v9
	v_mul_f32_e32 v22, v34, v42
	v_mul_f32_e32 v23, v35, v43
	v_add_f32_e32 v1, v10, v11
	v_add_f32_e32 v10, v14, v15
	v_add_f32_e32 v11, v12, v13
	v_add_f32_e32 v12, v16, v17
	v_add_f32_e32 v6, v6, v7
	v_add_f32_e32 v7, v20, v21
	v_add_f32_e32 v8, v8, v9
	v_add_f32_e32 v9, v22, v23
	v_cvt_pk_bf16_f32 v14, v1, v10
	v_cvt_pk_bf16_f32 v15, v11, v12
	v_cvt_pk_bf16_f32 v16, v6, v7
	v_cvt_pk_bf16_f32 v17, v8, v9
	s_nop 0
	v_lshlrev_b32_e32 v10, 16, v14
	v_and_b32_e32 v11, 0xffff0000, v14
	v_lshlrev_b32_e32 v12, 16, v15
	v_and_b32_e32 v13, 0xffff0000, v15
	v_lshlrev_b32_e32 v6, 16, v16
	v_and_b32_e32 v7, 0xffff0000, v16
	v_lshlrev_b32_e32 v8, 16, v17
	v_and_b32_e32 v9, 0xffff0000, v17

; __device__ __forceinline__ unsigned cvt_pk_bf16(float lo, float hi) { unsigned r; asm volatile("v_cvt_pk_bf16_f32 %0, %1, %2" : "=v"(r) : "v"(lo), "v"(hi)); return r; }
; __device__ __forceinline__ float bflo(unsigned w) { return __uint_as_float(w << 16); }
; __device__ __forceinline__ float bfhi(unsigned w) { return __uint_as_float(w & 0xffff0000u); }
; __device__ __forceinline__ void swa_prompt_unit(const Args& a, unsigned char* lds, int unit, int tid) {
;     ...
;     for (int it = 0; it < 4; ++it) { const int e = tid + it * 512, j = e >> 3, c = e & 7; const int kpos = (blk - 1) * 128 + j; const bool valid = kpos >= 0;
;         const size_t row = (size_t)b * 2048 + (valid ? kpos : 0);
;         u32x4 raw = (u32x4){0u, 0u, 0u, 0u}, rawv = (u32x4){0u, 0u, 0u, 0u}; float kf[8];
;         if (valid) { raw = *(const u32x4*)(Z + row * DINP + ZKS + kvh * 64 + c * 8); rawv = *(const u32x4*)(Z + row * DINP + ZVS + kvh * 64 + c * 8); }
;         kf[0] = bflo(raw.x); kf[1] = bfhi(raw.x); kf[2] = bflo(raw.y); kf[3] = bfhi(raw.y); kf[4] = bflo(raw.z); kf[5] = bfhi(raw.z); kf[6] = bflo(raw.w); kf[7] = bfhi(raw.w);
;         if (c < 2 && valid) { const u32x4 pr = *(const u32x4*)(Z + row * DINP + ZKS + kvh * 64 + (c ^ 1) * 8);
;             float pf[8]; pf[0] = bflo(pr.x); pf[1] = bfhi(pr.x); pf[2] = bflo(pr.y); pf[3] = bfhi(pr.y); pf[4] = bflo(pr.z); pf[5] = bfhi(pr.z); pf[6] = bflo(pr.w); pf[7] = bfhi(pr.w);
;             const f32x2* rp = ROPE + kpos * 8; const float sg = c == 0 ? -1.f : 1.f;
; #pragma unroll
;             for (int d = 0; d < 8; ++d) { const f32x2 cs = rp[d]; kf[d] = kf[d] * cs.x + sg * pf[d] * cs.y; }
;             raw.x = cvt_pk_bf16(kf[0], kf[1]); raw.y = cvt_pk_bf16(kf[2], kf[3]); raw.z = cvt_pk_bf16(kf[4], kf[5]); raw.w = cvt_pk_bf16(kf[6], kf[7]);
;             kf[0] = bflo(raw.x); kf[1] = bfhi(raw.x); kf[2] = bflo(raw.y); kf[3] = bfhi(raw.y); kf[4] = bflo(raw.z); kf[5] = bfhi(raw.z); kf[6] = bflo(raw.w); kf[7] = bfhi(raw.w); }
.LBB0_267:
	s_or_b64 exec, exec, s[18:19]
	v_add_u32_e32 v20, s25, v104
	v_mov_b32_e32 v21, v0
	v_lshl_add_u64 v[2:3], s[20:21], 0, v[20:21]
	v_mov_b64_e32 v[4:5], s[74:75]
	v_mad_u64_u32 v[4:5], s[18:19], v2, s89, v[4:5]
	v_mad_i32_i24 v5, v3, s89, v5
	s_lshl_b32 s62, s26, 1
	v_lshl_add_u64 v[22:23], v[4:5], 0, s[62:63]
	v_mov_b32_e32 v95, v0
	v_lshl_add_u64 v[2:3], v[22:23], 0, v[94:95]
	global_load_dwordx4 v[14:17], v[2:3], off offset:2048
	s_nop 0
	global_load_dwordx4 v[2:5], v[2:3], off offset:2560
	s_waitcnt vmcnt(1)
	v_lshlrev_b32_e32 v10, 16, v14
	v_and_b32_e32 v11, 0xffff0000, v14
	v_lshlrev_b32_e32 v12, 16, v15
	v_and_b32_e32 v13, 0xffff0000, v15
	v_lshlrev_b32_e32 v6, 16, v16
	v_and_b32_e32 v7, 0xffff0000, v16
	v_lshlrev_b32_e32 v8, 16, v17
	v_and_b32_e32 v9, 0xffff0000, v17
	s_and_saveexec_b64 s[18:19], s[6:7]
	s_xor_b64 s[18:19], exec, s[18:19]
	s_andn2_saveexec_b64 s[18:19], s[18:19]
	s_cbranch_execz .LBB0_271
	v_mov_b32_e32 v19, v0
	v_lshl_add_u64 v[14:15], v[22:23], 0, v[18:19]
	v_readlane_b32 s26, v249, 41
	global_load_dwordx4 v[14:17], v[14:15], off offset:2048
	v_lshlrev_b32_e32 v20, 3, v20
	v_mov_b32_e32 v21, v0
	v_readlane_b32 s27, v249, 42
	v_mov_b32_e32 v38, v13
	v_mov_b32_e32 v40, v7
	v_lshl_add_u64 v[32:33], v[20:21], 3, s[26:27]
	global_load_dwordx4 v[20:23], v[32:33], off
	global_load_dwordx4 v[24:27], v[32:33], off offset:16
	global_load_dwordx4 v[28:31], v[32:33], off offset:32
	s_nop 0
	global_load_dwordx4 v[32:35], v[32:33], off offset:48
	v_mov_b32_e32 v42, v9
	v_mov_b32_e32 v36, v11
	s_waitcnt vmcnt(4)
	v_lshlrev_b32_e32 v7, 16, v14
	v_and_b32_e32 v9, 0xffff0000, v14
	v_lshlrev_b32_e32 v13, 16, v15
	v_and_b32_e32 v14, 0xffff0000, v15
	v_lshlrev_b32_e32 v15, 16, v16
	v_and_b32_e32 v16, 0xffff0000, v16
	v_lshlrev_b32_e32 v19, 16, v17
	v_and_b32_e32 v17, 0xffff0000, v17
	v_cndmask_b32_e64 v11, v7, -v7, s[8:9]
	v_cndmask_b32_e64 v37, v9, -v9, s[8:9]
	v_cndmask_b32_e64 v13, v13, -v13, s[8:9]
	v_cndmask_b32_e64 v39, v14, -v14, s[8:9]
	v_cndmask_b32_e64 v7, v15, -v15, s[8:9]
	v_cndmask_b32_e64 v41, v16, -v16, s[8:9]
	v_cndmask_b32_e64 v9, v19, -v19, s[8:9]
	v_cndmask_b32_e64 v43, v17, -v17, s[8:9]
	s_waitcnt vmcnt(3)
	v_mul_f32_e32 v10, v20, v10
	v_mul_f32_e32 v11, v21, v11
	v_mul_f32_e32 v14, v22, v36
	v_mul_f32_e32 v15, v23, v37
	s_waitcnt vmcnt(2)
	v_mul_f32_e32 v12, v24, v12
	v_mul_f32_e32 v13, v25, v13
	v_mul_f32_e32 v16, v26, v38
	v_mul_f32_e32 v17, v27, v39
	s_waitcnt vmcnt(1)
	v_mul_f32_e32 v6, v28, v6
	v_mul_f32_e32 v7, v29, v7
	v_mul_f32_e32 v20, v30, v40
	v_mul_f32_e32 v21, v31, v41
	s_waitcnt vmcnt(0)
	v_mul_f32_e32 v8, v32, v8
	v_mul_f32_e32 v9, v33, v9
	v_mul_f32_e32 v22, v34, v42
	v_mul_f32_e32 v23, v35, v43
	v_add_f32_e32 v10, v10, v11
	v_add_f32_e32 v11, v14, v15
	v_add_f32_e32 v12, v12, v13
	v_add_f32_e32 v13, v16, v17
	v_add_f32_e32 v6, v6, v7
	v_add_f32_e32 v7, v20, v21
	v_add_f32_e32 v8, v8, v9
	v_add_f32_e32 v9, v22, v23
	v_cvt_pk_bf16_f32 v14, v10, v11
	v_cvt_pk_bf16_f32 v15, v12, v13
	v_cvt_pk_bf16_f32 v16, v6, v7
	v_cvt_pk_bf16_f32 v17, v8, v9
	s_nop 0
	v_lshlrev_b32_e32 v10, 16, v14
	v_and_b32_e32 v11, 0xffff0000, v14
	v_lshlrev_b32_e32 v12, 16, v15
	v_and_b32_e32 v13, 0xffff0000, v15
	v_lshlrev_b32_e32 v6, 16, v16
	v_and_b32_e32 v7, 0xffff0000, v16
	v_lshlrev_b32_e32 v8, 16, v17
	v_and_b32_e32 v9, 0xffff0000, v17

; __device__ __forceinline__ unsigned cvt_pk_bf16(float lo, float hi) { unsigned r; asm volatile("v_cvt_pk_bf16_f32 %0, %1, %2" : "=v"(r) : "v"(lo), "v"(hi)); return r; }
; __device__ __forceinline__ float bflo(unsigned w) { return __uint_as_float(w << 16); }
; __device__ __forceinline__ float bfhi(unsigned w) { return __uint_as_float(w & 0xffff0000u); }
; __device__ __forceinline__ void swa_prompt_unit(const Args& a, unsigned char* lds, int unit, int tid) {
;     ...
;     for (int it = 0; it < 4; ++it) { const int e = tid + it * 512, j = e >> 3, c = e & 7; const int kpos = (blk - 1) * 128 + j; const bool valid = kpos >= 0;
;         const size_t row = (size_t)b * 2048 + (valid ? kpos : 0);
;         u32x4 raw = (u32x4){0u, 0u, 0u, 0u}, rawv = (u32x4){0u, 0u, 0u, 0u}; float kf[8];
;         if (valid) { raw = *(const u32x4*)(Z + row * DINP + ZKS + kvh * 64 + c * 8); rawv = *(const u32x4*)(Z + row * DINP + ZVS + kvh * 64 + c * 8); }
;         kf[0] = bflo(raw.x); kf[1] = bfhi(raw.x); kf[2] = bflo(raw.y); kf[3] = bfhi(raw.y); kf[4] = bflo(raw.z); kf[5] = bfhi(raw.z); kf[6] = bflo(raw.w); kf[7] = bfhi(raw.w);
;         if (c < 2 && valid) { const u32x4 pr = *(const u32x4*)(Z + row * DINP + ZKS + kvh * 64 + (c ^ 1) * 8);
;             float pf[8]; pf[0] = bflo(pr.x); pf[1] = bfhi(pr.x); pf[2] = bflo(pr.y); pf[3] = bfhi(pr.y); pf[4] = bflo(pr.z); pf[5] = bfhi(pr.z); pf[6] = bflo(pr.w); pf[7] = bfhi(pr.w);
;             const f32x2* rp = ROPE + kpos * 8; const float sg = c == 0 ? -1.f : 1.f;
; #pragma unroll
;             for (int d = 0; d < 8; ++d) { const f32x2 cs = rp[d]; kf[d] = kf[d] * cs.x + sg * pf[d] * cs.y; }
;             raw.x = cvt_pk_bf16(kf[0], kf[1]); raw.y = cvt_pk_bf16(kf[2], kf[3]); raw.z = cvt_pk_bf16(kf[4], kf[5]); raw.w = cvt_pk_bf16(kf[6], kf[7]);
;             kf[0] = bflo(raw.x); kf[1] = bfhi(raw.x); kf[2] = bflo(raw.y); kf[3] = bfhi(raw.y); kf[4] = bflo(raw.z); kf[5] = bfhi(raw.z); kf[6] = bflo(raw.w); kf[7] = bfhi(raw.w); }
.LBB0_273:
	v_add_u32_e32 v20, s25, v105
	v_mov_b32_e32 v21, v0
	v_lshl_add_u64 v[2:3], s[20:21], 0, v[20:21]
	v_mov_b64_e32 v[4:5], s[74:75]
	v_mad_u64_u32 v[4:5], s[20:21], v2, s89, v[4:5]
	v_mad_i32_i24 v5, v3, s89, v5
	v_lshl_add_u64 v[22:23], v[4:5], 0, s[62:63]
	v_mov_b32_e32 v95, v0
	v_lshl_add_u64 v[2:3], v[22:23], 0, v[94:95]
	global_load_dwordx4 v[14:17], v[2:3], off offset:2048
	s_nop 0
	global_load_dwordx4 v[2:5], v[2:3], off offset:2560
	s_waitcnt vmcnt(1)
	v_lshlrev_b32_e32 v10, 16, v14
	v_and_b32_e32 v11, 0xffff0000, v14
	v_lshlrev_b32_e32 v12, 16, v15
	v_and_b32_e32 v13, 0xffff0000, v15
	v_lshlrev_b32_e32 v6, 16, v16
	v_and_b32_e32 v7, 0xffff0000, v16
	v_lshlrev_b32_e32 v8, 16, v17
	v_and_b32_e32 v9, 0xffff0000, v17
	s_and_saveexec_b64 s[20:21], s[6:7]
	s_xor_b64 s[20:21], exec, s[20:21]
	s_andn2_saveexec_b64 s[20:21], s[20:21]
	s_cbranch_execz .LBB0_277
	v_mov_b32_e32 v19, v0
	v_lshl_add_u64 v[14:15], v[22:23], 0, v[18:19]
	v_readlane_b32 s22, v249, 41
	global_load_dwordx4 v[14:17], v[14:15], off offset:2048
	v_lshlrev_b32_e32 v18, 3, v20
	v_readlane_b32 s23, v249, 42
	v_mov_b32_e32 v36, v13
	v_mov_b32_e32 v38, v7
	v_lshl_add_u64 v[30:31], v[18:19], 3, s[22:23]
	global_load_dwordx4 v[18:21], v[30:31], off
	global_load_dwordx4 v[22:25], v[30:31], off offset:16
	global_load_dwordx4 v[26:29], v[30:31], off offset:32
	s_nop 0
	global_load_dwordx4 v[30:33], v[30:31], off offset:48
	v_mov_b32_e32 v40, v9
	v_mov_b32_e32 v34, v11
	s_waitcnt vmcnt(4)
	v_lshlrev_b32_e32 v7, 16, v14
	v_and_b32_e32 v9, 0xffff0000, v14
	v_lshlrev_b32_e32 v13, 16, v15
	v_and_b32_e32 v14, 0xffff0000, v15
	v_lshlrev_b32_e32 v15, 16, v16
	v_and_b32_e32 v16, 0xffff0000, v16
	v_lshlrev_b32_e32 v41, 16, v17
	v_and_b32_e32 v17, 0xffff0000, v17
	v_cndmask_b32_e64 v11, v7, -v7, s[8:9]
	v_cndmask_b32_e64 v35, v9, -v9, s[8:9]
	v_cndmask_b32_e64 v13, v13, -v13, s[8:9]
	v_cndmask_b32_e64 v37, v14, -v14, s[8:9]
	v_cndmask_b32_e64 v7, v15, -v15, s[8:9]
	v_cndmask_b32_e64 v39, v16, -v16, s[8:9]
	v_cndmask_b32_e64 v9, v41, -v41, s[8:9]
	v_cndmask_b32_e64 v41, v17, -v17, s[8:9]
	s_waitcnt vmcnt(3)
	v_mul_f32_e32 v10, v18, v10
	v_mul_f32_e32 v11, v19, v11
	v_mul_f32_e32 v14, v20, v34
	v_mul_f32_e32 v15, v21, v35
	s_waitcnt vmcnt(2)
	v_mul_f32_e32 v12, v22, v12
	v_mul_f32_e32 v13, v23, v13
	v_mul_f32_e32 v16, v24, v36
	v_mul_f32_e32 v17, v25, v37
	s_waitcnt vmcnt(1)
	v_mul_f32_e32 v6, v26, v6
	v_mul_f32_e32 v7, v27, v7
	v_mul_f32_e32 v18, v28, v38
	v_mul_f32_e32 v19, v29, v39
	s_waitcnt vmcnt(0)
	v_mul_f32_e32 v8, v30, v8
	v_mul_f32_e32 v9, v31, v9
	v_mul_f32_e32 v20, v32, v40
	v_mul_f32_e32 v21, v33, v41
	v_add_f32_e32 v10, v10, v11
	v_add_f32_e32 v11, v14, v15
	v_add_f32_e32 v12, v12, v13
	v_add_f32_e32 v13, v16, v17
	v_add_f32_e32 v6, v6, v7
	v_add_f32_e32 v7, v18, v19
	v_add_f32_e32 v8, v8, v9
	v_add_f32_e32 v9, v20, v21
	v_cvt_pk_bf16_f32 v14, v10, v11
	v_cvt_pk_bf16_f32 v15, v12, v13
	v_cvt_pk_bf16_f32 v16, v6, v7
	v_cvt_pk_bf16_f32 v17, v8, v9
	s_nop 0
	v_lshlrev_b32_e32 v10, 16, v14
	v_and_b32_e32 v11, 0xffff0000, v14
	v_lshlrev_b32_e32 v12, 16, v15
	v_and_b32_e32 v13, 0xffff0000, v15
	v_lshlrev_b32_e32 v6, 16, v16
	v_and_b32_e32 v7, 0xffff0000, v16
	v_lshlrev_b32_e32 v8, 16, v17
	v_and_b32_e32 v9, 0xffff0000, v17

; __device__ __forceinline__ unsigned cvt_pk_bf16(float lo, float hi) { unsigned r; asm volatile("v_cvt_pk_bf16_f32 %0, %1, %2" : "=v"(r) : "v"(lo), "v"(hi)); return r; }
; __device__ __forceinline__ float bflo(unsigned w) { return __uint_as_float(w << 16); }
; __device__ __forceinline__ float bfhi(unsigned w) { return __uint_as_float(w & 0xffff0000u); }
; __device__ __forceinline__ void swa_prompt_unit(const Args& a, unsigned char* lds, int unit, int tid) {
;     ...
;         for (int kk = 0; kk < 2; ++kk) { const int c = kk * 4 + q4; const bf16_t* qp = Z + row * DINP + ZQS + (kvh * 4 + g) * 64;
;             const u32x4 raw = *(const u32x4*)(qp + c * 8); float f[8];
;             f[0] = bflo(raw.x); f[1] = bfhi(raw.x); f[2] = bflo(raw.y); f[3] = bfhi(raw.y); f[4] = bflo(raw.z); f[5] = bfhi(raw.z); f[6] = bflo(raw.w); f[7] = bfhi(raw.w);
;             if (kk == 0 && q4 < 2) { const u32x4 pr = *(const u32x4*)(qp + (c ^ 1) * 8);
;                 float pf[8]; pf[0] = bflo(pr.x); pf[1] = bfhi(pr.x); pf[2] = bflo(pr.y); pf[3] = bfhi(pr.y); pf[4] = bflo(pr.z); pf[5] = bfhi(pr.z); pf[6] = bflo(pr.w); pf[7] = bfhi(pr.w);
;                 const f32x2* rp = ROPE + qpos * 8; const float sg = c == 0 ? -1.f : 1.f;
; #pragma unroll
;                 for (int d = 0; d < 8; ++d) { const f32x2 cs = rp[d]; f[d] = f[d] * cs.x + sg * pf[d] * cs.y; } }
;             u32x4 w; w.x = cvt_pk_bf16(f[0] * 0.125f, f[1] * 0.125f); w.y = cvt_pk_bf16(f[2] * 0.125f, f[3] * 0.125f); w.z = cvt_pk_bf16(f[4] * 0.125f, f[5] * 0.125f); w.w = cvt_pk_bf16(f[6] * 0.125f, f[7] * 0.125f);
.LBB0_281:
	v_lshl_add_u64 v[2:3], s[86:87], 0, v[102:103]
	v_add_co_u32_e32 v4, vcc, 0xc600000, v2
	s_nop 1
	v_addc_co_u32_e32 v5, vcc, 0, v3, vcc
	global_load_dwordx4 v[16:19], v[4:5], off
	s_waitcnt vmcnt(0)
	v_lshlrev_b32_e32 v14, 16, v16
	v_and_b32_e32 v12, 0xffff0000, v16
	v_lshlrev_b32_e32 v10, 16, v17
	v_and_b32_e32 v8, 0xffff0000, v17
	v_lshlrev_b32_e32 v6, 16, v18
	v_and_b32_e32 v4, 0xffff0000, v18
	v_lshlrev_b32_e32 v16, 16, v19
	v_and_b32_e32 v18, 0xffff0000, v19
	s_and_saveexec_b64 s[0:1], s[12:13]
	s_cbranch_execz .LBB0_283
	v_lshl_add_u64 v[20:21], s[86:87], 0, v[98:99]
	global_load_dwordx4 v[20:23], v[20:21], off
	v_lshl_add_u64 v[28:29], s[86:87], 0, v[96:97]
	s_mov_b64 s[18:19], 0xa0000
	s_mov_b32 s20, 0xa0000
	v_lshl_add_u64 v[36:37], v[28:29], 0, s[18:19]
	v_add_co_u32_e32 v28, vcc, s20, v28
	global_load_dwordx4 v[24:27], v[36:37], off offset:48
	s_nop 0
	v_addc_co_u32_e32 v29, vcc, 0, v29, vcc
	global_load_dwordx4 v[28:31], v[28:29], off
	s_nop 0
	global_load_dwordx4 v[32:35], v[36:37], off offset:16
	s_nop 0
	global_load_dwordx4 v[36:39], v[36:37], off offset:32
	s_waitcnt vmcnt(4)
	v_and_b32_e32 v5, 0xffff0000, v20
	v_lshlrev_b32_e32 v7, 16, v21
	v_and_b32_e32 v9, 0xffff0000, v21
	v_and_b32_e32 v19, 0xffff0000, v22
	v_and_b32_e32 v21, 0xffff0000, v23
	v_lshlrev_b32_e32 v1, 16, v20
	v_lshlrev_b32_e32 v20, 16, v23
	v_cndmask_b32_e64 v13, v5, -v5, s[14:15]
	v_cndmask_b32_e64 v5, v19, -v19, s[14:15]
	v_cndmask_b32_e64 v19, v21, -v21, s[14:15]
	v_lshlrev_b32_e32 v17, 16, v22
	v_cndmask_b32_e64 v15, v1, -v1, s[14:15]
	v_cndmask_b32_e64 v1, v20, -v20, s[14:15]
	s_waitcnt vmcnt(3)
	v_mul_f32_e32 v18, v26, v18
	v_mul_f32_e32 v19, v27, v19
	v_cndmask_b32_e64 v11, v7, -v7, s[14:15]
	v_cndmask_b32_e64 v9, v9, -v9, s[14:15]
	v_cndmask_b32_e64 v7, v17, -v17, s[14:15]
	v_mul_f32_e32 v16, v24, v16
	s_waitcnt vmcnt(2)
	v_mul_f32_e32 v20, v30, v12
	v_mul_f32_e32 v42, v1, v25
	v_mov_b32_e32 v17, v18
	v_mov_b32_e32 v43, v19
	v_mul_f32_e32 v14, v28, v14
	v_mul_f32_e32 v15, v29, v15
	s_waitcnt vmcnt(1)
	v_mul_f32_e32 v22, v33, v11
	v_mul_f32_e32 v24, v35, v9
	s_waitcnt vmcnt(0)
	v_mul_f32_e32 v28, v37, v7
	v_mul_f32_e32 v40, v39, v5
	v_fma_f32 v12, v30, v12, v20
	v_fma_f32 v13, v31, v13, v20
	v_add_f32_e32 v16, v16, v42
	v_add_f32_e32 v17, v17, v43
	v_fma_f32 v10, v32, v10, v22
	v_fma_f32 v11, v33, v11, v22
	v_fma_f32 v8, v34, v8, v24
	v_fma_f32 v9, v35, v9, v24
	v_fma_f32 v6, v36, v6, v28
	v_fma_f32 v7, v37, v7, v28
	v_fma_f32 v4, v38, v4, v40
	v_fma_f32 v5, v39, v5, v40
	v_add_f32_e32 v14, v14, v15
	v_mov_b32_e32 v12, v13
	v_mov_b32_e32 v18, v17

; #define LBAR() asm volatile("s_waitcnt lgkmcnt(0)\n\ts_barrier" ::: "memory")
; #define SG_LOAD(k0) do { _Pragma("unroll") for (int i_ = 0; i_ < 4; ++i_) { const int id_ = tid + i_ * 512, rr_ = id_ >> 5, cc_ = id_ & 31; \
;         ra[i_] = *(const u32x4*)(Ag + (size_t)rr_ * lda + (k0) + cc_ * 8); rb[i_] = *(const u32x4*)(Bg + (size_t)rr_ * ldb + (k0) + cc_ * 8); } } while (0)
; template <class Epi>
; __device__ __forceinline__ void small_gemm_tile(unsigned char* lds, const bf16_t* A, int lda, const bf16_t* Bt, int ldb, int K, int kbreak, int rowbase, int tm, int tn, const Epi& E, int tid) {
;     ...
;     f32x4 cur[2], first[2];
; #pragma unroll
;     for (int n_ = 0; n_ < 2; ++n_) { cur[n_] = (f32x4){0.f, 0.f, 0.f, 0.f}; first[n_] = (f32x4){0.f, 0.f, 0.f, 0.f}; }
;     SG_LOAD(0);
;     for (int k0 = 0; k0 < K; k0 += 256) {
; #pragma unroll
;         for (int i = 0; i < 4; ++i) { const int id = tid + i * 512, rr = id >> 5, cc = id & 31; *(u32x4*)(AS + rr * 528 + cc * 16) = ra[i]; *(u32x4*)(BS + rr * 528 + cc * 16) = rb[i]; }
;         LBAR();
;         if (k0 + 256 < K) SG_LOAD(k0 + 256);
;         if (k0 == kbreak) {
; #pragma unroll
;             for (int n_ = 0; n_ < 2; ++n_) { first[n_] = cur[n_]; cur[n_] = (f32x4){0.f, 0.f, 0.f, 0.f}; } }
; #pragma unroll
;         for (int kk = 0; kk < 8; ++kk) { const bf16x8 af = *(const bf16x8*)(AS + (wm * 16 + r16) * 528 + kk * 64 + q4 * 16);
; #pragma unroll
;             for (int nt = 0; nt < 2; ++nt) { const bf16x8 bfg = *(const bf16x8*)(BS + (wn * 32 + nt * 16 + r16) * 528 + kk * 64 + q4 * 16); cur[nt] = __builtin_amdgcn_mfma_f32_16x16x32_bf16(bfg, af, cur[nt], 0, 0, 0); } }
;         LBAR();
.LBB0_578:
	s_and_b32 s1, s18, 0xffffffc0
	s_addk_i32 s1, 0x4000
	s_and_b32 s0, s19, 31
	v_mad_i64_i32 v[28:29], s[4:5], s1, v11, v[14:15]
	s_mul_i32 s8, s0, 0x60000
	v_lshl_add_u64 v[20:21], v[28:29], 0, v[4:5]
	v_lshl_add_u64 v[32:33], v[16:17], 0, s[8:9]
	v_add_co_u32_e32 v64, vcc, s16, v20
	v_lshl_add_u64 v[22:23], v[32:33], 0, v[4:5]
	s_nop 0
	v_addc_co_u32_e32 v65, vcc, 0, v21, vcc
	v_add_co_u32_e32 v68, vcc, s16, v22
	v_lshl_add_u64 v[30:31], v[28:29], 0, v[8:9]
	s_nop 0
	v_addc_co_u32_e32 v69, vcc, 0, v23, vcc
	v_lshl_add_u64 v[26:27], v[28:29], 0, v[6:7]
	v_lshl_add_u64 v[24:25], v[32:33], 0, v[6:7]
	v_lshl_add_u64 v[28:29], v[32:33], 0, v[8:9]
	global_load_dwordx4 v[32:35], v[20:21], off
	global_load_dwordx4 v[44:47], v[22:23], off
	global_load_dwordx4 v[48:51], v[26:27], off
	global_load_dwordx4 v[52:55], v[24:25], off
	global_load_dwordx4 v[56:59], v[30:31], off
	global_load_dwordx4 v[60:63], v[28:29], off
	s_nop 0
	global_load_dwordx4 v[64:67], v[64:65], off
	s_nop 0
	global_load_dwordx4 v[68:71], v[68:69], off
	v_lshl_or_b32 v43, s0, 6, v39
	v_lshlrev_b32_e32 v12, 1, v43
	s_add_i32 s19, s19, s24
	s_add_i32 s18, s18, s20
	s_cmpk_gt_i32 s19, 0xff
	s_waitcnt vmcnt(0)
	ds_write_b128 v40, v[32:35]
	ds_write_b128 v40, v[44:47] offset:33792
	ds_write_b128 v41, v[48:51]
	ds_write_b128 v41, v[52:55] offset:33792
	ds_write_b128 v40, v[64:67] offset:16896
	ds_write_b128 v40, v[68:71] offset:50688
	ds_write_b128 v42, v[56:59]
	ds_write_b128 v42, v[60:63] offset:33792
	s_waitcnt lgkmcnt(0)
	s_barrier
	ds_read_b128 v[32:35], v38 offset:33792
	ds_read_b128 v[44:47], v37
	ds_read_b128 v[48:51], v37 offset:64
	ds_read_b128 v[52:55], v38 offset:33856
	s_waitcnt lgkmcnt(2)
	v_mfma_f32_16x16x32_bf16 v[32:35], v[32:35], v[44:47], 0
	ds_read_b128 v[56:59], v38 offset:42240
	ds_read_b128 v[60:63], v38 offset:42304
	s_waitcnt lgkmcnt(2)
	v_mfma_f32_16x16x32_bf16 v[32:35], v[52:55], v[48:51], v[32:35]
	ds_read_b128 v[52:55], v38 offset:33920
	s_waitcnt lgkmcnt(2)
	v_mfma_f32_16x16x32_bf16 v[44:47], v[56:59], v[44:47], 0
	s_waitcnt lgkmcnt(1)
	v_mfma_f32_16x16x32_bf16 v[44:47], v[60:63], v[48:51], v[44:47]
	ds_read_b128 v[48:51], v37 offset:128
	ds_read_b128 v[56:59], v37 offset:192
	ds_read_b128 v[60:63], v38 offset:33984
	s_waitcnt lgkmcnt(2)
	v_mfma_f32_16x16x32_bf16 v[32:35], v[52:55], v[48:51], v[32:35]
	ds_read_b128 v[52:55], v38 offset:42368
	ds_read_b128 v[64:67], v38 offset:42432
	s_waitcnt lgkmcnt(1)
	v_mfma_f32_16x16x32_bf16 v[44:47], v[52:55], v[48:51], v[44:47]
	ds_read_b128 v[48:51], v38 offset:34048
	v_mfma_f32_16x16x32_bf16 v[32:35], v[60:63], v[56:59], v[32:35]
	s_waitcnt lgkmcnt(1)
	v_mfma_f32_16x16x32_bf16 v[44:47], v[64:67], v[56:59], v[44:47]
	ds_read_b128 v[52:55], v37 offset:256
	ds_read_b128 v[56:59], v37 offset:320
	ds_read_b128 v[60:63], v38 offset:34112
	s_waitcnt lgkmcnt(2)
	v_mfma_f32_16x16x32_bf16 v[48:51], v[48:51], v[52:55], v[32:35]
	s_nop 2
	ds_read_b128 v[32:35], v38 offset:42496
	ds_read_b128 v[64:67], v38 offset:42560
	s_waitcnt lgkmcnt(1)
	v_mfma_f32_16x16x32_bf16 v[44:47], v[32:35], v[52:55], v[44:47]
	ds_read_b128 v[52:55], v38 offset:34176
	v_lshl_add_u64 v[32:33], v[20:21], 0, s[14:15]
	v_lshl_add_u64 v[34:35], v[22:23], 0, s[14:15]
	v_mfma_f32_16x16x32_bf16 v[48:51], v[60:63], v[56:59], v[48:51]
	global_load_dwordx4 v[60:63], v[30:31], off offset:512
	ds_read_b128 v[68:71], v37 offset:384
	ds_read_b128 v[72:75], v38 offset:42624
	s_waitcnt lgkmcnt(3)
	v_mfma_f32_16x16x32_bf16 v[44:47], v[64:67], v[56:59], v[44:47]
	global_load_dwordx4 v[56:59], v[26:27], off offset:512
	ds_read_b128 v[64:67], v37 offset:448
	ds_read_b128 v[76:79], v38 offset:34240
	s_waitcnt lgkmcnt(3)
	v_mfma_f32_16x16x32_bf16 v[48:51], v[52:55], v[68:71], v[48:51]
	global_load_dwordx4 v[52:55], v[20:21], off offset:512
	global_load_dwordx4 v[80:83], v[22:23], off offset:512
	ds_read_b128 v[84:87], v38 offset:42688
	s_waitcnt lgkmcnt(3)
	v_mfma_f32_16x16x32_bf16 v[44:47], v[72:75], v[68:71], v[44:47]
	global_load_dwordx4 v[68:71], v[24:25], off offset:512
	global_load_dwordx4 v[72:75], v[32:33], off offset:512
	global_load_dwordx4 v[88:91], v[34:35], off offset:512
	s_waitcnt lgkmcnt(1)
	v_mfma_f32_16x16x32_bf16 v[48:51], v[76:79], v[64:67], v[48:51]
	global_load_dwordx4 v[76:79], v[28:29], off offset:512
	s_waitcnt lgkmcnt(0)
	s_barrier
	s_waitcnt vmcnt(5)
	ds_write_b128 v40, v[52:55]
	s_waitcnt vmcnt(4)
	ds_write_b128 v40, v[80:83] offset:33792
	ds_write_b128 v41, v[56:59]
	s_waitcnt vmcnt(3)
	ds_write_b128 v41, v[68:71] offset:33792
	s_waitcnt vmcnt(2)
	ds_write_b128 v40, v[72:75] offset:16896
	s_waitcnt vmcnt(1)
	ds_write_b128 v40, v[88:91] offset:50688
	ds_write_b128 v42, v[60:63]
	s_waitcnt vmcnt(0)
	ds_write_b128 v42, v[76:79] offset:33792
	s_waitcnt lgkmcnt(0)
	s_barrier
; #define LBAR() asm volatile("s_waitcnt lgkmcnt(0)\n\ts_barrier" ::: "memory")
; #define SG_LOAD(k0) do { _Pragma("unroll") for (int i_ = 0; i_ < 4; ++i_) { const int id_ = tid + i_ * 512, rr_ = id_ >> 5, cc_ = id_ & 31; \
;         ra[i_] = *(const u32x4*)(Ag + (size_t)rr_ * lda + (k0) + cc_ * 8); rb[i_] = *(const u32x4*)(Bg + (size_t)rr_ * ldb + (k0) + cc_ * 8); } } while (0)
; template <class Epi>
; __device__ __forceinline__ void small_gemm_tile(unsigned char* lds, const bf16_t* A, int lda, const bf16_t* Bt, int ldb, int K, int kbreak, int rowbase, int tm, int tn, const Epi& E, int tid) {
;     ...
;     f32x4 cur[2], first[2];
; #pragma unroll
;     for (int n_ = 0; n_ < 2; ++n_) { cur[n_] = (f32x4){0.f, 0.f, 0.f, 0.f}; first[n_] = (f32x4){0.f, 0.f, 0.f, 0.f}; }
;     SG_LOAD(0);
;     for (int k0 = 0; k0 < K; k0 += 256) {
; #pragma unroll
;         for (int i = 0; i < 4; ++i) { const int id = tid + i * 512, rr = id >> 5, cc = id & 31; *(u32x4*)(AS + rr * 528 + cc * 16) = ra[i]; *(u32x4*)(BS + rr * 528 + cc * 16) = rb[i]; }
;         LBAR();
;         if (k0 + 256 < K) SG_LOAD(k0 + 256);
;         if (k0 == kbreak) {
; #pragma unroll
;             for (int n_ = 0; n_ < 2; ++n_) { first[n_] = cur[n_]; cur[n_] = (f32x4){0.f, 0.f, 0.f, 0.f}; } }
; #pragma unroll
;         for (int kk = 0; kk < 8; ++kk) { const bf16x8 af = *(const bf16x8*)(AS + (wm * 16 + r16) * 528 + kk * 64 + q4 * 16);
; #pragma unroll
;             for (int nt = 0; nt < 2; ++nt) { const bf16x8 bfg = *(const bf16x8*)(BS + (wn * 32 + nt * 16 + r16) * 528 + kk * 64 + q4 * 16); cur[nt] = __builtin_amdgcn_mfma_f32_16x16x32_bf16(bfg, af, cur[nt], 0, 0, 0); } }
;         LBAR();
	s_waitcnt lgkmcnt(8)
	v_mfma_f32_16x16x32_bf16 v[44:47], v[84:87], v[64:67], v[44:47]
	ds_read_b128 v[52:55], v38 offset:33792
	ds_read_b128 v[56:59], v37
	ds_read_b128 v[60:63], v37 offset:64
	ds_read_b128 v[64:67], v38 offset:33856
	s_waitcnt lgkmcnt(2)
	v_mfma_f32_16x16x32_bf16 v[48:51], v[52:55], v[56:59], v[48:51]
	ds_read_b128 v[52:55], v38 offset:42240
	ds_read_b128 v[68:71], v38 offset:42304
	s_waitcnt lgkmcnt(1)
	v_mfma_f32_16x16x32_bf16 v[44:47], v[52:55], v[56:59], v[44:47]
	ds_read_b128 v[52:55], v38 offset:33920
	v_mfma_f32_16x16x32_bf16 v[48:51], v[64:67], v[60:63], v[48:51]
	s_waitcnt lgkmcnt(1)
	v_mfma_f32_16x16x32_bf16 v[44:47], v[68:71], v[60:63], v[44:47]
	ds_read_b128 v[56:59], v37 offset:128
	ds_read_b128 v[60:63], v37 offset:192
	ds_read_b128 v[64:67], v38 offset:33984
	s_waitcnt lgkmcnt(2)
	v_mfma_f32_16x16x32_bf16 v[48:51], v[52:55], v[56:59], v[48:51]
	ds_read_b128 v[52:55], v38 offset:42368
	ds_read_b128 v[68:71], v38 offset:42432
	s_waitcnt lgkmcnt(1)
	v_mfma_f32_16x16x32_bf16 v[44:47], v[52:55], v[56:59], v[44:47]
	ds_read_b128 v[52:55], v38 offset:34048
	v_mfma_f32_16x16x32_bf16 v[48:51], v[64:67], v[60:63], v[48:51]
	s_waitcnt lgkmcnt(1)
	v_mfma_f32_16x16x32_bf16 v[44:47], v[68:71], v[60:63], v[44:47]
	ds_read_b128 v[56:59], v37 offset:256
	ds_read_b128 v[60:63], v37 offset:320
	ds_read_b128 v[64:67], v38 offset:34112
	s_waitcnt lgkmcnt(2)
	v_mfma_f32_16x16x32_bf16 v[48:51], v[52:55], v[56:59], v[48:51]
	ds_read_b128 v[52:55], v38 offset:42496
	ds_read_b128 v[68:71], v38 offset:42560
	s_waitcnt lgkmcnt(1)
	v_mfma_f32_16x16x32_bf16 v[44:47], v[52:55], v[56:59], v[44:47]
	ds_read_b128 v[52:55], v38 offset:34176
	global_load_dwordx4 v[56:59], v[30:31], off offset:1024
	v_mfma_f32_16x16x32_bf16 v[48:51], v[64:67], v[60:63], v[48:51]
	ds_read_b128 v[64:67], v37 offset:384
	ds_read_b128 v[72:75], v38 offset:42624
	s_waitcnt lgkmcnt(3)
	v_mfma_f32_16x16x32_bf16 v[44:47], v[68:71], v[60:63], v[44:47]
	global_load_dwordx4 v[60:63], v[26:27], off offset:1024
	ds_read_b128 v[68:71], v37 offset:448
	ds_read_b128 v[76:79], v38 offset:34240
	s_waitcnt lgkmcnt(3)
	v_mfma_f32_16x16x32_bf16 v[48:51], v[52:55], v[64:67], v[48:51]
	global_load_dwordx4 v[52:55], v[20:21], off offset:1024
	global_load_dwordx4 v[80:83], v[22:23], off offset:1024
	ds_read_b128 v[84:87], v38 offset:42688
	s_waitcnt lgkmcnt(3)
	v_mfma_f32_16x16x32_bf16 v[44:47], v[72:75], v[64:67], v[44:47]
	global_load_dwordx4 v[64:67], v[24:25], off offset:1024
	global_load_dwordx4 v[72:75], v[32:33], off offset:1024
	global_load_dwordx4 v[88:91], v[34:35], off offset:1024
	s_waitcnt lgkmcnt(1)
	v_mfma_f32_16x16x32_bf16 v[48:51], v[76:79], v[68:71], v[48:51]
	global_load_dwordx4 v[76:79], v[28:29], off offset:1024
	s_waitcnt lgkmcnt(0)
	s_barrier
	s_waitcnt vmcnt(5)
	ds_write_b128 v40, v[52:55]
	s_waitcnt vmcnt(4)
	ds_write_b128 v40, v[80:83] offset:33792
	ds_write_b128 v41, v[60:63]
	s_waitcnt vmcnt(3)
	ds_write_b128 v41, v[64:67] offset:33792
	s_waitcnt vmcnt(2)
	ds_write_b128 v40, v[72:75] offset:16896
	s_waitcnt vmcnt(1)
	ds_write_b128 v40, v[88:91] offset:50688
	ds_write_b128 v42, v[56:59]
	s_waitcnt vmcnt(0)
	ds_write_b128 v42, v[76:79] offset:33792
	s_waitcnt lgkmcnt(0)
	s_barrier
	ds_read_b128 v[52:55], v38 offset:33792
	ds_read_b128 v[56:59], v37
	ds_read_b128 v[60:63], v37 offset:64
	ds_read_b128 v[64:67], v38 offset:33856
	s_waitcnt lgkmcnt(12)
	v_mfma_f32_16x16x32_bf16 v[44:47], v[84:87], v[68:71], v[44:47]
	s_waitcnt lgkmcnt(2)
	v_mfma_f32_16x16x32_bf16 v[48:51], v[52:55], v[56:59], v[48:51]
	ds_read_b128 v[52:55], v38 offset:42240
	ds_read_b128 v[68:71], v38 offset:42304
	s_waitcnt lgkmcnt(1)
	v_mfma_f32_16x16x32_bf16 v[44:47], v[52:55], v[56:59], v[44:47]
	ds_read_b128 v[52:55], v38 offset:33920
	v_mfma_f32_16x16x32_bf16 v[48:51], v[64:67], v[60:63], v[48:51]
	s_waitcnt lgkmcnt(1)
	v_mfma_f32_16x16x32_bf16 v[44:47], v[68:71], v[60:63], v[44:47]
	ds_read_b128 v[56:59], v37 offset:128
	ds_read_b128 v[60:63], v37 offset:192
	ds_read_b128 v[64:67], v38 offset:33984
	s_waitcnt lgkmcnt(2)
	v_mfma_f32_16x16x32_bf16 v[48:51], v[52:55], v[56:59], v[48:51]
	ds_read_b128 v[52:55], v38 offset:42368
	ds_read_b128 v[68:71], v38 offset:42432
	s_waitcnt lgkmcnt(1)
	v_mfma_f32_16x16x32_bf16 v[44:47], v[52:55], v[56:59], v[44:47]
	ds_read_b128 v[52:55], v38 offset:34048
	v_mfma_f32_16x16x32_bf16 v[48:51], v[64:67], v[60:63], v[48:51]
	s_waitcnt lgkmcnt(1)
	v_mfma_f32_16x16x32_bf16 v[44:47], v[68:71], v[60:63], v[44:47]
	ds_read_b128 v[56:59], v37 offset:256
	ds_read_b128 v[60:63], v37 offset:320
	ds_read_b128 v[64:67], v38 offset:34112
	s_waitcnt lgkmcnt(2)
	v_mfma_f32_16x16x32_bf16 v[48:51], v[52:55], v[56:59], v[48:51]
	ds_read_b128 v[52:55], v38 offset:42496
	ds_read_b128 v[68:71], v38 offset:42560
	ds_read_b128 v[72:75], v38 offset:34176
	s_waitcnt lgkmcnt(2)
	v_mfma_f32_16x16x32_bf16 v[44:47], v[52:55], v[56:59], v[44:47]
	v_mov_b64_e32 v[54:55], v[2:3]
	v_mov_b64_e32 v[58:59], v[2:3]
	v_mov_b64_e32 v[52:53], v[0:1]
	v_mfma_f32_16x16x32_bf16 v[48:51], v[64:67], v[60:63], v[48:51]
	global_load_dwordx4 v[64:67], v[26:27], off offset:1536
	ds_read_b128 v[76:79], v37 offset:384
	ds_read_b128 v[80:83], v38 offset:42624
	v_mov_b64_e32 v[56:57], v[0:1]
	s_waitcnt lgkmcnt(3)
	v_mfma_f32_16x16x32_bf16 v[44:47], v[68:71], v[60:63], v[44:47]
	global_load_dwordx4 v[60:63], v[30:31], off offset:1536
	ds_read_b128 v[68:71], v37 offset:448
	ds_read_b128 v[84:87], v38 offset:34240
	s_waitcnt lgkmcnt(3)
	v_mfma_f32_16x16x32_bf16 v[48:51], v[72:75], v[76:79], v[48:51]
	global_load_dwordx4 v[72:75], v[20:21], off offset:1536
	s_nop 0
	global_load_dwordx4 v[20:23], v[22:23], off offset:1536
	ds_read_b128 v[88:91], v38 offset:42688
	s_waitcnt lgkmcnt(3)
	v_mfma_f32_16x16x32_bf16 v[44:47], v[80:83], v[76:79], v[44:47]
	global_load_dwordx4 v[24:27], v[24:25], off offset:1536
	s_nop 0
	global_load_dwordx4 v[30:33], v[32:33], off offset:1536
	s_nop 0
	global_load_dwordx4 v[76:79], v[34:35], off offset:1536
	global_load_dwordx4 v[80:83], v[28:29], off offset:1536
	s_waitcnt lgkmcnt(0)
	s_barrier
; #define MFMA_SETTLE4(a, b, c, d) asm volatile("s_nop 15\n\ts_nop 15" : "+v"(a), "+v"(b), "+v"(c), "+v"(d))
; #define LBAR() asm volatile("s_waitcnt lgkmcnt(0)\n\ts_barrier" ::: "memory")
; #define SG_LOAD(k0) do { _Pragma("unroll") for (int i_ = 0; i_ < 4; ++i_) { const int id_ = tid + i_ * 512, rr_ = id_ >> 5, cc_ = id_ & 31; \
;         ra[i_] = *(const u32x4*)(Ag + (size_t)rr_ * lda + (k0) + cc_ * 8); rb[i_] = *(const u32x4*)(Bg + (size_t)rr_ * ldb + (k0) + cc_ * 8); } } while (0)
; template <class Epi>
; __device__ __forceinline__ void small_gemm_tile(unsigned char* lds, const bf16_t* A, int lda, const bf16_t* Bt, int ldb, int K, int kbreak, int rowbase, int tm, int tn, const Epi& E, int tid) {
;     ...
;     for (int k0 = 0; k0 < K; k0 += 256) {
; #pragma unroll
;         for (int i = 0; i < 4; ++i) { const int id = tid + i * 512, rr = id >> 5, cc = id & 31; *(u32x4*)(AS + rr * 528 + cc * 16) = ra[i]; *(u32x4*)(BS + rr * 528 + cc * 16) = rb[i]; }
;         LBAR();
;         if (k0 + 256 < K) SG_LOAD(k0 + 256);
;         if (k0 == kbreak) {
; #pragma unroll
;             for (int n_ = 0; n_ < 2; ++n_) { first[n_] = cur[n_]; cur[n_] = (f32x4){0.f, 0.f, 0.f, 0.f}; } }
; #pragma unroll
;         for (int kk = 0; kk < 8; ++kk) { const bf16x8 af = *(const bf16x8*)(AS + (wm * 16 + r16) * 528 + kk * 64 + q4 * 16);
; #pragma unroll
;             for (int nt = 0; nt < 2; ++nt) { const bf16x8 bfg = *(const bf16x8*)(BS + (wn * 32 + nt * 16 + r16) * 528 + kk * 64 + q4 * 16); cur[nt] = __builtin_amdgcn_mfma_f32_16x16x32_bf16(bfg, af, cur[nt], 0, 0, 0); } }
;         LBAR();
;     }
;     MFMA_SETTLE4(cur[0], cur[1], first[0], first[1]);
;     const int row = rowbase + tm * 64 + wm * 16 + r16; float ssq = 0.f;
	s_waitcnt lgkmcnt(1)
	v_mfma_f32_16x16x32_bf16 v[48:51], v[84:87], v[68:71], v[48:51]
	s_waitcnt vmcnt(5)
	ds_write_b128 v40, v[72:75]
	s_waitcnt vmcnt(4)
	ds_write_b128 v40, v[20:23] offset:33792
	ds_write_b128 v41, v[64:67]
	s_waitcnt vmcnt(3)
	ds_write_b128 v41, v[24:27] offset:33792
	s_waitcnt vmcnt(2)
	ds_write_b128 v40, v[30:33] offset:16896
	s_waitcnt vmcnt(1)
	ds_write_b128 v40, v[76:79] offset:50688
	ds_write_b128 v42, v[60:63]
	s_waitcnt vmcnt(0)
	ds_write_b128 v42, v[80:83] offset:33792
	s_waitcnt lgkmcnt(0)
	s_barrier
	ds_read_b128 v[20:23], v38 offset:33792
	ds_read_b128 v[24:27], v37
	ds_read_b128 v[28:31], v37 offset:64
	ds_read_b128 v[32:35], v38 offset:33856
	s_waitcnt lgkmcnt(2)
	v_mfma_f32_16x16x32_bf16 v[20:23], v[20:23], v[24:27], v[48:51]
	s_nop 2
	ds_read_b128 v[48:51], v38 offset:42240
	ds_read_b128 v[60:63], v38 offset:42304
	v_add_u32_e32 v66, s1, v36
	v_lshlrev_b32_e32 v64, 2, v43
	v_mfma_f32_16x16x32_bf16 v[44:47], v[88:91], v[68:71], v[44:47]
	v_ashrrev_i32_e32 v67, 31, v66
	v_mov_b32_e32 v65, v13
	s_waitcnt lgkmcnt(2)
	v_mfma_f32_16x16x32_bf16 v[20:23], v[32:35], v[28:31], v[20:23]
	ds_read_b128 v[32:35], v38 offset:33920
	s_waitcnt lgkmcnt(2)
	v_mfma_f32_16x16x32_bf16 v[24:27], v[48:51], v[24:27], v[44:47]
	s_waitcnt lgkmcnt(1)
	v_mfma_f32_16x16x32_bf16 v[24:27], v[60:63], v[28:31], v[24:27]
	ds_read_b128 v[28:31], v37 offset:128
	ds_read_b128 v[44:47], v37 offset:192
	ds_read_b128 v[48:51], v38 offset:33984
	s_waitcnt lgkmcnt(2)
	v_mfma_f32_16x16x32_bf16 v[20:23], v[32:35], v[28:31], v[20:23]
	ds_read_b128 v[32:35], v38 offset:42368
	ds_read_b128 v[60:63], v38 offset:42432
	s_waitcnt lgkmcnt(1)
	v_mfma_f32_16x16x32_bf16 v[24:27], v[32:35], v[28:31], v[24:27]
	ds_read_b128 v[28:31], v38 offset:34048
	v_mfma_f32_16x16x32_bf16 v[20:23], v[48:51], v[44:47], v[20:23]
	s_waitcnt lgkmcnt(1)
	v_mfma_f32_16x16x32_bf16 v[24:27], v[60:63], v[44:47], v[24:27]
	ds_read_b128 v[32:35], v37 offset:256
	ds_read_b128 v[44:47], v37 offset:320
	ds_read_b128 v[48:51], v38 offset:34112
	s_waitcnt lgkmcnt(2)
	v_mfma_f32_16x16x32_bf16 v[20:23], v[28:31], v[32:35], v[20:23]
	ds_read_b128 v[28:31], v38 offset:42496
	ds_read_b128 v[60:63], v38 offset:42560
	s_waitcnt lgkmcnt(1)
	v_mfma_f32_16x16x32_bf16 v[24:27], v[28:31], v[32:35], v[24:27]
	v_mad_i64_i32 v[28:29], s[0:1], v66, s17, v[18:19]
	v_lshl_add_u64 v[68:69], v[28:29], 0, s[10:11]
	ds_read_b128 v[28:31], v38 offset:34176
	v_mfma_f32_16x16x32_bf16 v[20:23], v[48:51], v[44:47], v[20:23]
	v_lshlrev_b64 v[66:67], 13, v[66:67]
	s_waitcnt lgkmcnt(1)
	v_mfma_f32_16x16x32_bf16 v[24:27], v[60:63], v[44:47], v[24:27]
	ds_read_b128 v[32:35], v37 offset:384
	ds_read_b128 v[44:47], v37 offset:448
	ds_read_b128 v[48:51], v38 offset:34240
	s_waitcnt lgkmcnt(2)
	v_mfma_f32_16x16x32_bf16 v[20:23], v[28:31], v[32:35], v[20:23]
	ds_read_b128 v[28:31], v38 offset:42624
	ds_read_b128 v[60:63], v38 offset:42688
	s_waitcnt lgkmcnt(0)
	s_barrier
; __device__ __forceinline__ float bflo(unsigned w) { return __uint_as_float(w << 16); }
; __device__ __forceinline__ float bfhi(unsigned w) { return __uint_as_float(w & 0xffff0000u); }
; __device__ __forceinline__ float sigmoidf_(float x) { return 1.f / (1.f + __expf(-x)); }
; #define MFMA_SETTLE4(a, b, c, d) asm volatile("s_nop 15\n\ts_nop 15" : "+v"(a), "+v"(b), "+v"(c), "+v"(d))
; template <class Epi>
; __device__ __forceinline__ void small_gemm_tile(unsigned char* lds, const bf16_t* A, int lda, const bf16_t* Bt, int ldb, int K, int kbreak, int rowbase, int tm, int tn, const Epi& E, int tid) {
;     ...
;     MFMA_SETTLE4(cur[0], cur[1], first[0], first[1]);
;     const int row = rowbase + tm * 64 + wm * 16 + r16; float ssq = 0.f;
; #pragma unroll
;     for (int nt = 0; nt < 2; ++nt) ssq += E(cur[nt], first[nt], row, tn * 64 + wn * 32 + nt * 16 + q4 * 4);
;     __device__ __forceinline__ float operator()(const f32x4& a0, const f32x4&, int row, int col) const {
;         const u32x2 gs = *(const u32x2*)(Z + (size_t)row * DINP + ZGS + col); f32x4 o;
;         o[0] = a0[0] * sigmoidf_(bflo(gs.x)); o[1] = a0[1] * sigmoidf_(bfhi(gs.x)); o[2] = a0[2] * sigmoidf_(bflo(gs.y)); o[3] = a0[3] * sigmoidf_(bfhi(gs.y));
;         *(f32x4*)(T + (size_t)row * DM + col) = o; return 0.f; }
	s_waitcnt lgkmcnt(1)
	v_mfma_f32_16x16x32_bf16 v[24:27], v[28:31], v[32:35], v[24:27]
	v_lshl_add_u64 v[30:31], v[68:69], 0, v[12:13]
	v_or_b32_e32 v12, 32, v12
	v_lshl_add_u64 v[32:33], v[68:69], 0, v[12:13]
	v_mfma_f32_16x16x32_bf16 v[20:23], v[48:51], v[44:47], v[20:23]
	v_lshl_add_u64 v[28:29], s[84:85], 0, v[66:67]
	v_lshl_add_u64 v[28:29], v[28:29], 0, v[64:65]
	s_waitcnt lgkmcnt(0)
	v_mfma_f32_16x16x32_bf16 v[24:27], v[60:63], v[44:47], v[24:27]
	s_nop 15
	s_nop 15
	global_load_dwordx2 v[30:31], v[30:31], off
	s_waitcnt vmcnt(0)
	v_lshlrev_b32_e32 v12, 16, v30
	v_and_b32_e32 v30, 0xffff0000, v30
	v_lshlrev_b32_e32 v34, 16, v31
	v_and_b32_e32 v31, 0xffff0000, v31
	v_mul_f32_e32 v12, 0xbfb8aa3b, v12
	v_mul_f32_e32 v43, 0xbfb8aa3b, v30
	v_mul_f32_e32 v31, 0xbfb8aa3b, v31
	v_exp_f32_e32 v30, v12
	v_exp_f32_e32 v35, v31
	v_exp_f32_e32 v31, v43
	v_mul_f32_e32 v34, 0xbfb8aa3b, v34
	v_exp_f32_e32 v34, v34
	v_add_f32_e32 v30, 1.0, v30
	v_add_f32_e32 v31, 1.0, v31
	s_nop 0
	v_div_scale_f32 v12, s[0:1], v31, v31, 1.0
	v_add_f32_e32 v34, 1.0, v34
	v_add_f32_e32 v35, 1.0, v35
	v_div_scale_f32 v44, s[0:1], v30, v30, 1.0
	v_rcp_f32_e32 v50, v12
	v_div_scale_f32 v46, s[4:5], v35, v35, 1.0
	v_rcp_f32_e32 v51, v44
	v_div_scale_f32 v48, s[6:7], v34, v34, 1.0
	v_rcp_f32_e32 v52, v46
	v_rcp_f32_e32 v53, v48
	v_fma_f32 v54, -v12, v50, 1.0
	v_div_scale_f32 v43, vcc, 1.0, v31, 1.0
	v_fma_f32 v55, -v44, v51, 1.0
	v_fmac_f32_e32 v50, v54, v50
	v_div_scale_f32 v45, s[0:1], 1.0, v30, 1.0
	v_fma_f32 v56, -v46, v52, 1.0
	v_fmac_f32_e32 v51, v55, v51
	v_mul_f32_e32 v54, v43, v50
	v_div_scale_f32 v47, s[4:5], 1.0, v35, 1.0
	v_fma_f32 v57, -v48, v53, 1.0
	v_fmac_f32_e32 v52, v56, v52
	v_mul_f32_e32 v55, v45, v51
	v_fma_f32 v58, -v12, v54, v43
	v_div_scale_f32 v49, s[6:7], 1.0, v34, 1.0
	v_fmac_f32_e32 v53, v57, v53
	v_mul_f32_e32 v56, v47, v52
	v_fma_f32 v59, -v44, v55, v45
	v_fmac_f32_e32 v54, v58, v50
	v_mul_f32_e32 v57, v49, v53
	v_fma_f32 v60, -v46, v56, v47
	v_fmac_f32_e32 v55, v59, v51
	v_fma_f32 v12, -v12, v54, v43
	v_fma_f32 v61, -v48, v57, v49
	v_fmac_f32_e32 v56, v60, v52
	v_fma_f32 v43, -v44, v55, v45
	v_div_fmas_f32 v12, v12, v50, v54
	s_mov_b64 vcc, s[0:1]
	v_fmac_f32_e32 v57, v61, v53
	v_fma_f32 v44, -v46, v56, v47
	v_div_fixup_f32 v31, v12, v31, 1.0
	v_div_fmas_f32 v12, v43, v51, v55
	s_mov_b64 vcc, s[4:5]
	v_fma_f32 v45, -v48, v57, v49
	v_div_fixup_f32 v30, v12, v30, 1.0
	v_div_fmas_f32 v12, v44, v52, v56
	s_mov_b64 vcc, s[6:7]
	v_div_fixup_f32 v35, v12, v35, 1.0
	v_div_fmas_f32 v12, v45, v53, v57
	v_div_fixup_f32 v34, v12, v34, 1.0
	v_mul_f32_e32 v20, v20, v30
	v_mul_f32_e32 v21, v21, v31
	v_mul_f32_e32 v22, v22, v34
	v_mul_f32_e32 v23, v23, v35
	global_store_dwordx4 v[28:29], v[20:23], off
	global_load_dwordx2 v[20:21], v[32:33], off
	s_waitcnt vmcnt(0)
	v_lshlrev_b32_e32 v12, 16, v20
	v_and_b32_e32 v20, 0xffff0000, v20
	v_lshlrev_b32_e32 v22, 16, v21
	v_and_b32_e32 v21, 0xffff0000, v21
	v_mul_f32_e32 v12, 0xbfb8aa3b, v12
	v_mul_f32_e32 v30, 0xbfb8aa3b, v20
	v_mul_f32_e32 v21, 0xbfb8aa3b, v21
	v_exp_f32_e32 v20, v12
	v_exp_f32_e32 v23, v21
	v_exp_f32_e32 v21, v30
	v_mul_f32_e32 v22, 0xbfb8aa3b, v22
	v_exp_f32_e32 v22, v22
	v_add_f32_e32 v20, 1.0, v20
	v_add_f32_e32 v21, 1.0, v21
	s_nop 0
	v_div_scale_f32 v12, s[0:1], v21, v21, 1.0
	v_add_f32_e32 v22, 1.0, v22
	v_add_f32_e32 v23, 1.0, v23
	v_div_scale_f32 v31, s[0:1], v20, v20, 1.0
	v_rcp_f32_e32 v44, v12
	v_div_scale_f32 v33, s[4:5], v23, v23, 1.0
	v_rcp_f32_e32 v45, v31
	v_div_scale_f32 v35, s[6:7], v22, v22, 1.0
	v_rcp_f32_e32 v46, v33
	v_rcp_f32_e32 v47, v35
	v_fma_f32 v48, -v12, v44, 1.0
	v_div_scale_f32 v30, vcc, 1.0, v21, 1.0
	v_fma_f32 v49, -v31, v45, 1.0
	v_fmac_f32_e32 v44, v48, v44
	v_div_scale_f32 v32, s[0:1], 1.0, v20, 1.0
	v_fma_f32 v50, -v33, v46, 1.0
	v_fmac_f32_e32 v45, v49, v45
	v_mul_f32_e32 v48, v30, v44
	v_div_scale_f32 v34, s[4:5], 1.0, v23, 1.0
	v_fma_f32 v51, -v35, v47, 1.0
	v_fmac_f32_e32 v46, v50, v46
	v_mul_f32_e32 v49, v32, v45
	v_fma_f32 v52, -v12, v48, v30
	v_div_scale_f32 v43, s[6:7], 1.0, v22, 1.0
	v_fmac_f32_e32 v47, v51, v47
	v_mul_f32_e32 v50, v34, v46
	v_fma_f32 v53, -v31, v49, v32
	v_fmac_f32_e32 v48, v52, v44
	v_mul_f32_e32 v51, v43, v47
	v_fma_f32 v54, -v33, v50, v34
	v_fmac_f32_e32 v49, v53, v45
	v_fma_f32 v12, -v12, v48, v30
	v_fma_f32 v55, -v35, v51, v43
	v_fmac_f32_e32 v50, v54, v46
	v_fma_f32 v30, -v31, v49, v32
	v_div_fmas_f32 v12, v12, v44, v48
	s_mov_b64 vcc, s[0:1]
	v_fmac_f32_e32 v51, v55, v47
	v_fma_f32 v31, -v33, v50, v34
	v_div_fixup_f32 v21, v12, v21, 1.0
	v_div_fmas_f32 v12, v30, v45, v49
	s_mov_b64 vcc, s[4:5]
	v_fma_f32 v32, -v35, v51, v43
	v_div_fixup_f32 v20, v12, v20, 1.0
	v_div_fmas_f32 v12, v31, v46, v50
	s_mov_b64 vcc, s[6:7]
	v_div_fixup_f32 v23, v12, v23, 1.0
	v_div_fmas_f32 v12, v32, v47, v51
	v_div_fixup_f32 v22, v12, v22, 1.0
	v_mul_f32_e32 v20, v24, v20
	v_mul_f32_e32 v21, v25, v21
	v_mul_f32_e32 v22, v26, v22
	v_mul_f32_e32 v23, v27, v23
	global_store_dwordx4 v[28:29], v[20:23], off offset:64
	s_barrier
	s_cbranch_scc0 .LBB0_578
	v_lshlrev_b32_e32 v10, 1, v10
	v_mov_b32_e32 v11, 0
	v_lshl_add_u64 v[0:1], s[86:87], 0, v[10:11]
	s_mov_b64 s[0:1], 0x24a00800
	v_lshl_add_u64 v[12:13], v[0:1], 0, s[0:1]
	s_mov_b64 s[0:1], 0x3000800
	s_mov_b32 s15, 0
	v_lshl_add_u64 v[14:15], v[0:1], 0, s[0:1]
	s_mov_b64 s[16:17], 0x30000
	s_mov_b32 s21, 0x30000
	s_mov_b32 s8, s15
	s_mov_b32 s9, s15
	s_mov_b32 s10, s15
	s_mov_b32 s11, s15
	s_movk_i32 s22, 0x5e00
	s_mov_b64 s[18:19], 0x4c00
	v_mov_b32_e32 v32, 0x1800
	s_mov_b32 s23, s2

; __device__ __forceinline__ unsigned cvt_pk_bf16(float lo, float hi) { unsigned r; asm volatile("v_cvt_pk_bf16_f32 %0, %1, %2" : "=v"(r) : "v"(lo), "v"(hi)); return r; }
; __device__ __forceinline__ float bflo(unsigned w) { return __uint_as_float(w << 16); }
; __device__ __forceinline__ float bfhi(unsigned w) { return __uint_as_float(w & 0xffff0000u); }
; __device__ __forceinline__ float sigmoidf_(float x) { return 1.f / (1.f + __expf(-x)); }
; __global__ void __launch_bounds__(512, 2) hybrid_fwd(Args a) {
;     ...
;             const f32x4 g0 = *(const f32x4*)(a.gla_norm + lane * 8), g1 = *(const f32x4*)(a.gla_norm + lane * 8 + 4);
;             const float gn[8] = {g0[0], g0[1], g0[2], g0[3], g1[0], g1[1], g1[2], g1[3]};
; #pragma unroll
;             for (int u = 0; u < 4; ++u) { const int it = it0 + u * NGW; const int row = it >> 2, h = it & 3; const float rs = rsqrtf(wave_sum(gp[u]) * (1.0f / 512.0f) + EPS);
;                 float o[8] = {bflo(ow[u].x), bfhi(ow[u].x), bflo(ow[u].y), bfhi(ow[u].y), bflo(ow[u].z), bfhi(ow[u].z), bflo(ow[u].w), bfhi(ow[u].w)};
;                 float r[8] = {bflo(rw[u].x), bfhi(rw[u].x), bflo(rw[u].y), bfhi(rw[u].y), bflo(rw[u].z), bfhi(rw[u].z), bflo(rw[u].w), bfhi(rw[u].w)};
; #pragma unroll
;                 for (int e = 0; e < 8; ++e) o[e] = o[e] * rs * gn[e] * (r[e] * sigmoidf_(r[e]));
;                 *(u32x4*)(OCAT + (size_t)row * OC + 1024 + h * 512 + lane * 8) = (u32x4){cvt_pk_bf16(o[0], o[1]), cvt_pk_bf16(o[2], o[3]), cvt_pk_bf16(o[4], o[5]), cvt_pk_bf16(o[6], o[7])}; } }
.LBB0_583:
	s_or_b64 exec, exec, s[0:1]
	global_load_dwordx4 v[4:7], v[44:45], off nt
	global_load_dwordx4 v[0:3], v[44:45], off offset:16 nt
	s_waitcnt vmcnt(0)
	ds_bpermute_b32 v49, v62, v73
	v_lshlrev_b32_e32 v79, 16, v37
	v_lshlrev_b32_e32 v78, 16, v33
	v_and_b32_e32 v81, 0xffff0000, v37
	v_and_b32_e32 v80, 0xffff0000, v33
	v_lshlrev_b32_e32 v37, 16, v39
	v_and_b32_e32 v33, 0xffff0000, v39
	s_waitcnt lgkmcnt(0)
	v_add_f32_e32 v39, v73, v49
	ds_bpermute_b32 v49, v63, v39
	v_lshlrev_b32_e32 v75, 16, v36
	v_and_b32_e32 v77, 0xffff0000, v36
	v_lshlrev_b32_e32 v82, 16, v34
	v_and_b32_e32 v84, 0xffff0000, v34
	s_waitcnt lgkmcnt(0)
	v_add_f32_e32 v39, v39, v49
	ds_bpermute_b32 v49, v64, v39
	v_mul_f32_e32 v34, 0xbfb8aa3b, v75
	v_lshlrev_b32_e32 v74, 16, v32
	v_and_b32_e32 v76, 0xffff0000, v32
	v_lshlrev_b32_e32 v36, 16, v35
	s_waitcnt lgkmcnt(0)
	v_add_f32_e32 v39, v39, v49
	ds_bpermute_b32 v49, v65, v39
	v_and_b32_e32 v32, 0xffff0000, v35
	v_mul_f32_e32 v35, 0xbfb8aa3b, v77
	v_exp_f32_e32 v34, v34
	v_exp_f32_e32 v35, v35
	s_waitcnt lgkmcnt(0)
	v_add_f32_e32 v39, v39, v49
	ds_bpermute_b32 v49, v66, v39
	v_lshlrev_b32_e32 v83, 16, v38
	v_and_b32_e32 v85, 0xffff0000, v38
	v_mul_f32_e32 v38, 0xbfb8aa3b, v79
	v_add_f32_e32 v34, 1.0, v34
	s_waitcnt lgkmcnt(0)
	v_add_f32_e32 v39, v39, v49
	ds_bpermute_b32 v49, v67, v39
	v_exp_f32_e32 v38, v38
	v_add_f32_e32 v73, 1.0, v35
	v_div_scale_f32 v35, s[0:1], v34, v34, 1.0
	v_rcp_f32_e32 v89, v35
	v_div_scale_f32 v87, s[0:1], v73, v73, 1.0
	v_rcp_f32_e32 v90, v87
	v_add_f32_e32 v86, 1.0, v38
	s_waitcnt lgkmcnt(0)
	v_add_f32_e32 v39, v39, v49
	v_div_scale_f32 v91, s[6:7], v86, v86, 1.0
	v_fma_f32 v93, -v35, v89, 1.0
	v_fmamk_f32 v39, v39, 0x3b000000, v69
	v_div_scale_f32 v38, vcc, 1.0, v34, 1.0
	v_fmac_f32_e32 v89, v93, v89
	v_mul_f32_e32 v49, 0x4b800000, v39
	v_cmp_gt_f32_e64 s[6:7], s18, v39
	v_fma_f32 v94, -v87, v90, 1.0
	v_mul_f32_e32 v93, v38, v89
	v_cndmask_b32_e64 v39, v39, v49, s[6:7]
	v_div_scale_f32 v88, s[0:1], 1.0, v73, 1.0
	v_fmac_f32_e32 v90, v94, v90
	v_fma_f32 v95, -v35, v93, v38
	v_rsq_f32_e32 v39, v39
	v_mul_f32_e32 v94, v88, v90
	v_fmac_f32_e32 v93, v95, v89
	v_fma_f32 v96, -v87, v94, v88
	v_fma_f32 v35, -v35, v93, v38
	v_fmac_f32_e32 v94, v96, v90
	v_div_fmas_f32 v35, v35, v89, v93
	v_rcp_f32_e32 v92, v91
	v_fma_f32 v38, -v87, v94, v88
	v_div_fixup_f32 v35, v35, v34, 1.0
	s_mov_b64 vcc, s[0:1]
	v_mul_f32_e32 v34, 0x45800000, v39
	v_div_fmas_f32 v49, v38, v90, v94
	v_cndmask_b32_e64 v34, v39, v34, s[6:7]
	v_mul_f32_e32 v38, v34, v74
	v_mul_f32_e32 v39, v35, v75
	v_div_fixup_f32 v35, v49, v73, 1.0
	v_mul_f32_e32 v74, v34, v76
	v_mul_f32_e32 v75, v35, v77
	v_add_u32_e32 v68, s15, v68
	v_mul_f32_e32 v35, v4, v38
	v_mul_f32_e32 v49, v35, v39
	v_fma_f32 v35, -v91, v92, 1.0
	v_mul_f32_e32 v38, v5, v74
	v_fmac_f32_e32 v92, v35, v92
	v_div_scale_f32 v35, vcc, 1.0, v86, 1.0
	v_mul_f32_e32 v73, v38, v75
	v_mul_f32_e32 v38, v35, v92
	v_fma_f32 v39, -v91, v38, v35
	v_fmac_f32_e32 v38, v39, v92
	v_mul_f32_e32 v39, 0xbfb8aa3b, v81
	v_exp_f32_e32 v39, v39
	v_fma_f32 v35, -v91, v38, v35
	v_div_fmas_f32 v35, v35, v92, v38
	v_div_fixup_f32 v35, v35, v86, 1.0
	v_add_f32_e32 v74, 1.0, v39
	v_div_scale_f32 v75, s[0:1], v74, v74, 1.0
	v_rcp_f32_e32 v76, v75
	v_mul_f32_e32 v38, v34, v78
	v_mul_f32_e32 v39, v35, v79
	s_nop 0
	v_mul_f32_e32 v35, v6, v38
	v_mul_f32_e32 v77, v35, v39
	v_fma_f32 v35, -v75, v76, 1.0
	v_fmac_f32_e32 v76, v35, v76
	v_div_scale_f32 v35, vcc, 1.0, v74, 1.0
	v_mul_f32_e32 v38, v35, v76
	v_fma_f32 v39, -v75, v38, v35
	v_fmac_f32_e32 v38, v39, v76
	v_mul_f32_e32 v39, 0xbfb8aa3b, v83
	v_exp_f32_e32 v39, v39
	v_fma_f32 v35, -v75, v38, v35
	v_div_fmas_f32 v35, v35, v76, v38
	v_div_fixup_f32 v35, v35, v74, 1.0
	v_add_f32_e32 v74, 1.0, v39
	v_div_scale_f32 v75, s[0:1], v74, v74, 1.0
	v_rcp_f32_e32 v76, v75
	v_mul_f32_e32 v38, v34, v80
	v_mul_f32_e32 v39, v35, v81
	s_nop 0
	v_mul_f32_e32 v35, v7, v38
	v_mul_f32_e32 v78, v35, v39
	v_fma_f32 v35, -v75, v76, 1.0
	v_fmac_f32_e32 v76, v35, v76
	v_div_scale_f32 v35, vcc, 1.0, v74, 1.0
	v_mul_f32_e32 v38, v35, v76
	v_fma_f32 v39, -v75, v38, v35
	v_fmac_f32_e32 v38, v39, v76
	v_mul_f32_e32 v39, 0xbfb8aa3b, v85
	v_exp_f32_e32 v39, v39
	v_fma_f32 v35, -v75, v38, v35
	v_div_fmas_f32 v35, v35, v76, v38
	v_div_fixup_f32 v35, v35, v74, 1.0
	v_add_f32_e32 v74, 1.0, v39
	v_div_scale_f32 v75, s[0:1], v74, v74, 1.0
	v_rcp_f32_e32 v76, v75
	v_mul_f32_e32 v38, v34, v82
	v_mul_f32_e32 v39, v35, v83
	s_nop 0
	v_mul_f32_e32 v35, v0, v38
	v_mul_f32_e32 v79, v35, v39
	v_fma_f32 v35, -v75, v76, 1.0
	v_fmac_f32_e32 v76, v35, v76
	v_div_scale_f32 v35, vcc, 1.0, v74, 1.0
	v_mul_f32_e32 v38, v35, v76
	v_fma_f32 v39, -v75, v38, v35
	v_fmac_f32_e32 v38, v39, v76
	v_mul_f32_e32 v39, 0xbfb8aa3b, v37
	v_exp_f32_e32 v39, v39
	v_fma_f32 v35, -v75, v38, v35
	v_div_fmas_f32 v35, v35, v76, v38
	v_div_fixup_f32 v35, v35, v74, 1.0
	v_add_f32_e32 v74, 1.0, v39
	v_div_scale_f32 v75, s[0:1], v74, v74, 1.0
	v_rcp_f32_e32 v76, v75
	v_mul_f32_e32 v38, v34, v84
	v_mul_f32_e32 v39, v35, v85
	s_nop 0
	v_mul_f32_e32 v35, v1, v38
	v_mul_f32_e32 v38, v35, v39
	v_fma_f32 v35, -v75, v76, 1.0
	v_fmac_f32_e32 v76, v35, v76
	v_div_scale_f32 v35, vcc, 1.0, v74, 1.0
	v_mul_f32_e32 v39, v35, v76
	v_fma_f32 v80, -v75, v39, v35
	v_fmac_f32_e32 v39, v80, v76
	v_fma_f32 v35, -v75, v39, v35
	v_div_fmas_f32 v35, v35, v76, v39
	v_mul_f32_e32 v39, 0xbfb8aa3b, v33
	ds_bpermute_b32 v75, v62, v72
	v_exp_f32_e32 v39, v39
	v_div_fixup_f32 v35, v35, v74, 1.0
	v_mul_f32_e32 v36, v34, v36
	v_mul_f32_e32 v37, v35, v37
	s_nop 0
	v_mul_f32_e32 v35, v2, v36
	v_add_f32_e32 v36, 1.0, v39
	s_waitcnt lgkmcnt(0)
; __device__ __forceinline__ unsigned cvt_pk_bf16(float lo, float hi) { unsigned r; asm volatile("v_cvt_pk_bf16_f32 %0, %1, %2" : "=v"(r) : "v"(lo), "v"(hi)); return r; }
; __device__ __forceinline__ float bflo(unsigned w) { return __uint_as_float(w << 16); }
; __device__ __forceinline__ float bfhi(unsigned w) { return __uint_as_float(w & 0xffff0000u); }
; __device__ __forceinline__ float sigmoidf_(float x) { return 1.f / (1.f + __expf(-x)); }
; __global__ void __launch_bounds__(512, 2) hybrid_fwd(Args a) {
;     ...
;             const f32x4 g0 = *(const f32x4*)(a.gla_norm + lane * 8), g1 = *(const f32x4*)(a.gla_norm + lane * 8 + 4);
;             const float gn[8] = {g0[0], g0[1], g0[2], g0[3], g1[0], g1[1], g1[2], g1[3]};
; #pragma unroll
;             for (int u = 0; u < 4; ++u) { const int it = it0 + u * NGW; const int row = it >> 2, h = it & 3; const float rs = rsqrtf(wave_sum(gp[u]) * (1.0f / 512.0f) + EPS);
;                 float o[8] = {bflo(ow[u].x), bfhi(ow[u].x), bflo(ow[u].y), bfhi(ow[u].y), bflo(ow[u].z), bfhi(ow[u].z), bflo(ow[u].w), bfhi(ow[u].w)};
;                 float r[8] = {bflo(rw[u].x), bfhi(rw[u].x), bflo(rw[u].y), bfhi(rw[u].y), bflo(rw[u].z), bfhi(rw[u].z), bflo(rw[u].w), bfhi(rw[u].w)};
; #pragma unroll
;                 for (int e = 0; e < 8; ++e) o[e] = o[e] * rs * gn[e] * (r[e] * sigmoidf_(r[e]));
;                 *(u32x4*)(OCAT + (size_t)row * OC + 1024 + h * 512 + lane * 8) = (u32x4){cvt_pk_bf16(o[0], o[1]), cvt_pk_bf16(o[2], o[3]), cvt_pk_bf16(o[4], o[5]), cvt_pk_bf16(o[6], o[7])}; } }
	v_add_f32_e32 v39, v72, v75
	ds_bpermute_b32 v72, v63, v39
	v_mul_f32_e32 v37, v35, v37
	v_div_scale_f32 v74, s[0:1], v36, v36, 1.0
	v_rcp_f32_e32 v75, v74
	s_waitcnt lgkmcnt(0)
	v_add_f32_e32 v35, v39, v72
	ds_bpermute_b32 v39, v64, v35
	v_fma_f32 v72, -v74, v75, 1.0
	v_fmac_f32_e32 v75, v72, v75
	v_div_scale_f32 v72, vcc, 1.0, v36, 1.0
	s_waitcnt lgkmcnt(0)
	v_add_f32_e32 v35, v35, v39
	ds_bpermute_b32 v39, v65, v35
	v_mul_f32_e32 v76, v72, v75
	v_fma_f32 v80, -v74, v76, v72
	v_fmac_f32_e32 v76, v80, v75
	v_fma_f32 v72, -v74, v76, v72
	s_waitcnt lgkmcnt(0)
	v_add_f32_e32 v39, v35, v39
	ds_bpermute_b32 v74, v66, v39
	v_div_fmas_f32 v35, v72, v75, v76
	v_div_fixup_f32 v35, v35, v36, 1.0
	v_mul_f32_e32 v32, v34, v32
	v_mul_f32_e32 v33, v35, v33
	v_lshlrev_b32_e32 v72, 16, v27
	s_waitcnt lgkmcnt(0)
	v_add_f32_e32 v34, v39, v74
	ds_bpermute_b32 v35, v67, v34
	v_mul_f32_e32 v32, v3, v32
	v_mul_f32_e32 v36, v32, v33
	v_cvt_pk_bf16_f32 v32, v49, v73
	v_cvt_pk_bf16_f32 v33, v77, v78
	s_waitcnt lgkmcnt(0)
	v_add_f32_e32 v34, v34, v35
	v_fmamk_f32 v34, v34, 0x3b000000, v69
	v_mul_f32_e32 v35, 0x4b800000, v34
	v_cmp_gt_f32_e32 vcc, s18, v34
	v_lshlrev_b32_e32 v73, 16, v31
	v_and_b32_e32 v31, 0xffff0000, v31
	v_cndmask_b32_e32 v34, v34, v35, vcc
	v_rsq_f32_e32 v39, v34
	v_cvt_pk_bf16_f32 v34, v79, v38
	v_cvt_pk_bf16_f32 v35, v37, v36
	global_store_dwordx4 v[60:61], v[32:35], off offset:2048
	v_and_b32_e32 v36, 0xffff0000, v24
	v_and_b32_e32 v60, 0xffff0000, v26
	v_lshlrev_b32_e32 v35, 16, v28
	v_mul_f32_e32 v33, 0xbfb8aa3b, v35
	v_exp_f32_e32 v33, v33
	v_lshlrev_b32_e32 v34, 16, v24
	v_lshlrev_b32_e32 v24, 16, v26
	v_mul_f32_e32 v32, 0x45800000, v39
	v_add_f32_e32 v26, 1.0, v33
	v_div_scale_f32 v33, s[0:1], v26, v26, 1.0
	v_rcp_f32_e32 v49, v33
	v_and_b32_e32 v37, 0xffff0000, v28
	v_lshlrev_b32_e32 v38, 16, v25
	v_and_b32_e32 v28, 0xffff0000, v25
	v_lshlrev_b32_e32 v25, 16, v30
	v_and_b32_e32 v61, 0xffff0000, v30
	v_and_b32_e32 v30, 0xffff0000, v27
	v_fma_f32 v27, -v33, v49, 1.0
	v_cndmask_b32_e32 v32, v39, v32, vcc
	v_fmac_f32_e32 v49, v27, v49
	v_div_scale_f32 v27, vcc, 1.0, v26, 1.0
	v_mul_f32_e32 v74, v27, v49
	v_fma_f32 v75, -v33, v74, v27
	v_fmac_f32_e32 v74, v75, v49
	v_fma_f32 v27, -v33, v74, v27
	v_mul_f32_e32 v33, 0xbfb8aa3b, v37
	v_exp_f32_e32 v75, v33
	v_div_fmas_f32 v27, v27, v49, v74
	v_div_fixup_f32 v33, v27, v26, 1.0
	v_mul_f32_e32 v26, v32, v34
	v_mul_f32_e32 v27, v33, v35
	v_add_f32_e32 v49, 1.0, v75
	v_div_scale_f32 v74, s[0:1], v49, v49, 1.0
	v_rcp_f32_e32 v75, v74
	v_mul_f32_e32 v26, v4, v26
	v_mul_f32_e32 v34, v26, v27
	v_lshlrev_b32_e32 v39, 16, v29
	v_fma_f32 v26, -v74, v75, 1.0
	v_fmac_f32_e32 v75, v26, v75
	v_div_scale_f32 v26, vcc, 1.0, v49, 1.0
	v_mul_f32_e32 v27, v26, v75
	v_fma_f32 v33, -v74, v27, v26
	v_fmac_f32_e32 v27, v33, v75
	v_mul_f32_e32 v33, 0xbfb8aa3b, v39
	v_exp_f32_e32 v35, v33
	v_fma_f32 v26, -v74, v27, v26
	v_div_fmas_f32 v26, v26, v75, v27
	v_div_fixup_f32 v33, v26, v49, 1.0
	v_add_f32_e32 v35, 1.0, v35
	v_div_scale_f32 v49, s[0:1], v35, v35, 1.0
	v_rcp_f32_e32 v74, v49
	v_mul_f32_e32 v26, v32, v36
	v_mul_f32_e32 v27, v33, v37
	v_and_b32_e32 v29, 0xffff0000, v29
	v_mul_f32_e32 v26, v5, v26
	v_mul_f32_e32 v36, v26, v27
	v_fma_f32 v26, -v49, v74, 1.0
	v_fmac_f32_e32 v74, v26, v74
	v_div_scale_f32 v26, vcc, 1.0, v35, 1.0
	v_mul_f32_e32 v27, v26, v74
	v_fma_f32 v33, -v49, v27, v26
	v_fmac_f32_e32 v27, v33, v74
	v_mul_f32_e32 v33, 0xbfb8aa3b, v29
	v_exp_f32_e32 v37, v33
	v_fma_f32 v26, -v49, v27, v26
	v_div_fmas_f32 v26, v26, v74, v27
	v_div_fixup_f32 v33, v26, v35, 1.0
	v_add_f32_e32 v35, 1.0, v37
	v_div_scale_f32 v37, s[0:1], v35, v35, 1.0
	v_rcp_f32_e32 v49, v37
	v_mul_f32_e32 v26, v32, v38
	v_mul_f32_e32 v27, v33, v39
	s_nop 0
	v_mul_f32_e32 v26, v6, v26
	v_mul_f32_e32 v38, v26, v27
	v_fma_f32 v26, -v37, v49, 1.0
	v_fmac_f32_e32 v49, v26, v49
	v_div_scale_f32 v26, vcc, 1.0, v35, 1.0
	v_mul_f32_e32 v27, v26, v49
	v_fma_f32 v33, -v37, v27, v26
	v_fmac_f32_e32 v27, v33, v49
	v_mul_f32_e32 v33, 0xbfb8aa3b, v25
	v_fma_f32 v26, -v37, v27, v26
	v_exp_f32_e32 v37, v33
	v_div_fmas_f32 v26, v26, v49, v27
	v_div_fixup_f32 v33, v26, v35, 1.0
	v_mul_f32_e32 v26, v32, v28
	v_mul_f32_e32 v27, v33, v29
	v_add_f32_e32 v35, 1.0, v37
	v_div_scale_f32 v37, s[0:1], v35, v35, 1.0
	v_rcp_f32_e32 v39, v37
	v_mul_f32_e32 v26, v7, v26
	v_mul_f32_e32 v26, v26, v27
	v_fma_f32 v27, -v37, v39, 1.0
	v_fmac_f32_e32 v39, v27, v39
	v_div_scale_f32 v27, vcc, 1.0, v35, 1.0
	v_mul_f32_e32 v28, v27, v39
	v_fma_f32 v29, -v37, v28, v27
	v_fmac_f32_e32 v28, v29, v39
	v_mul_f32_e32 v29, 0xbfb8aa3b, v61
	v_exp_f32_e32 v29, v29
	v_fma_f32 v27, -v37, v28, v27
	v_div_fmas_f32 v27, v27, v39, v28
	v_div_fixup_f32 v33, v27, v35, 1.0
	v_add_f32_e32 v27, 1.0, v29
	v_div_scale_f32 v28, s[0:1], v27, v27, 1.0
	v_rcp_f32_e32 v29, v28
	v_mul_f32_e32 v24, v32, v24
	v_mul_f32_e32 v25, v33, v25
	s_nop 0
	v_mul_f32_e32 v24, v0, v24
	v_mul_f32_e32 v35, v24, v25
	v_fma_f32 v24, -v28, v29, 1.0
	v_fmac_f32_e32 v29, v24, v29
	v_div_scale_f32 v24, vcc, 1.0, v27, 1.0
	v_mul_f32_e32 v25, v24, v29
	v_fma_f32 v33, -v28, v25, v24
	v_fmac_f32_e32 v25, v33, v29
	v_fma_f32 v24, -v28, v25, v24
	v_mul_f32_e32 v28, 0xbfb8aa3b, v73
	v_exp_f32_e32 v28, v28
	v_div_fmas_f32 v24, v24, v29, v25
	v_div_fixup_f32 v33, v24, v27, 1.0
	v_mul_f32_e32 v24, v32, v60
	v_mul_f32_e32 v25, v33, v61
	v_add_f32_e32 v27, 1.0, v28
	v_div_scale_f32 v28, s[0:1], v27, v27, 1.0
	v_rcp_f32_e32 v29, v28
	v_mul_f32_e32 v24, v1, v24
	v_mul_f32_e32 v37, v24, v25
	v_fma_f32 v24, -v28, v29, 1.0
	v_fmac_f32_e32 v29, v24, v29
	v_div_scale_f32 v24, vcc, 1.0, v27, 1.0
	v_mul_f32_e32 v25, v24, v29
	v_fma_f32 v33, -v28, v25, v24
	v_fmac_f32_e32 v25, v33, v29
	v_fma_f32 v24, -v28, v25, v24
	v_div_fmas_f32 v24, v24, v29, v25
	v_mul_f32_e32 v25, 0xbfb8aa3b, v31
	ds_bpermute_b32 v29, v62, v71
	v_exp_f32_e32 v28, v25
	v_div_fixup_f32 v33, v24, v27, 1.0
	v_mul_f32_e32 v24, v32, v72
	v_mul_f32_e32 v25, v33, v73
	v_add_f32_e32 v27, 1.0, v28
	s_waitcnt lgkmcnt(0)
; __device__ __forceinline__ unsigned cvt_pk_bf16(float lo, float hi) { unsigned r; asm volatile("v_cvt_pk_bf16_f32 %0, %1, %2" : "=v"(r) : "v"(lo), "v"(hi)); return r; }
; __device__ __forceinline__ float bflo(unsigned w) { return __uint_as_float(w << 16); }
; __device__ __forceinline__ float bfhi(unsigned w) { return __uint_as_float(w & 0xffff0000u); }
; __device__ __forceinline__ float sigmoidf_(float x) { return 1.f / (1.f + __expf(-x)); }
; __global__ void __launch_bounds__(512, 2) hybrid_fwd(Args a) {
;     ...
;             const f32x4 g0 = *(const f32x4*)(a.gla_norm + lane * 8), g1 = *(const f32x4*)(a.gla_norm + lane * 8 + 4);
;             const float gn[8] = {g0[0], g0[1], g0[2], g0[3], g1[0], g1[1], g1[2], g1[3]};
; #pragma unroll
;             for (int u = 0; u < 4; ++u) { const int it = it0 + u * NGW; const int row = it >> 2, h = it & 3; const float rs = rsqrtf(wave_sum(gp[u]) * (1.0f / 512.0f) + EPS);
;                 float o[8] = {bflo(ow[u].x), bfhi(ow[u].x), bflo(ow[u].y), bfhi(ow[u].y), bflo(ow[u].z), bfhi(ow[u].z), bflo(ow[u].w), bfhi(ow[u].w)};
;                 float r[8] = {bflo(rw[u].x), bfhi(rw[u].x), bflo(rw[u].y), bfhi(rw[u].y), bflo(rw[u].z), bfhi(rw[u].z), bflo(rw[u].w), bfhi(rw[u].w)};
; #pragma unroll
;                 for (int e = 0; e < 8; ++e) o[e] = o[e] * rs * gn[e] * (r[e] * sigmoidf_(r[e]));
;                 *(u32x4*)(OCAT + (size_t)row * OC + 1024 + h * 512 + lane * 8) = (u32x4){cvt_pk_bf16(o[0], o[1]), cvt_pk_bf16(o[2], o[3]), cvt_pk_bf16(o[4], o[5]), cvt_pk_bf16(o[6], o[7])}; } }
	v_add_f32_e32 v28, v71, v29
	ds_bpermute_b32 v29, v63, v28
	v_mul_f32_e32 v24, v2, v24
	v_mul_f32_e32 v49, v24, v25
	v_div_scale_f32 v33, s[0:1], v27, v27, 1.0
	s_waitcnt lgkmcnt(0)
	v_add_f32_e32 v24, v28, v29
	ds_bpermute_b32 v25, v64, v24
	v_rcp_f32_e32 v39, v33
	s_waitcnt lgkmcnt(0)
	v_add_f32_e32 v24, v24, v25
	ds_bpermute_b32 v25, v65, v24
	v_fma_f32 v28, -v33, v39, 1.0
	v_fmac_f32_e32 v39, v28, v39
	v_div_scale_f32 v28, vcc, 1.0, v27, 1.0
	v_mul_f32_e32 v29, v28, v39
	v_fma_f32 v60, -v33, v29, v28
	v_fmac_f32_e32 v29, v60, v39
	s_waitcnt lgkmcnt(0)
	v_add_f32_e32 v60, v24, v25
	ds_bpermute_b32 v61, v66, v60
	v_fma_f32 v28, -v33, v29, v28
	v_div_fmas_f32 v24, v28, v39, v29
	v_div_fixup_f32 v33, v24, v27, 1.0
	v_mul_f32_e32 v24, v32, v30
	v_mul_f32_e32 v25, v33, v31
	s_waitcnt lgkmcnt(0)
	v_add_f32_e32 v27, v60, v61
	ds_bpermute_b32 v28, v67, v27
	v_mul_f32_e32 v24, v3, v24
	v_mul_f32_e32 v29, v24, v25
	v_cvt_pk_bf16_f32 v24, v34, v36
	v_cvt_pk_bf16_f32 v25, v38, v26
	s_waitcnt lgkmcnt(0)
	v_add_f32_e32 v26, v27, v28
	v_fmamk_f32 v26, v26, 0x3b000000, v69
	v_mul_f32_e32 v27, 0x4b800000, v26
	v_cmp_gt_f32_e32 vcc, s18, v26
	v_and_b32_e32 v32, 0xffff0000, v18
	v_lshlrev_b32_e32 v30, 16, v17
	v_cndmask_b32_e32 v26, v26, v27, vcc
	v_rsq_f32_e32 v28, v26
	v_cvt_pk_bf16_f32 v26, v35, v37
	v_cvt_pk_bf16_f32 v27, v49, v29
	global_store_dwordx4 v[58:59], v[24:27], off offset:2048
	v_and_b32_e32 v29, 0xffff0000, v20
	v_and_b32_e32 v33, 0xffff0000, v22
	v_lshlrev_b32_e32 v27, 16, v20
	v_mul_f32_e32 v25, 0xbfb8aa3b, v27
	v_exp_f32_e32 v25, v25
	v_mul_f32_e32 v24, 0x45800000, v28
	v_cndmask_b32_e32 v24, v28, v24, vcc
	v_lshlrev_b32_e32 v26, 16, v16
	v_and_b32_e32 v28, 0xffff0000, v16
	v_lshlrev_b32_e32 v16, 16, v18
	v_add_f32_e32 v18, 1.0, v25
	v_div_scale_f32 v25, s[0:1], v18, v18, 1.0
	v_rcp_f32_e32 v36, v25
	v_and_b32_e32 v20, 0xffff0000, v17
	v_lshlrev_b32_e32 v17, 16, v22
	v_lshlrev_b32_e32 v34, 16, v19
	v_and_b32_e32 v22, 0xffff0000, v19
	v_fma_f32 v19, -v25, v36, 1.0
	v_fmac_f32_e32 v36, v19, v36
	v_div_scale_f32 v19, vcc, 1.0, v18, 1.0
	v_mul_f32_e32 v37, v19, v36
	v_fma_f32 v38, -v25, v37, v19
	v_fmac_f32_e32 v37, v38, v36
	v_fma_f32 v19, -v25, v37, v19
	v_mul_f32_e32 v25, 0xbfb8aa3b, v29
	v_exp_f32_e32 v38, v25
	v_div_fmas_f32 v19, v19, v36, v37
	v_div_fixup_f32 v25, v19, v18, 1.0
	v_mul_f32_e32 v18, v24, v26
	v_mul_f32_e32 v19, v25, v27
	v_add_f32_e32 v36, 1.0, v38
	v_div_scale_f32 v37, s[0:1], v36, v36, 1.0
	v_rcp_f32_e32 v38, v37
	v_mul_f32_e32 v18, v4, v18
	v_mul_f32_e32 v26, v18, v19
	v_lshlrev_b32_e32 v31, 16, v21
	v_fma_f32 v18, -v37, v38, 1.0
	v_fmac_f32_e32 v38, v18, v38
	v_div_scale_f32 v18, vcc, 1.0, v36, 1.0
	v_mul_f32_e32 v19, v18, v38
	v_fma_f32 v25, -v37, v19, v18
	v_fmac_f32_e32 v19, v25, v38
	v_mul_f32_e32 v25, 0xbfb8aa3b, v31
	v_exp_f32_e32 v27, v25
	v_fma_f32 v18, -v37, v19, v18
	v_div_fmas_f32 v18, v18, v38, v19
	v_div_fixup_f32 v25, v18, v36, 1.0
	v_add_f32_e32 v27, 1.0, v27
	v_div_scale_f32 v36, s[0:1], v27, v27, 1.0
	v_rcp_f32_e32 v37, v36
	v_mul_f32_e32 v18, v24, v28
	v_mul_f32_e32 v19, v25, v29
	v_and_b32_e32 v21, 0xffff0000, v21
	v_mul_f32_e32 v18, v5, v18
	v_mul_f32_e32 v28, v18, v19
	v_fma_f32 v18, -v36, v37, 1.0
	v_fmac_f32_e32 v37, v18, v37
	v_div_scale_f32 v18, vcc, 1.0, v27, 1.0
	v_mul_f32_e32 v19, v18, v37
	v_fma_f32 v25, -v36, v19, v18
	v_fmac_f32_e32 v19, v25, v37
	v_mul_f32_e32 v25, 0xbfb8aa3b, v21
	v_exp_f32_e32 v29, v25
	v_fma_f32 v18, -v36, v19, v18
	v_div_fmas_f32 v18, v18, v37, v19
	v_div_fixup_f32 v25, v18, v27, 1.0
	v_add_f32_e32 v27, 1.0, v29
	v_div_scale_f32 v29, s[0:1], v27, v27, 1.0
	v_rcp_f32_e32 v36, v29
	v_mul_f32_e32 v18, v24, v30
	v_mul_f32_e32 v19, v25, v31
	v_lshlrev_b32_e32 v35, 16, v23
	v_mul_f32_e32 v18, v6, v18
	v_mul_f32_e32 v30, v18, v19
	v_fma_f32 v18, -v29, v36, 1.0
	v_fmac_f32_e32 v36, v18, v36
	v_div_scale_f32 v18, vcc, 1.0, v27, 1.0
	v_mul_f32_e32 v19, v18, v36
	v_fma_f32 v25, -v29, v19, v18
	v_fmac_f32_e32 v19, v25, v36
	v_mul_f32_e32 v25, 0xbfb8aa3b, v17
	v_fma_f32 v18, -v29, v19, v18
	v_exp_f32_e32 v29, v25
	v_div_fmas_f32 v18, v18, v36, v19
	v_div_fixup_f32 v25, v18, v27, 1.0
	v_mul_f32_e32 v18, v24, v20
	v_mul_f32_e32 v19, v25, v21
	v_add_f32_e32 v27, 1.0, v29
	v_div_scale_f32 v29, s[0:1], v27, v27, 1.0
	v_rcp_f32_e32 v31, v29
	v_mul_f32_e32 v18, v7, v18
	v_mul_f32_e32 v18, v18, v19
	v_and_b32_e32 v23, 0xffff0000, v23
	v_fma_f32 v19, -v29, v31, 1.0
	v_fmac_f32_e32 v31, v19, v31
	v_div_scale_f32 v19, vcc, 1.0, v27, 1.0
	v_mul_f32_e32 v20, v19, v31
	v_fma_f32 v21, -v29, v20, v19
	v_fmac_f32_e32 v20, v21, v31
	v_mul_f32_e32 v21, 0xbfb8aa3b, v33
	v_exp_f32_e32 v21, v21
	v_fma_f32 v19, -v29, v20, v19
	v_div_fmas_f32 v19, v19, v31, v20
	v_div_fixup_f32 v25, v19, v27, 1.0
	v_add_f32_e32 v19, 1.0, v21
	v_div_scale_f32 v20, s[0:1], v19, v19, 1.0
	v_rcp_f32_e32 v21, v20
	v_mul_f32_e32 v16, v24, v16
	v_mul_f32_e32 v17, v25, v17
	s_nop 0
	v_mul_f32_e32 v16, v0, v16
	v_mul_f32_e32 v27, v16, v17
	v_fma_f32 v16, -v20, v21, 1.0
	v_fmac_f32_e32 v21, v16, v21
	v_div_scale_f32 v16, vcc, 1.0, v19, 1.0
	v_mul_f32_e32 v17, v16, v21
	v_fma_f32 v25, -v20, v17, v16
	v_fmac_f32_e32 v17, v25, v21
	v_fma_f32 v16, -v20, v17, v16
	v_mul_f32_e32 v20, 0xbfb8aa3b, v35
	v_exp_f32_e32 v20, v20
	v_div_fmas_f32 v16, v16, v21, v17
	v_div_fixup_f32 v25, v16, v19, 1.0
	v_mul_f32_e32 v16, v24, v32
	v_mul_f32_e32 v17, v25, v33
	v_add_f32_e32 v19, 1.0, v20
	v_div_scale_f32 v20, s[0:1], v19, v19, 1.0
	v_rcp_f32_e32 v21, v20
	v_mul_f32_e32 v16, v1, v16
	v_mul_f32_e32 v29, v16, v17
	v_fma_f32 v16, -v20, v21, 1.0
	v_fmac_f32_e32 v21, v16, v21
	v_div_scale_f32 v16, vcc, 1.0, v19, 1.0
	v_mul_f32_e32 v17, v16, v21
	v_fma_f32 v25, -v20, v17, v16
	v_fmac_f32_e32 v17, v25, v21
	v_fma_f32 v16, -v20, v17, v16
	v_div_fmas_f32 v16, v16, v21, v17
	v_mul_f32_e32 v17, 0xbfb8aa3b, v23
	ds_bpermute_b32 v21, v62, v40
	v_exp_f32_e32 v20, v17
	v_div_fixup_f32 v25, v16, v19, 1.0
	v_mul_f32_e32 v16, v24, v34
	v_mul_f32_e32 v17, v25, v35
	v_add_f32_e32 v19, 1.0, v20
	s_waitcnt lgkmcnt(0)
; __device__ __forceinline__ unsigned cvt_pk_bf16(float lo, float hi) { unsigned r; asm volatile("v_cvt_pk_bf16_f32 %0, %1, %2" : "=v"(r) : "v"(lo), "v"(hi)); return r; }
; __device__ __forceinline__ float bflo(unsigned w) { return __uint_as_float(w << 16); }
; __device__ __forceinline__ float bfhi(unsigned w) { return __uint_as_float(w & 0xffff0000u); }
; __device__ __forceinline__ float sigmoidf_(float x) { return 1.f / (1.f + __expf(-x)); }
; __global__ void __launch_bounds__(512, 2) hybrid_fwd(Args a) {
;     ...
;             const f32x4 g0 = *(const f32x4*)(a.gla_norm + lane * 8), g1 = *(const f32x4*)(a.gla_norm + lane * 8 + 4);
;             const float gn[8] = {g0[0], g0[1], g0[2], g0[3], g1[0], g1[1], g1[2], g1[3]};
; #pragma unroll
;             for (int u = 0; u < 4; ++u) { const int it = it0 + u * NGW; const int row = it >> 2, h = it & 3; const float rs = rsqrtf(wave_sum(gp[u]) * (1.0f / 512.0f) + EPS);
;                 float o[8] = {bflo(ow[u].x), bfhi(ow[u].x), bflo(ow[u].y), bfhi(ow[u].y), bflo(ow[u].z), bfhi(ow[u].z), bflo(ow[u].w), bfhi(ow[u].w)};
;                 float r[8] = {bflo(rw[u].x), bfhi(rw[u].x), bflo(rw[u].y), bfhi(rw[u].y), bflo(rw[u].z), bfhi(rw[u].z), bflo(rw[u].w), bfhi(rw[u].w)};
; #pragma unroll
;                 for (int e = 0; e < 8; ++e) o[e] = o[e] * rs * gn[e] * (r[e] * sigmoidf_(r[e]));
;                 *(u32x4*)(OCAT + (size_t)row * OC + 1024 + h * 512 + lane * 8) = (u32x4){cvt_pk_bf16(o[0], o[1]), cvt_pk_bf16(o[2], o[3]), cvt_pk_bf16(o[4], o[5]), cvt_pk_bf16(o[6], o[7])}; } }
	v_add_f32_e32 v20, v40, v21
	ds_bpermute_b32 v21, v63, v20
	v_mul_f32_e32 v16, v2, v16
	v_mul_f32_e32 v32, v16, v17
	v_div_scale_f32 v25, s[0:1], v19, v19, 1.0
	s_waitcnt lgkmcnt(0)
	v_add_f32_e32 v16, v20, v21
	ds_bpermute_b32 v17, v64, v16
	v_rcp_f32_e32 v31, v25
	s_waitcnt lgkmcnt(0)
	v_add_f32_e32 v16, v16, v17
	ds_bpermute_b32 v17, v65, v16
	v_fma_f32 v20, -v25, v31, 1.0
	v_fmac_f32_e32 v31, v20, v31
	v_div_scale_f32 v20, vcc, 1.0, v19, 1.0
	v_mul_f32_e32 v21, v20, v31
	v_fma_f32 v33, -v25, v21, v20
	v_fmac_f32_e32 v21, v33, v31
	s_waitcnt lgkmcnt(0)
	v_add_f32_e32 v33, v16, v17
	ds_bpermute_b32 v34, v66, v33
	v_fma_f32 v20, -v25, v21, v20
	v_div_fmas_f32 v16, v20, v31, v21
	v_div_fixup_f32 v25, v16, v19, 1.0
	v_mul_f32_e32 v16, v24, v22
	v_mul_f32_e32 v17, v25, v23
	s_waitcnt lgkmcnt(0)
	v_add_f32_e32 v19, v33, v34
	ds_bpermute_b32 v20, v67, v19
	v_mul_f32_e32 v16, v3, v16
	v_mul_f32_e32 v21, v16, v17
	v_cvt_pk_bf16_f32 v16, v26, v28
	v_cvt_pk_bf16_f32 v17, v30, v18
	s_waitcnt lgkmcnt(0)
	v_add_f32_e32 v18, v19, v20
	v_fmamk_f32 v18, v18, 0x3b000000, v69
	v_mul_f32_e32 v19, 0x4b800000, v18
	v_cmp_gt_f32_e32 vcc, s18, v18
	v_and_b32_e32 v24, 0xffff0000, v10
	v_lshlrev_b32_e32 v22, 16, v9
	v_cndmask_b32_e32 v18, v18, v19, vcc
	v_rsq_f32_e32 v20, v18
	v_cvt_pk_bf16_f32 v18, v27, v29
	v_cvt_pk_bf16_f32 v19, v32, v21
	global_store_dwordx4 v[56:57], v[16:19], off offset:2048
	v_and_b32_e32 v21, 0xffff0000, v12
	v_and_b32_e32 v25, 0xffff0000, v14
	v_lshlrev_b32_e32 v19, 16, v12
	v_mul_f32_e32 v17, 0xbfb8aa3b, v19
	v_exp_f32_e32 v17, v17
	v_mul_f32_e32 v16, 0x45800000, v20
	v_cndmask_b32_e32 v16, v20, v16, vcc
	v_lshlrev_b32_e32 v18, 16, v8
	v_and_b32_e32 v20, 0xffff0000, v8
	v_lshlrev_b32_e32 v8, 16, v10
	v_add_f32_e32 v10, 1.0, v17
	v_div_scale_f32 v17, s[0:1], v10, v10, 1.0
	v_rcp_f32_e32 v28, v17
	v_and_b32_e32 v12, 0xffff0000, v9
	v_lshlrev_b32_e32 v9, 16, v14
	v_lshlrev_b32_e32 v26, 16, v11
	v_and_b32_e32 v14, 0xffff0000, v11
	v_fma_f32 v11, -v17, v28, 1.0
	v_fmac_f32_e32 v28, v11, v28
	v_div_scale_f32 v11, vcc, 1.0, v10, 1.0
	v_mul_f32_e32 v29, v11, v28
	v_fma_f32 v30, -v17, v29, v11
	v_fmac_f32_e32 v29, v30, v28
	v_fma_f32 v11, -v17, v29, v11
	v_mul_f32_e32 v17, 0xbfb8aa3b, v21
	v_exp_f32_e32 v30, v17
	v_div_fmas_f32 v11, v11, v28, v29
	v_div_fixup_f32 v17, v11, v10, 1.0
	v_mul_f32_e32 v10, v16, v18
	v_mul_f32_e32 v11, v17, v19
	v_add_f32_e32 v28, 1.0, v30
	v_div_scale_f32 v29, s[0:1], v28, v28, 1.0
	v_rcp_f32_e32 v30, v29
	v_mul_f32_e32 v4, v4, v10
	v_mul_f32_e32 v18, v4, v11
	v_lshlrev_b32_e32 v23, 16, v13
	v_fma_f32 v4, -v29, v30, 1.0
	v_fmac_f32_e32 v30, v4, v30
	v_div_scale_f32 v4, vcc, 1.0, v28, 1.0
	v_mul_f32_e32 v10, v4, v30
	v_fma_f32 v11, -v29, v10, v4
	v_fmac_f32_e32 v10, v11, v30
	v_mul_f32_e32 v11, 0xbfb8aa3b, v23
	v_exp_f32_e32 v11, v11
	v_fma_f32 v4, -v29, v10, v4
	v_div_fmas_f32 v4, v4, v30, v10
	v_div_fixup_f32 v17, v4, v28, 1.0
	v_add_f32_e32 v4, 1.0, v11
	v_div_scale_f32 v19, s[0:1], v4, v4, 1.0
	v_rcp_f32_e32 v28, v19
	v_mul_f32_e32 v10, v16, v20
	v_mul_f32_e32 v11, v17, v21
	v_and_b32_e32 v13, 0xffff0000, v13
	v_mul_f32_e32 v5, v5, v10
	v_mul_f32_e32 v10, v5, v11
	v_fma_f32 v5, -v19, v28, 1.0
	v_fmac_f32_e32 v28, v5, v28
	v_div_scale_f32 v5, vcc, 1.0, v4, 1.0
	v_mul_f32_e32 v11, v5, v28
	v_fma_f32 v17, -v19, v11, v5
	v_fmac_f32_e32 v11, v17, v28
	v_mul_f32_e32 v17, 0xbfb8aa3b, v13
	v_fma_f32 v5, -v19, v11, v5
	v_exp_f32_e32 v19, v17
	v_div_fmas_f32 v5, v5, v28, v11
	v_div_fixup_f32 v17, v5, v4, 1.0
	v_mul_f32_e32 v4, v16, v22
	v_mul_f32_e32 v5, v17, v23
	v_add_f32_e32 v11, 1.0, v19
	v_div_scale_f32 v19, s[0:1], v11, v11, 1.0
	v_rcp_f32_e32 v20, v19
	v_mul_f32_e32 v4, v6, v4
	v_mul_f32_e32 v6, v4, v5
	v_lshlrev_b32_e32 v27, 16, v15
	v_fma_f32 v4, -v19, v20, 1.0
	v_fmac_f32_e32 v20, v4, v20
	v_div_scale_f32 v4, vcc, 1.0, v11, 1.0
	v_mul_f32_e32 v5, v4, v20
	v_fma_f32 v17, -v19, v5, v4
	v_fmac_f32_e32 v5, v17, v20
	v_mul_f32_e32 v17, 0xbfb8aa3b, v9
	v_fma_f32 v4, -v19, v5, v4
	v_exp_f32_e32 v19, v17
	v_div_fmas_f32 v4, v4, v20, v5
	v_div_fixup_f32 v17, v4, v11, 1.0
	v_mul_f32_e32 v4, v16, v12
	v_mul_f32_e32 v5, v17, v13
	v_add_f32_e32 v11, 1.0, v19
	v_div_scale_f32 v19, s[0:1], v11, v11, 1.0
	v_rcp_f32_e32 v20, v19
	v_mul_f32_e32 v4, v7, v4
	v_mul_f32_e32 v7, v4, v5
	v_and_b32_e32 v15, 0xffff0000, v15
	v_fma_f32 v4, -v19, v20, 1.0
	v_fmac_f32_e32 v20, v4, v20
	v_div_scale_f32 v4, vcc, 1.0, v11, 1.0
	v_mul_f32_e32 v5, v4, v20
	v_fma_f32 v12, -v19, v5, v4
	v_fmac_f32_e32 v5, v12, v20
	v_mul_f32_e32 v12, 0xbfb8aa3b, v25
	v_exp_f32_e32 v12, v12
	v_fma_f32 v4, -v19, v5, v4
	v_div_fmas_f32 v4, v4, v20, v5
	v_div_fixup_f32 v17, v4, v11, 1.0
	v_add_f32_e32 v11, 1.0, v12
	v_div_scale_f32 v12, s[0:1], v11, v11, 1.0
	v_rcp_f32_e32 v13, v12
	v_mul_f32_e32 v4, v16, v8
	v_mul_f32_e32 v5, v17, v9
	s_nop 0
	v_mul_f32_e32 v0, v0, v4
	v_mul_f32_e32 v8, v0, v5
	v_fma_f32 v0, -v12, v13, 1.0
	v_fmac_f32_e32 v13, v0, v13
	v_div_scale_f32 v0, vcc, 1.0, v11, 1.0
	v_mul_f32_e32 v4, v0, v13
	v_fma_f32 v5, -v12, v4, v0
	v_fmac_f32_e32 v4, v5, v13
	v_mul_f32_e32 v5, 0xbfb8aa3b, v27
	v_exp_f32_e32 v5, v5
	v_fma_f32 v0, -v12, v4, v0
	v_div_fmas_f32 v0, v0, v13, v4
	v_div_fixup_f32 v17, v0, v11, 1.0
	v_add_f32_e32 v0, 1.0, v5
	v_div_scale_f32 v9, s[0:1], v0, v0, 1.0
	v_rcp_f32_e32 v11, v9
	v_mul_f32_e32 v4, v16, v24
	v_mul_f32_e32 v5, v17, v25
	s_nop 0
	v_mul_f32_e32 v1, v1, v4
	v_mul_f32_e32 v4, v1, v5
	v_fma_f32 v1, -v9, v11, 1.0
	v_fmac_f32_e32 v11, v1, v11
	v_div_scale_f32 v1, vcc, 1.0, v0, 1.0
	v_mul_f32_e32 v5, v1, v11
	v_fma_f32 v12, -v9, v5, v1
	v_fmac_f32_e32 v5, v12, v11
	v_fma_f32 v1, -v9, v5, v1
	v_mul_f32_e32 v9, 0xbfb8aa3b, v15
	v_exp_f32_e32 v9, v9
	v_div_fmas_f32 v1, v1, v11, v5
	v_div_fixup_f32 v17, v1, v0, 1.0
	v_mul_f32_e32 v0, v16, v26
	v_mul_f32_e32 v1, v17, v27
	v_add_f32_e32 v5, 1.0, v9
	v_div_scale_f32 v9, s[0:1], v5, v5, 1.0
	v_rcp_f32_e32 v11, v9
	v_mul_f32_e32 v0, v2, v0
	v_mul_f32_e32 v12, v0, v1
	v_fma_f32 v0, -v9, v11, 1.0
	v_fmac_f32_e32 v11, v0, v11
	v_div_scale_f32 v0, vcc, 1.0, v5, 1.0
	v_mul_f32_e32 v1, v0, v11
	v_fma_f32 v2, -v9, v1, v0
	v_fmac_f32_e32 v1, v2, v11
	v_fma_f32 v0, -v9, v1, v0
	v_div_fmas_f32 v0, v0, v11, v1
	v_div_fixup_f32 v17, v0, v5, 1.0
	v_mul_f32_e32 v0, v16, v14
	v_mul_f32_e32 v1, v17, v15
	s_nop 0
	v_mul_f32_e32 v0, v3, v0
	v_mul_f32_e32 v3, v0, v1
	v_cvt_pk_bf16_f32 v0, v18, v10
	v_cvt_pk_bf16_f32 v1, v6, v7
	v_cvt_pk_bf16_f32 v2, v8, v4
	v_cvt_pk_bf16_f32 v3, v12, v3
	global_store_dwordx4 v[54:55], v[0:3], off offset:2048
	s_nop 1
	v_add_u32_e32 v0, s88, v70
	v_cmp_lt_i32_e32 vcc, s19, v0
	s_or_b64 s[10:11], vcc, s[10:11]
	s_andn2_b64 exec, exec, s[10:11]
	s_cbranch_execz .LBB0_592

; #define LBAR() asm volatile("s_waitcnt lgkmcnt(0)\n\ts_barrier" ::: "memory")
; #define SG_LOAD(k0) do { _Pragma("unroll") for (int i_ = 0; i_ < 4; ++i_) { const int id_ = tid + i_ * 512, rr_ = id_ >> 5, cc_ = id_ & 31; \
;         ra[i_] = *(const u32x4*)(Ag + (size_t)rr_ * lda + (k0) + cc_ * 8); rb[i_] = *(const u32x4*)(Bg + (size_t)rr_ * ldb + (k0) + cc_ * 8); } } while (0)
; template <class Epi>
; __device__ __forceinline__ void small_gemm_tile(unsigned char* lds, const bf16_t* A, int lda, const bf16_t* Bt, int ldb, int K, int kbreak, int rowbase, int tm, int tn, const Epi& E, int tid) {
;     ...
;     f32x4 cur[2], first[2];
; #pragma unroll
;     for (int n_ = 0; n_ < 2; ++n_) { cur[n_] = (f32x4){0.f, 0.f, 0.f, 0.f}; first[n_] = (f32x4){0.f, 0.f, 0.f, 0.f}; }
;     SG_LOAD(0);
;     for (int k0 = 0; k0 < K; k0 += 256) {
; #pragma unroll
;         for (int i = 0; i < 4; ++i) { const int id = tid + i * 512, rr = id >> 5, cc = id & 31; *(u32x4*)(AS + rr * 528 + cc * 16) = ra[i]; *(u32x4*)(BS + rr * 528 + cc * 16) = rb[i]; }
;         LBAR();
;         if (k0 + 256 < K) SG_LOAD(k0 + 256);
;         if (k0 == kbreak) {
; #pragma unroll
;             for (int n_ = 0; n_ < 2; ++n_) { first[n_] = cur[n_]; cur[n_] = (f32x4){0.f, 0.f, 0.f, 0.f}; } }
; #pragma unroll
;         for (int kk = 0; kk < 8; ++kk) { const bf16x8 af = *(const bf16x8*)(AS + (wm * 16 + r16) * 528 + kk * 64 + q4 * 16);
; #pragma unroll
;             for (int nt = 0; nt < 2; ++nt) { const bf16x8 bfg = *(const bf16x8*)(BS + (wn * 32 + nt * 16 + r16) * 528 + kk * 64 + q4 * 16); cur[nt] = __builtin_amdgcn_mfma_f32_16x16x32_bf16(bfg, af, cur[nt], 0, 0, 0); } }
;         LBAR();
.LBB0_764:
	s_and_b32 s0, s3, 0xffffffc0
	s_add_i32 s10, s0, 0x4000
	s_ashr_i32 s11, s10, 31
	s_and_b32 s20, s19, 31
	s_lshl_b64 s[0:1], s[10:11], 12
	v_lshl_add_u64 v[26:27], v[6:7], 0, s[0:1]
	s_lshl_b32 s8, s20, 18
	v_lshl_add_u64 v[28:29], v[8:9], 0, s[8:9]
	v_lshl_add_u64 v[20:21], v[26:27], 0, v[10:11]
	v_lshl_add_u64 v[18:19], v[26:27], 0, v[12:13]
	v_lshl_add_u64 v[30:31], v[26:27], 0, v[14:15]
	v_lshl_add_u64 v[26:27], v[26:27], 0, v[16:17]
	v_lshl_add_u64 v[24:25], v[28:29], 0, v[10:11]
	global_load_dwordx4 v[54:57], v[20:21], off
	global_load_dwordx4 v[58:61], v[24:25], off
	v_lshl_add_u64 v[22:23], v[28:29], 0, v[12:13]
	global_load_dwordx4 v[62:65], v[18:19], off
	global_load_dwordx4 v[66:69], v[22:23], off
	v_lshl_add_u64 v[32:33], v[28:29], 0, v[14:15]
	global_load_dwordx4 v[70:73], v[30:31], off
	global_load_dwordx4 v[74:77], v[32:33], off
	v_lshl_add_u64 v[28:29], v[28:29], 0, v[16:17]
	global_load_dwordx4 v[78:81], v[26:27], off
	global_load_dwordx4 v[82:85], v[28:29], off
	v_lshl_or_b32 v53, s20, 6, v44
	v_lshlrev_b32_e32 v4, 2, v53
	v_cmp_lt_i32_e64 s[0:1], v50, v51
	s_waitcnt vmcnt(0)
	ds_write_b128 v45, v[54:57]
	ds_write_b128 v45, v[58:61] offset:33792
	ds_write_b128 v46, v[62:65]
	ds_write_b128 v46, v[66:69] offset:33792
	ds_write_b128 v45, v[70:73] offset:16896
	ds_write_b128 v45, v[74:77] offset:50688
	ds_write_b128 v47, v[78:81]
	ds_write_b128 v47, v[82:85] offset:33792
	s_waitcnt lgkmcnt(0)
	s_barrier
	ds_read_b128 v[54:57], v41 offset:33792
	ds_read_b128 v[58:61], v48
	ds_read_b128 v[62:65], v48 offset:64
	ds_read_b128 v[66:69], v41 offset:33856
	s_waitcnt lgkmcnt(2)
	v_mfma_f32_16x16x32_bf16 v[54:57], v[54:57], v[58:61], 0
	ds_read_b128 v[70:73], v41 offset:42240
	ds_read_b128 v[74:77], v41 offset:42304
	s_waitcnt lgkmcnt(2)
	v_mfma_f32_16x16x32_bf16 v[54:57], v[66:69], v[62:65], v[54:57]
	ds_read_b128 v[66:69], v41 offset:33920
	s_waitcnt lgkmcnt(2)
	v_mfma_f32_16x16x32_bf16 v[58:61], v[70:73], v[58:61], 0
	s_waitcnt lgkmcnt(1)
	v_mfma_f32_16x16x32_bf16 v[58:61], v[74:77], v[62:65], v[58:61]
	ds_read_b128 v[62:65], v48 offset:128
	ds_read_b128 v[70:73], v48 offset:192
	ds_read_b128 v[74:77], v41 offset:33984
	s_waitcnt lgkmcnt(2)
	v_mfma_f32_16x16x32_bf16 v[54:57], v[66:69], v[62:65], v[54:57]
	ds_read_b128 v[66:69], v41 offset:42368
	ds_read_b128 v[78:81], v41 offset:42432
	s_waitcnt lgkmcnt(1)
	v_mfma_f32_16x16x32_bf16 v[58:61], v[66:69], v[62:65], v[58:61]
	ds_read_b128 v[62:65], v41 offset:34048
	v_mfma_f32_16x16x32_bf16 v[54:57], v[74:77], v[70:73], v[54:57]
	s_waitcnt lgkmcnt(1)
	v_mfma_f32_16x16x32_bf16 v[58:61], v[78:81], v[70:73], v[58:61]
	ds_read_b128 v[66:69], v48 offset:256
	ds_read_b128 v[70:73], v48 offset:320
	ds_read_b128 v[74:77], v41 offset:34112
	s_waitcnt lgkmcnt(2)
	v_mfma_f32_16x16x32_bf16 v[54:57], v[62:65], v[66:69], v[54:57]
	ds_read_b128 v[62:65], v41 offset:42496
	ds_read_b128 v[78:81], v41 offset:42560
	s_waitcnt lgkmcnt(1)
	v_mfma_f32_16x16x32_bf16 v[58:61], v[62:65], v[66:69], v[58:61]
	ds_read_b128 v[62:65], v41 offset:34176
	v_mfma_f32_16x16x32_bf16 v[54:57], v[74:77], v[70:73], v[54:57]
	global_load_dwordx4 v[66:69], v[30:31], off offset:512
	global_load_dwordx4 v[74:77], v[32:33], off offset:512
	ds_read_b128 v[82:85], v48 offset:384
	ds_read_b128 v[86:89], v41 offset:42624
	s_waitcnt lgkmcnt(3)
	v_mfma_f32_16x16x32_bf16 v[58:61], v[78:81], v[70:73], v[58:61]
	global_load_dwordx4 v[70:73], v[20:21], off offset:512
	global_load_dwordx4 v[78:81], v[24:25], off offset:512
	ds_read_b128 v[90:93], v48 offset:448
	ds_read_b128 v[94:97], v41 offset:34240
	s_waitcnt lgkmcnt(3)
	v_mfma_f32_16x16x32_bf16 v[54:57], v[62:65], v[82:85], v[54:57]
	global_load_dwordx4 v[62:65], v[18:19], off offset:512
	global_load_dwordx4 v[98:101], v[22:23], off offset:512
	ds_read_b128 v[102:105], v41 offset:42688
	s_waitcnt lgkmcnt(3)
	v_mfma_f32_16x16x32_bf16 v[58:61], v[86:89], v[82:85], v[58:61]
	global_load_dwordx4 v[82:85], v[26:27], off offset:512
	global_load_dwordx4 v[86:89], v[28:29], off offset:512
	s_waitcnt lgkmcnt(0)
	s_barrier
	s_waitcnt vmcnt(5)
	ds_write_b128 v45, v[70:73]
	s_waitcnt vmcnt(4)
	ds_write_b128 v45, v[78:81] offset:33792
	s_waitcnt vmcnt(3)
	ds_write_b128 v46, v[62:65]
	s_waitcnt vmcnt(2)
	ds_write_b128 v46, v[98:101] offset:33792
	ds_write_b128 v45, v[66:69] offset:16896
	ds_write_b128 v45, v[74:77] offset:50688
	s_waitcnt vmcnt(1)
	ds_write_b128 v47, v[82:85]
	s_waitcnt vmcnt(0)
	ds_write_b128 v47, v[86:89] offset:33792
	s_waitcnt lgkmcnt(0)
	s_barrier
; #define LBAR() asm volatile("s_waitcnt lgkmcnt(0)\n\ts_barrier" ::: "memory")
; #define SG_LOAD(k0) do { _Pragma("unroll") for (int i_ = 0; i_ < 4; ++i_) { const int id_ = tid + i_ * 512, rr_ = id_ >> 5, cc_ = id_ & 31; \
;         ra[i_] = *(const u32x4*)(Ag + (size_t)rr_ * lda + (k0) + cc_ * 8); rb[i_] = *(const u32x4*)(Bg + (size_t)rr_ * ldb + (k0) + cc_ * 8); } } while (0)
; template <class Epi>
; __device__ __forceinline__ void small_gemm_tile(unsigned char* lds, const bf16_t* A, int lda, const bf16_t* Bt, int ldb, int K, int kbreak, int rowbase, int tm, int tn, const Epi& E, int tid) {
;     ...
;     for (int k0 = 0; k0 < K; k0 += 256) {
; #pragma unroll
;         for (int i = 0; i < 4; ++i) { const int id = tid + i * 512, rr = id >> 5, cc = id & 31; *(u32x4*)(AS + rr * 528 + cc * 16) = ra[i]; *(u32x4*)(BS + rr * 528 + cc * 16) = rb[i]; }
;         LBAR();
;         if (k0 + 256 < K) SG_LOAD(k0 + 256);
;         if (k0 == kbreak) {
; #pragma unroll
;             for (int n_ = 0; n_ < 2; ++n_) { first[n_] = cur[n_]; cur[n_] = (f32x4){0.f, 0.f, 0.f, 0.f}; } }
; #pragma unroll
;         for (int kk = 0; kk < 8; ++kk) { const bf16x8 af = *(const bf16x8*)(AS + (wm * 16 + r16) * 528 + kk * 64 + q4 * 16);
; #pragma unroll
;             for (int nt = 0; nt < 2; ++nt) { const bf16x8 bfg = *(const bf16x8*)(BS + (wn * 32 + nt * 16 + r16) * 528 + kk * 64 + q4 * 16); cur[nt] = __builtin_amdgcn_mfma_f32_16x16x32_bf16(bfg, af, cur[nt], 0, 0, 0); } }
;         LBAR();
	ds_read_b128 v[62:65], v41 offset:33792
	s_waitcnt lgkmcnt(10)
	v_mfma_f32_16x16x32_bf16 v[54:57], v[94:97], v[90:93], v[54:57]
	ds_read_b128 v[66:69], v48
	ds_read_b128 v[70:73], v48 offset:64
	ds_read_b128 v[74:77], v41 offset:33856
	s_waitcnt lgkmcnt(12)
	v_mfma_f32_16x16x32_bf16 v[58:61], v[102:105], v[90:93], v[58:61]
	s_waitcnt lgkmcnt(2)
	v_mfma_f32_16x16x32_bf16 v[54:57], v[62:65], v[66:69], v[54:57]
	ds_read_b128 v[62:65], v41 offset:42240
	ds_read_b128 v[78:81], v41 offset:42304
	s_waitcnt lgkmcnt(1)
	v_mfma_f32_16x16x32_bf16 v[58:61], v[62:65], v[66:69], v[58:61]
	ds_read_b128 v[62:65], v41 offset:33920
	v_mfma_f32_16x16x32_bf16 v[54:57], v[74:77], v[70:73], v[54:57]
	s_waitcnt lgkmcnt(1)
	v_mfma_f32_16x16x32_bf16 v[58:61], v[78:81], v[70:73], v[58:61]
	ds_read_b128 v[66:69], v48 offset:128
	ds_read_b128 v[70:73], v48 offset:192
	ds_read_b128 v[74:77], v41 offset:33984
	s_waitcnt lgkmcnt(2)
	v_mfma_f32_16x16x32_bf16 v[54:57], v[62:65], v[66:69], v[54:57]
	ds_read_b128 v[62:65], v41 offset:42368
	ds_read_b128 v[78:81], v41 offset:42432
	s_waitcnt lgkmcnt(1)
	v_mfma_f32_16x16x32_bf16 v[58:61], v[62:65], v[66:69], v[58:61]
	ds_read_b128 v[62:65], v41 offset:34048
	v_mfma_f32_16x16x32_bf16 v[54:57], v[74:77], v[70:73], v[54:57]
	s_waitcnt lgkmcnt(1)
	v_mfma_f32_16x16x32_bf16 v[58:61], v[78:81], v[70:73], v[58:61]
	ds_read_b128 v[66:69], v48 offset:256
	ds_read_b128 v[70:73], v48 offset:320
	ds_read_b128 v[74:77], v41 offset:34112
	s_waitcnt lgkmcnt(2)
	v_mfma_f32_16x16x32_bf16 v[54:57], v[62:65], v[66:69], v[54:57]
	ds_read_b128 v[62:65], v41 offset:42496
	ds_read_b128 v[78:81], v41 offset:42560
	s_waitcnt lgkmcnt(1)
	v_mfma_f32_16x16x32_bf16 v[58:61], v[62:65], v[66:69], v[58:61]
	ds_read_b128 v[62:65], v41 offset:34176
	v_mfma_f32_16x16x32_bf16 v[54:57], v[74:77], v[70:73], v[54:57]
	global_load_dwordx4 v[66:69], v[30:31], off offset:1024
	global_load_dwordx4 v[74:77], v[32:33], off offset:1024
	ds_read_b128 v[82:85], v48 offset:384
	ds_read_b128 v[86:89], v41 offset:42624
	s_waitcnt lgkmcnt(3)
	v_mfma_f32_16x16x32_bf16 v[58:61], v[78:81], v[70:73], v[58:61]
	global_load_dwordx4 v[70:73], v[20:21], off offset:1024
	global_load_dwordx4 v[78:81], v[24:25], off offset:1024
	ds_read_b128 v[90:93], v48 offset:448
	ds_read_b128 v[94:97], v41 offset:34240
	s_waitcnt lgkmcnt(3)
	v_mfma_f32_16x16x32_bf16 v[54:57], v[62:65], v[82:85], v[54:57]
	global_load_dwordx4 v[62:65], v[18:19], off offset:1024
	global_load_dwordx4 v[98:101], v[22:23], off offset:1024
	ds_read_b128 v[102:105], v41 offset:42688
	s_waitcnt lgkmcnt(3)
	v_mfma_f32_16x16x32_bf16 v[58:61], v[86:89], v[82:85], v[58:61]
	global_load_dwordx4 v[82:85], v[26:27], off offset:1024
	global_load_dwordx4 v[86:89], v[28:29], off offset:1024
	s_waitcnt lgkmcnt(0)
	s_barrier
	s_waitcnt vmcnt(5)
	ds_write_b128 v45, v[70:73]
	s_waitcnt vmcnt(4)
	ds_write_b128 v45, v[78:81] offset:33792
	s_waitcnt vmcnt(3)
	ds_write_b128 v46, v[62:65]
	s_waitcnt vmcnt(2)
	ds_write_b128 v46, v[98:101] offset:33792
	ds_write_b128 v45, v[66:69] offset:16896
	ds_write_b128 v45, v[74:77] offset:50688
	s_waitcnt vmcnt(1)
	ds_write_b128 v47, v[82:85]
	s_waitcnt vmcnt(0)
	ds_write_b128 v47, v[86:89] offset:33792
	s_waitcnt lgkmcnt(0)
	s_barrier
	ds_read_b128 v[62:65], v41 offset:33792
	s_waitcnt lgkmcnt(10)
	v_mfma_f32_16x16x32_bf16 v[54:57], v[94:97], v[90:93], v[54:57]
	ds_read_b128 v[66:69], v48
	ds_read_b128 v[70:73], v48 offset:64
	ds_read_b128 v[74:77], v41 offset:33856
	s_waitcnt lgkmcnt(12)
	v_mfma_f32_16x16x32_bf16 v[58:61], v[102:105], v[90:93], v[58:61]
	s_waitcnt lgkmcnt(2)
	v_mfma_f32_16x16x32_bf16 v[54:57], v[62:65], v[66:69], v[54:57]
	ds_read_b128 v[62:65], v41 offset:42240
	ds_read_b128 v[78:81], v41 offset:42304
	s_waitcnt lgkmcnt(1)
	v_mfma_f32_16x16x32_bf16 v[58:61], v[62:65], v[66:69], v[58:61]
	ds_read_b128 v[62:65], v41 offset:33920
	v_mfma_f32_16x16x32_bf16 v[54:57], v[74:77], v[70:73], v[54:57]
	s_waitcnt lgkmcnt(1)
	v_mfma_f32_16x16x32_bf16 v[58:61], v[78:81], v[70:73], v[58:61]
	ds_read_b128 v[66:69], v48 offset:128
	ds_read_b128 v[70:73], v48 offset:192
	ds_read_b128 v[74:77], v41 offset:33984
	s_waitcnt lgkmcnt(2)
	v_mfma_f32_16x16x32_bf16 v[54:57], v[62:65], v[66:69], v[54:57]
	ds_read_b128 v[62:65], v41 offset:42368
	ds_read_b128 v[78:81], v41 offset:42432
	s_waitcnt lgkmcnt(1)
	v_mfma_f32_16x16x32_bf16 v[58:61], v[62:65], v[66:69], v[58:61]
	ds_read_b128 v[62:65], v41 offset:34048
	v_mfma_f32_16x16x32_bf16 v[54:57], v[74:77], v[70:73], v[54:57]
	s_waitcnt lgkmcnt(1)
	v_mfma_f32_16x16x32_bf16 v[58:61], v[78:81], v[70:73], v[58:61]
	ds_read_b128 v[66:69], v48 offset:256
	ds_read_b128 v[70:73], v48 offset:320
	ds_read_b128 v[74:77], v41 offset:34112
	s_waitcnt lgkmcnt(2)
	v_mfma_f32_16x16x32_bf16 v[54:57], v[62:65], v[66:69], v[54:57]
	ds_read_b128 v[62:65], v41 offset:42496
	ds_read_b128 v[78:81], v41 offset:42560
	s_waitcnt lgkmcnt(1)
	v_mfma_f32_16x16x32_bf16 v[58:61], v[62:65], v[66:69], v[58:61]
	ds_read_b128 v[62:65], v41 offset:34176
	v_mfma_f32_16x16x32_bf16 v[54:57], v[74:77], v[70:73], v[54:57]
	global_load_dwordx4 v[66:69], v[30:31], off offset:1536
	global_load_dwordx4 v[74:77], v[32:33], off offset:1536
	ds_read_b128 v[82:85], v48 offset:384
	ds_read_b128 v[86:89], v41 offset:42624
	s_waitcnt lgkmcnt(3)
	v_mfma_f32_16x16x32_bf16 v[58:61], v[78:81], v[70:73], v[58:61]
	global_load_dwordx4 v[70:73], v[20:21], off offset:1536
	global_load_dwordx4 v[78:81], v[24:25], off offset:1536
	ds_read_b128 v[90:93], v48 offset:448
	ds_read_b128 v[94:97], v41 offset:34240
	s_waitcnt lgkmcnt(3)
	v_mfma_f32_16x16x32_bf16 v[54:57], v[62:65], v[82:85], v[54:57]
	global_load_dwordx4 v[62:65], v[18:19], off offset:1536
	global_load_dwordx4 v[98:101], v[22:23], off offset:1536
	ds_read_b128 v[102:105], v41 offset:42688
	s_waitcnt lgkmcnt(3)
	v_mfma_f32_16x16x32_bf16 v[58:61], v[86:89], v[82:85], v[58:61]
	global_load_dwordx4 v[82:85], v[26:27], off offset:1536
	global_load_dwordx4 v[86:89], v[28:29], off offset:1536
	s_waitcnt lgkmcnt(0)
	s_barrier
; #define LBAR() asm volatile("s_waitcnt lgkmcnt(0)\n\ts_barrier" ::: "memory")
; #define SG_LOAD(k0) do { _Pragma("unroll") for (int i_ = 0; i_ < 4; ++i_) { const int id_ = tid + i_ * 512, rr_ = id_ >> 5, cc_ = id_ & 31; \
;         ra[i_] = *(const u32x4*)(Ag + (size_t)rr_ * lda + (k0) + cc_ * 8); rb[i_] = *(const u32x4*)(Bg + (size_t)rr_ * ldb + (k0) + cc_ * 8); } } while (0)
; template <class Epi>
; __device__ __forceinline__ void small_gemm_tile(unsigned char* lds, const bf16_t* A, int lda, const bf16_t* Bt, int ldb, int K, int kbreak, int rowbase, int tm, int tn, const Epi& E, int tid) {
;     ...
;     for (int k0 = 0; k0 < K; k0 += 256) {
; #pragma unroll
;         for (int i = 0; i < 4; ++i) { const int id = tid + i * 512, rr = id >> 5, cc = id & 31; *(u32x4*)(AS + rr * 528 + cc * 16) = ra[i]; *(u32x4*)(BS + rr * 528 + cc * 16) = rb[i]; }
;         LBAR();
;         if (k0 + 256 < K) SG_LOAD(k0 + 256);
;         if (k0 == kbreak) {
; #pragma unroll
;             for (int n_ = 0; n_ < 2; ++n_) { first[n_] = cur[n_]; cur[n_] = (f32x4){0.f, 0.f, 0.f, 0.f}; } }
; #pragma unroll
;         for (int kk = 0; kk < 8; ++kk) { const bf16x8 af = *(const bf16x8*)(AS + (wm * 16 + r16) * 528 + kk * 64 + q4 * 16);
; #pragma unroll
;             for (int nt = 0; nt < 2; ++nt) { const bf16x8 bfg = *(const bf16x8*)(BS + (wn * 32 + nt * 16 + r16) * 528 + kk * 64 + q4 * 16); cur[nt] = __builtin_amdgcn_mfma_f32_16x16x32_bf16(bfg, af, cur[nt], 0, 0, 0); } }
;         LBAR();
	s_waitcnt vmcnt(5)
	ds_write_b128 v45, v[70:73]
	s_waitcnt vmcnt(4)
	ds_write_b128 v45, v[78:81] offset:33792
	s_waitcnt vmcnt(3)
	ds_write_b128 v46, v[62:65]
	s_waitcnt vmcnt(2)
	ds_write_b128 v46, v[98:101] offset:33792
	ds_write_b128 v45, v[66:69] offset:16896
	ds_write_b128 v45, v[74:77] offset:50688
	s_waitcnt vmcnt(1)
	ds_write_b128 v47, v[82:85]
	s_waitcnt vmcnt(0)
	ds_write_b128 v47, v[86:89] offset:33792
	s_waitcnt lgkmcnt(0)
	s_barrier
	ds_read_b128 v[62:65], v41 offset:33792
	s_waitcnt lgkmcnt(10)
	v_mfma_f32_16x16x32_bf16 v[54:57], v[94:97], v[90:93], v[54:57]
	ds_read_b128 v[66:69], v48
	ds_read_b128 v[70:73], v48 offset:64
	ds_read_b128 v[74:77], v41 offset:33856
	s_waitcnt lgkmcnt(12)
	v_mfma_f32_16x16x32_bf16 v[58:61], v[102:105], v[90:93], v[58:61]
	s_waitcnt lgkmcnt(2)
	v_mfma_f32_16x16x32_bf16 v[54:57], v[62:65], v[66:69], v[54:57]
	ds_read_b128 v[62:65], v41 offset:42240
	ds_read_b128 v[78:81], v41 offset:42304
	s_waitcnt lgkmcnt(1)
	v_mfma_f32_16x16x32_bf16 v[58:61], v[62:65], v[66:69], v[58:61]
	ds_read_b128 v[62:65], v41 offset:33920
	v_mfma_f32_16x16x32_bf16 v[54:57], v[74:77], v[70:73], v[54:57]
	s_waitcnt lgkmcnt(1)
	v_mfma_f32_16x16x32_bf16 v[58:61], v[78:81], v[70:73], v[58:61]
	ds_read_b128 v[66:69], v48 offset:128
	ds_read_b128 v[70:73], v48 offset:192
	ds_read_b128 v[74:77], v41 offset:33984
	s_waitcnt lgkmcnt(2)
	v_mfma_f32_16x16x32_bf16 v[54:57], v[62:65], v[66:69], v[54:57]
	ds_read_b128 v[62:65], v41 offset:42368
	ds_read_b128 v[78:81], v41 offset:42432
	s_waitcnt lgkmcnt(1)
	v_mfma_f32_16x16x32_bf16 v[58:61], v[62:65], v[66:69], v[58:61]
	ds_read_b128 v[62:65], v41 offset:34048
	v_mfma_f32_16x16x32_bf16 v[54:57], v[74:77], v[70:73], v[54:57]
	s_waitcnt lgkmcnt(1)
	v_mfma_f32_16x16x32_bf16 v[58:61], v[78:81], v[70:73], v[58:61]
	ds_read_b128 v[66:69], v48 offset:256
	ds_read_b128 v[70:73], v48 offset:320
	ds_read_b128 v[74:77], v41 offset:34112
	s_waitcnt lgkmcnt(2)
	v_mfma_f32_16x16x32_bf16 v[54:57], v[62:65], v[66:69], v[54:57]
	ds_read_b128 v[62:65], v41 offset:42496
	ds_read_b128 v[78:81], v41 offset:42560
	s_waitcnt lgkmcnt(1)
	v_mfma_f32_16x16x32_bf16 v[58:61], v[62:65], v[66:69], v[58:61]
	ds_read_b128 v[62:65], v41 offset:34176
	v_mfma_f32_16x16x32_bf16 v[54:57], v[74:77], v[70:73], v[54:57]
	global_load_dwordx4 v[66:69], v[30:31], off offset:2048
	global_load_dwordx4 v[74:77], v[32:33], off offset:2048
	ds_read_b128 v[82:85], v48 offset:384
	ds_read_b128 v[86:89], v41 offset:42624
	s_waitcnt lgkmcnt(3)
	v_mfma_f32_16x16x32_bf16 v[58:61], v[78:81], v[70:73], v[58:61]
	global_load_dwordx4 v[70:73], v[20:21], off offset:2048
	global_load_dwordx4 v[78:81], v[24:25], off offset:2048
	ds_read_b128 v[90:93], v48 offset:448
	ds_read_b128 v[94:97], v41 offset:34240
	s_waitcnt lgkmcnt(3)
	v_mfma_f32_16x16x32_bf16 v[54:57], v[62:65], v[82:85], v[54:57]
	global_load_dwordx4 v[62:65], v[18:19], off offset:2048
	global_load_dwordx4 v[98:101], v[22:23], off offset:2048
	ds_read_b128 v[102:105], v41 offset:42688
	s_waitcnt lgkmcnt(3)
	v_mfma_f32_16x16x32_bf16 v[58:61], v[86:89], v[82:85], v[58:61]
	global_load_dwordx4 v[82:85], v[26:27], off offset:2048
	global_load_dwordx4 v[86:89], v[28:29], off offset:2048
	s_waitcnt lgkmcnt(0)
	s_barrier
	s_waitcnt vmcnt(5)
	ds_write_b128 v45, v[70:73]
	s_waitcnt vmcnt(4)
	ds_write_b128 v45, v[78:81] offset:33792
	s_waitcnt vmcnt(3)
	ds_write_b128 v46, v[62:65]
	s_waitcnt vmcnt(2)
	ds_write_b128 v46, v[98:101] offset:33792
	ds_write_b128 v45, v[66:69] offset:16896
	ds_write_b128 v45, v[74:77] offset:50688
	s_waitcnt vmcnt(1)
	ds_write_b128 v47, v[82:85]
	s_waitcnt vmcnt(0)
	ds_write_b128 v47, v[86:89] offset:33792
	s_waitcnt lgkmcnt(0)
	s_barrier
	ds_read_b128 v[62:65], v41 offset:33792
	s_waitcnt lgkmcnt(10)
	v_mfma_f32_16x16x32_bf16 v[54:57], v[94:97], v[90:93], v[54:57]
	ds_read_b128 v[66:69], v48
	ds_read_b128 v[70:73], v48 offset:64
	ds_read_b128 v[74:77], v41 offset:33856
	s_waitcnt lgkmcnt(12)
	v_mfma_f32_16x16x32_bf16 v[58:61], v[102:105], v[90:93], v[58:61]
	s_waitcnt lgkmcnt(2)
	v_mfma_f32_16x16x32_bf16 v[54:57], v[62:65], v[66:69], v[54:57]
	ds_read_b128 v[62:65], v41 offset:42240
	ds_read_b128 v[78:81], v41 offset:42304
	s_waitcnt lgkmcnt(1)
	v_mfma_f32_16x16x32_bf16 v[58:61], v[62:65], v[66:69], v[58:61]
	ds_read_b128 v[62:65], v41 offset:33920
	v_mfma_f32_16x16x32_bf16 v[54:57], v[74:77], v[70:73], v[54:57]
	s_waitcnt lgkmcnt(1)
	v_mfma_f32_16x16x32_bf16 v[58:61], v[78:81], v[70:73], v[58:61]
	ds_read_b128 v[66:69], v48 offset:128
	ds_read_b128 v[70:73], v48 offset:192
	ds_read_b128 v[74:77], v41 offset:33984
	s_waitcnt lgkmcnt(2)
	v_mfma_f32_16x16x32_bf16 v[54:57], v[62:65], v[66:69], v[54:57]
	ds_read_b128 v[62:65], v41 offset:42368
	ds_read_b128 v[78:81], v41 offset:42432
	s_waitcnt lgkmcnt(1)
	v_mfma_f32_16x16x32_bf16 v[58:61], v[62:65], v[66:69], v[58:61]
	ds_read_b128 v[62:65], v41 offset:34048
	v_mfma_f32_16x16x32_bf16 v[54:57], v[74:77], v[70:73], v[54:57]
	s_waitcnt lgkmcnt(1)
	v_mfma_f32_16x16x32_bf16 v[58:61], v[78:81], v[70:73], v[58:61]
	ds_read_b128 v[66:69], v48 offset:256
	ds_read_b128 v[70:73], v48 offset:320
	ds_read_b128 v[74:77], v41 offset:34112
	s_waitcnt lgkmcnt(2)
	v_mfma_f32_16x16x32_bf16 v[54:57], v[62:65], v[66:69], v[54:57]
	ds_read_b128 v[62:65], v41 offset:42496
	ds_read_b128 v[78:81], v41 offset:42560
	s_waitcnt lgkmcnt(1)
	v_mfma_f32_16x16x32_bf16 v[58:61], v[62:65], v[66:69], v[58:61]
	ds_read_b128 v[62:65], v41 offset:34176
	v_mfma_f32_16x16x32_bf16 v[54:57], v[74:77], v[70:73], v[54:57]
	global_load_dwordx4 v[66:69], v[30:31], off offset:2560
	global_load_dwordx4 v[74:77], v[32:33], off offset:2560
	ds_read_b128 v[82:85], v48 offset:384
	ds_read_b128 v[86:89], v41 offset:42624
	s_waitcnt lgkmcnt(3)
	v_mfma_f32_16x16x32_bf16 v[58:61], v[78:81], v[70:73], v[58:61]
	global_load_dwordx4 v[70:73], v[20:21], off offset:2560
	global_load_dwordx4 v[78:81], v[24:25], off offset:2560
	ds_read_b128 v[90:93], v48 offset:448
	ds_read_b128 v[94:97], v41 offset:34240
	s_waitcnt lgkmcnt(3)
	v_mfma_f32_16x16x32_bf16 v[54:57], v[62:65], v[82:85], v[54:57]
	global_load_dwordx4 v[62:65], v[18:19], off offset:2560
	global_load_dwordx4 v[98:101], v[22:23], off offset:2560
	ds_read_b128 v[102:105], v41 offset:42688
	s_waitcnt lgkmcnt(3)
	v_mfma_f32_16x16x32_bf16 v[58:61], v[86:89], v[82:85], v[58:61]
	global_load_dwordx4 v[82:85], v[26:27], off offset:2560
	global_load_dwordx4 v[86:89], v[28:29], off offset:2560
	s_waitcnt lgkmcnt(0)
	s_barrier
; #define LBAR() asm volatile("s_waitcnt lgkmcnt(0)\n\ts_barrier" ::: "memory")
; #define SG_LOAD(k0) do { _Pragma("unroll") for (int i_ = 0; i_ < 4; ++i_) { const int id_ = tid + i_ * 512, rr_ = id_ >> 5, cc_ = id_ & 31; \
;         ra[i_] = *(const u32x4*)(Ag + (size_t)rr_ * lda + (k0) + cc_ * 8); rb[i_] = *(const u32x4*)(Bg + (size_t)rr_ * ldb + (k0) + cc_ * 8); } } while (0)
; template <class Epi>
; __device__ __forceinline__ void small_gemm_tile(unsigned char* lds, const bf16_t* A, int lda, const bf16_t* Bt, int ldb, int K, int kbreak, int rowbase, int tm, int tn, const Epi& E, int tid) {
;     ...
;     for (int k0 = 0; k0 < K; k0 += 256) {
; #pragma unroll
;         for (int i = 0; i < 4; ++i) { const int id = tid + i * 512, rr = id >> 5, cc = id & 31; *(u32x4*)(AS + rr * 528 + cc * 16) = ra[i]; *(u32x4*)(BS + rr * 528 + cc * 16) = rb[i]; }
;         LBAR();
;         if (k0 + 256 < K) SG_LOAD(k0 + 256);
;         if (k0 == kbreak) {
; #pragma unroll
;             for (int n_ = 0; n_ < 2; ++n_) { first[n_] = cur[n_]; cur[n_] = (f32x4){0.f, 0.f, 0.f, 0.f}; } }
; #pragma unroll
;         for (int kk = 0; kk < 8; ++kk) { const bf16x8 af = *(const bf16x8*)(AS + (wm * 16 + r16) * 528 + kk * 64 + q4 * 16);
; #pragma unroll
;             for (int nt = 0; nt < 2; ++nt) { const bf16x8 bfg = *(const bf16x8*)(BS + (wn * 32 + nt * 16 + r16) * 528 + kk * 64 + q4 * 16); cur[nt] = __builtin_amdgcn_mfma_f32_16x16x32_bf16(bfg, af, cur[nt], 0, 0, 0); } }
;         LBAR();
	s_waitcnt vmcnt(5)
	ds_write_b128 v45, v[70:73]
	s_waitcnt vmcnt(4)
	ds_write_b128 v45, v[78:81] offset:33792
	s_waitcnt vmcnt(3)
	ds_write_b128 v46, v[62:65]
	s_waitcnt vmcnt(2)
	ds_write_b128 v46, v[98:101] offset:33792
	ds_write_b128 v45, v[66:69] offset:16896
	ds_write_b128 v45, v[74:77] offset:50688
	s_waitcnt vmcnt(1)
	ds_write_b128 v47, v[82:85]
	s_waitcnt vmcnt(0)
	ds_write_b128 v47, v[86:89] offset:33792
	s_waitcnt lgkmcnt(0)
	s_barrier
	ds_read_b128 v[62:65], v41 offset:33792
	s_waitcnt lgkmcnt(10)
	v_mfma_f32_16x16x32_bf16 v[54:57], v[94:97], v[90:93], v[54:57]
	ds_read_b128 v[66:69], v48
	ds_read_b128 v[70:73], v48 offset:64
	ds_read_b128 v[74:77], v41 offset:33856
	s_waitcnt lgkmcnt(12)
	v_mfma_f32_16x16x32_bf16 v[58:61], v[102:105], v[90:93], v[58:61]
	s_waitcnt lgkmcnt(2)
	v_mfma_f32_16x16x32_bf16 v[54:57], v[62:65], v[66:69], v[54:57]
	ds_read_b128 v[62:65], v41 offset:42240
	ds_read_b128 v[78:81], v41 offset:42304
	s_waitcnt lgkmcnt(1)
	v_mfma_f32_16x16x32_bf16 v[58:61], v[62:65], v[66:69], v[58:61]
	ds_read_b128 v[62:65], v41 offset:33920
	v_mfma_f32_16x16x32_bf16 v[54:57], v[74:77], v[70:73], v[54:57]
	s_waitcnt lgkmcnt(1)
	v_mfma_f32_16x16x32_bf16 v[58:61], v[78:81], v[70:73], v[58:61]
	ds_read_b128 v[66:69], v48 offset:128
	ds_read_b128 v[70:73], v48 offset:192
	ds_read_b128 v[74:77], v41 offset:33984
	s_waitcnt lgkmcnt(2)
	v_mfma_f32_16x16x32_bf16 v[54:57], v[62:65], v[66:69], v[54:57]
	ds_read_b128 v[62:65], v41 offset:42368
	ds_read_b128 v[78:81], v41 offset:42432
	s_waitcnt lgkmcnt(1)
	v_mfma_f32_16x16x32_bf16 v[58:61], v[62:65], v[66:69], v[58:61]
	ds_read_b128 v[62:65], v41 offset:34048
	v_mfma_f32_16x16x32_bf16 v[54:57], v[74:77], v[70:73], v[54:57]
	s_waitcnt lgkmcnt(1)
	v_mfma_f32_16x16x32_bf16 v[58:61], v[78:81], v[70:73], v[58:61]
	ds_read_b128 v[66:69], v48 offset:256
	ds_read_b128 v[70:73], v48 offset:320
	ds_read_b128 v[74:77], v41 offset:34112
	s_waitcnt lgkmcnt(2)
	v_mfma_f32_16x16x32_bf16 v[54:57], v[62:65], v[66:69], v[54:57]
	ds_read_b128 v[62:65], v41 offset:42496
	ds_read_b128 v[78:81], v41 offset:42560
	s_waitcnt lgkmcnt(1)
	v_mfma_f32_16x16x32_bf16 v[58:61], v[62:65], v[66:69], v[58:61]
	ds_read_b128 v[62:65], v41 offset:34176
	v_mfma_f32_16x16x32_bf16 v[54:57], v[74:77], v[70:73], v[54:57]
	global_load_dwordx4 v[66:69], v[30:31], off offset:3072
	global_load_dwordx4 v[74:77], v[32:33], off offset:3072
	ds_read_b128 v[82:85], v48 offset:384
	ds_read_b128 v[86:89], v41 offset:42624
	s_waitcnt lgkmcnt(3)
	v_mfma_f32_16x16x32_bf16 v[58:61], v[78:81], v[70:73], v[58:61]
	global_load_dwordx4 v[70:73], v[20:21], off offset:3072
	global_load_dwordx4 v[78:81], v[24:25], off offset:3072
	ds_read_b128 v[90:93], v48 offset:448
	ds_read_b128 v[94:97], v41 offset:34240
	s_waitcnt lgkmcnt(3)
	v_mfma_f32_16x16x32_bf16 v[54:57], v[62:65], v[82:85], v[54:57]
	global_load_dwordx4 v[62:65], v[18:19], off offset:3072
	global_load_dwordx4 v[98:101], v[22:23], off offset:3072
	ds_read_b128 v[102:105], v41 offset:42688
	s_waitcnt lgkmcnt(3)
	v_mfma_f32_16x16x32_bf16 v[58:61], v[86:89], v[82:85], v[58:61]
	global_load_dwordx4 v[82:85], v[26:27], off offset:3072
	global_load_dwordx4 v[86:89], v[28:29], off offset:3072
	s_waitcnt lgkmcnt(0)
	s_barrier
	s_waitcnt vmcnt(5)
	ds_write_b128 v45, v[70:73]
	s_waitcnt vmcnt(4)
	ds_write_b128 v45, v[78:81] offset:33792
	s_waitcnt vmcnt(3)
	ds_write_b128 v46, v[62:65]
	s_waitcnt vmcnt(2)
	ds_write_b128 v46, v[98:101] offset:33792
	ds_write_b128 v45, v[66:69] offset:16896
	ds_write_b128 v45, v[74:77] offset:50688
	s_waitcnt vmcnt(1)
	ds_write_b128 v47, v[82:85]
	s_waitcnt vmcnt(0)
	ds_write_b128 v47, v[86:89] offset:33792
	s_waitcnt lgkmcnt(0)
	s_barrier
	ds_read_b128 v[62:65], v41 offset:33792
	s_waitcnt lgkmcnt(10)
	v_mfma_f32_16x16x32_bf16 v[54:57], v[94:97], v[90:93], v[54:57]
	ds_read_b128 v[66:69], v48
	ds_read_b128 v[70:73], v48 offset:64
	ds_read_b128 v[74:77], v41 offset:33856
	s_waitcnt lgkmcnt(12)
	v_mfma_f32_16x16x32_bf16 v[58:61], v[102:105], v[90:93], v[58:61]
	s_waitcnt lgkmcnt(2)
	v_mfma_f32_16x16x32_bf16 v[54:57], v[62:65], v[66:69], v[54:57]
	ds_read_b128 v[62:65], v41 offset:42240
	ds_read_b128 v[78:81], v41 offset:42304
	s_waitcnt lgkmcnt(1)
	v_mfma_f32_16x16x32_bf16 v[58:61], v[62:65], v[66:69], v[58:61]
	ds_read_b128 v[62:65], v41 offset:33920
	v_mfma_f32_16x16x32_bf16 v[54:57], v[74:77], v[70:73], v[54:57]
	s_waitcnt lgkmcnt(1)
	v_mfma_f32_16x16x32_bf16 v[58:61], v[78:81], v[70:73], v[58:61]
	ds_read_b128 v[66:69], v48 offset:128
	ds_read_b128 v[70:73], v48 offset:192
	ds_read_b128 v[74:77], v41 offset:33984
	s_waitcnt lgkmcnt(2)
	v_mfma_f32_16x16x32_bf16 v[54:57], v[62:65], v[66:69], v[54:57]
	ds_read_b128 v[62:65], v41 offset:42368
	ds_read_b128 v[78:81], v41 offset:42432
	s_waitcnt lgkmcnt(1)
	v_mfma_f32_16x16x32_bf16 v[58:61], v[62:65], v[66:69], v[58:61]
	ds_read_b128 v[62:65], v41 offset:34048
	v_mfma_f32_16x16x32_bf16 v[54:57], v[74:77], v[70:73], v[54:57]
	s_waitcnt lgkmcnt(1)
	v_mfma_f32_16x16x32_bf16 v[58:61], v[78:81], v[70:73], v[58:61]
	ds_read_b128 v[66:69], v48 offset:256
	ds_read_b128 v[70:73], v48 offset:320
	ds_read_b128 v[74:77], v41 offset:34112
	s_waitcnt lgkmcnt(2)
	v_mfma_f32_16x16x32_bf16 v[54:57], v[62:65], v[66:69], v[54:57]
	ds_read_b128 v[62:65], v41 offset:42496
	ds_read_b128 v[78:81], v41 offset:42560
	s_waitcnt lgkmcnt(1)
	v_mfma_f32_16x16x32_bf16 v[58:61], v[62:65], v[66:69], v[58:61]
	ds_read_b128 v[62:65], v41 offset:34176
	global_load_dwordx4 v[66:69], v[30:31], off offset:3584
	s_nop 0
	global_load_dwordx4 v[30:33], v[32:33], off offset:3584
	v_mfma_f32_16x16x32_bf16 v[54:57], v[74:77], v[70:73], v[54:57]
	ds_read_b128 v[74:77], v48 offset:384
	ds_read_b128 v[82:85], v41 offset:42624
	s_waitcnt lgkmcnt(3)
	v_mfma_f32_16x16x32_bf16 v[58:61], v[78:81], v[70:73], v[58:61]
	global_load_dwordx4 v[70:73], v[20:21], off offset:3584
	global_load_dwordx4 v[78:81], v[24:25], off offset:3584
	ds_read_b128 v[86:89], v48 offset:448
	ds_read_b128 v[90:93], v41 offset:34240
	global_load_dwordx4 v[18:21], v[18:19], off offset:3584
	s_nop 0
	global_load_dwordx4 v[22:25], v[22:23], off offset:3584
	s_waitcnt lgkmcnt(3)
	v_mfma_f32_16x16x32_bf16 v[54:57], v[62:65], v[74:77], v[54:57]
	ds_read_b128 v[62:65], v41 offset:42688
	s_waitcnt lgkmcnt(3)
	v_mfma_f32_16x16x32_bf16 v[58:61], v[82:85], v[74:77], v[58:61]
	global_load_dwordx4 v[74:77], v[26:27], off offset:3584
	s_nop 0
	global_load_dwordx4 v[26:29], v[28:29], off offset:3584
	s_waitcnt lgkmcnt(0)
	s_barrier
; __device__ __forceinline__ unsigned cvt_pk_bf16(float lo, float hi) { unsigned r; asm volatile("v_cvt_pk_bf16_f32 %0, %1, %2" : "=v"(r) : "v"(lo), "v"(hi)); return r; }
; __device__ __forceinline__ float bflo(unsigned w) { return __uint_as_float(w << 16); }
; __device__ __forceinline__ float bfhi(unsigned w) { return __uint_as_float(w & 0xffff0000u); }
; #define MFMA_SETTLE4(a, b, c, d) asm volatile("s_nop 15\n\ts_nop 15" : "+v"(a), "+v"(b), "+v"(c), "+v"(d))
; template <class Epi>
; __device__ __forceinline__ void small_gemm_tile(unsigned char* lds, const bf16_t* A, int lda, const bf16_t* Bt, int ldb, int K, int kbreak, int rowbase, int tm, int tn, const Epi& E, int tid) {
;     ...
;     MFMA_SETTLE4(cur[0], cur[1], first[0], first[1]);
;     const int row = rowbase + tm * 64 + wm * 16 + r16; float ssq = 0.f;
; #pragma unroll
;     for (int nt = 0; nt < 2; ++nt) ssq += E(cur[nt], first[nt], row, tn * 64 + wn * 32 + nt * 16 + q4 * 4);
;     if (Epi::SUMSQ) { ssq += __shfl_xor(ssq, 16); ssq += __shfl_xor(ssq, 32);
;         if (lane < 16) RED[wn * 64 + wm * 16 + r16] = ssq;
;         __syncthreads();
;         if (tid < 64) E.ss[(size_t)(rowbase + tm * 64 + tid) * 32 + tn] = RED[tid] + RED[64 + tid];
;     __device__ __forceinline__ float operator()(const f32x4& a0, const f32x4&, int row, int col) const {
;         f32x4 o;
;         if (MODE == 0) o = *(const f32x4*)(basef + (size_t)row * DM + col) + a0;
;         else { const u32x2 w = *(const u32x2*)(baseb + (size_t)row * DM + col); o = (f32x4){bflo(w.x) + a0[0], bfhi(w.x) + a0[1], bflo(w.y) + a0[2], bfhi(w.y) + a0[3]}; }
;         *(u32x2*)(ob + (size_t)row * DM + col) = (u32x2){cvt_pk_bf16(o[0], o[1]), cvt_pk_bf16(o[2], o[3])};
;         return (o[0] * o[0] + o[1] * o[1]) + (o[2] * o[2] + o[3] * o[3]); }
	s_waitcnt vmcnt(5)
	ds_write_b128 v45, v[70:73]
	s_waitcnt vmcnt(4)
	ds_write_b128 v45, v[78:81] offset:33792
	s_waitcnt vmcnt(3)
	ds_write_b128 v46, v[18:21]
	s_waitcnt vmcnt(2)
	ds_write_b128 v46, v[22:25] offset:33792
	ds_write_b128 v45, v[66:69] offset:16896
	ds_write_b128 v45, v[30:33] offset:50688
	s_waitcnt vmcnt(1)
	ds_write_b128 v47, v[74:77]
	s_waitcnt vmcnt(0)
	ds_write_b128 v47, v[26:29] offset:33792
	s_waitcnt lgkmcnt(0)
	s_barrier
	ds_read_b128 v[18:21], v41 offset:33792
	s_waitcnt lgkmcnt(10)
	v_mfma_f32_16x16x32_bf16 v[54:57], v[90:93], v[86:89], v[54:57]
	v_add_u32_e32 v74, s10, v40
	v_ashrrev_i32_e32 v75, 31, v74
	s_waitcnt lgkmcnt(9)
	v_mfma_f32_16x16x32_bf16 v[22:25], v[62:65], v[86:89], v[58:61]
	ds_read_b128 v[26:29], v48
	ds_read_b128 v[30:33], v48 offset:64
	s_nop 0
	ds_read_b128 v[58:61], v41 offset:33856
	s_waitcnt lgkmcnt(2)
	v_mfma_f32_16x16x32_bf16 v[18:21], v[18:21], v[26:29], v[54:57]
	s_nop 2
	ds_read_b128 v[54:57], v41 offset:42240
	ds_read_b128 v[62:65], v41 offset:42304
	s_waitcnt lgkmcnt(1)
	v_mfma_f32_16x16x32_bf16 v[22:25], v[54:57], v[26:29], v[22:25]
	ds_read_b128 v[26:29], v41 offset:33920
	v_mfma_f32_16x16x32_bf16 v[18:21], v[58:61], v[30:33], v[18:21]
	s_waitcnt lgkmcnt(1)
	v_mfma_f32_16x16x32_bf16 v[22:25], v[62:65], v[30:33], v[22:25]
	ds_read_b128 v[30:33], v48 offset:128
	ds_read_b128 v[54:57], v48 offset:192
	ds_read_b128 v[58:61], v41 offset:33984
	s_waitcnt lgkmcnt(2)
	v_mfma_f32_16x16x32_bf16 v[18:21], v[26:29], v[30:33], v[18:21]
	ds_read_b128 v[26:29], v41 offset:42368
	ds_read_b128 v[62:65], v41 offset:42432
	s_waitcnt lgkmcnt(1)
	v_mfma_f32_16x16x32_bf16 v[22:25], v[26:29], v[30:33], v[22:25]
	ds_read_b128 v[26:29], v41 offset:34048
	v_mfma_f32_16x16x32_bf16 v[18:21], v[58:61], v[54:57], v[18:21]
	s_waitcnt lgkmcnt(1)
	v_mfma_f32_16x16x32_bf16 v[22:25], v[62:65], v[54:57], v[22:25]
	ds_read_b128 v[30:33], v48 offset:256
	ds_read_b128 v[54:57], v48 offset:320
	ds_read_b128 v[58:61], v41 offset:34112
	s_waitcnt lgkmcnt(2)
	v_mfma_f32_16x16x32_bf16 v[18:21], v[26:29], v[30:33], v[18:21]
	ds_read_b128 v[26:29], v41 offset:42496
	ds_read_b128 v[62:65], v41 offset:42560
	s_waitcnt lgkmcnt(1)
	v_mfma_f32_16x16x32_bf16 v[22:25], v[26:29], v[30:33], v[22:25]
	ds_read_b128 v[26:29], v41 offset:34176
	v_mov_b64_e32 v[32:33], v[2:3]
	v_mov_b64_e32 v[30:31], v[0:1]
	v_mfma_f32_16x16x32_bf16 v[18:21], v[58:61], v[54:57], v[18:21]
	ds_read_b128 v[58:61], v48 offset:384
	ds_read_b128 v[66:69], v41 offset:42624
	s_waitcnt lgkmcnt(3)
	v_mfma_f32_16x16x32_bf16 v[22:25], v[62:65], v[54:57], v[22:25]
	ds_read_b128 v[62:65], v48 offset:448
	ds_read_b128 v[70:73], v41 offset:34240
	v_mov_b64_e32 v[56:57], v[2:3]
	v_mov_b64_e32 v[54:55], v[0:1]
	s_waitcnt lgkmcnt(3)
	v_mfma_f32_16x16x32_bf16 v[18:21], v[26:29], v[58:61], v[18:21]
	ds_read_b128 v[26:29], v41 offset:42688
	s_waitcnt lgkmcnt(0)
	s_barrier
	s_waitcnt lgkmcnt(3)
	v_mfma_f32_16x16x32_bf16 v[22:25], v[66:69], v[58:61], v[22:25]
	v_lshlrev_b64 v[58:59], 13, v[74:75]
	v_lshl_add_u64 v[58:59], s[6:7], 0, v[58:59]
	v_lshl_add_u64 v[58:59], v[58:59], 0, v[4:5]
	s_waitcnt lgkmcnt(1)
	v_mfma_f32_16x16x32_bf16 v[18:21], v[70:73], v[62:65], v[18:21]
	v_lshlrev_b32_e32 v4, 1, v53
	s_waitcnt lgkmcnt(0)
	v_mfma_f32_16x16x32_bf16 v[22:25], v[26:29], v[62:65], v[22:25]
	s_nop 15
	s_nop 15
	global_load_dwordx4 v[26:29], v[58:59], off
	v_lshlrev_b64 v[30:31], 12, v[74:75]
	v_lshl_add_u64 v[30:31], s[12:13], 0, v[30:31]
	v_lshl_add_u64 v[30:31], v[30:31], 0, v[4:5]
	v_cndmask_b32_e64 v4, v49, v50, s[0:1]
	v_lshlrev_b32_e32 v4, 2, v4
	v_cmp_lt_i32_e64 s[0:1], v52, v51
	s_waitcnt vmcnt(0)
	v_add_f32_e32 v28, v20, v28
	v_add_f32_e32 v29, v21, v29
	v_add_f32_e32 v26, v18, v26
	v_add_f32_e32 v27, v19, v27
	s_nop 0
	v_cvt_pk_bf16_f32 v18, v26, v27
	v_cvt_pk_bf16_f32 v19, v28, v29
	global_store_dwordx2 v[30:31], v[18:19], off
	global_load_dwordx4 v[18:21], v[58:59], off offset:64
	v_mul_f32_e32 v27, v27, v27
	v_mul_f32_e32 v29, v29, v29
	v_fmac_f32_e32 v27, v26, v26
	v_fmac_f32_e32 v29, v28, v28
	v_add_f32_e32 v26, v27, v29
	s_waitcnt vmcnt(0)
	v_add_f32_e32 v20, v24, v20
	v_add_f32_e32 v21, v25, v21
	v_add_f32_e32 v22, v22, v18
	v_add_f32_e32 v23, v23, v19
	v_mul_f32_e32 v19, v21, v21
	v_mul_f32_e32 v18, v23, v23
	v_fmac_f32_e32 v18, v22, v22
	v_fmac_f32_e32 v19, v20, v20
	v_add_f32_e32 v18, v18, v19
	v_add_f32_e32 v18, v26, v18
	ds_bpermute_b32 v4, v4, v18
	v_cndmask_b32_e64 v19, v49, v52, s[0:1]
	v_cvt_pk_bf16_f32 v22, v22, v23
	v_cvt_pk_bf16_f32 v23, v20, v21
	global_store_dwordx2 v[30:31], v[22:23], off offset:32
	s_waitcnt lgkmcnt(0)
	v_add_f32_e32 v4, v18, v4
	v_lshlrev_b32_e32 v18, 2, v19
	ds_bpermute_b32 v18, v18, v4
	s_and_saveexec_b64 s[0:1], vcc
	s_cbranch_execz .LBB0_766
	s_waitcnt lgkmcnt(0)
	v_add_f32_e32 v4, v4, v18
	ds_write_b32 v42, v4

; __device__ __forceinline__ unsigned cvt_pk_bf16(float lo, float hi) { unsigned r; asm volatile("v_cvt_pk_bf16_f32 %0, %1, %2" : "=v"(r) : "v"(lo), "v"(hi)); return r; }
;     __device__ __forceinline__ void operator()(const f32x4 (&acc)[2][2][4][2], const Unit& u, int wr, int wc, int fr, int fq) const {
;         const int row0 = u.pm * BM + wr * 64 + fr, col0 = u.pn * BM + wc * 32 + 8 * fq;
; #pragma unroll
;         for (int ai = 0; ai < 2; ++ai)
; #pragma unroll
;             for (int m = 0; m < 4; ++m) { const int row = row0 + ai * HALF + m * 16; const float rs = ACT == 1 ? ss[row] : 1.0f;
;                 bf16_t* rowp = O + (size_t)row * ldc + col0;
; #pragma unroll
;                 for (int bj = 0; bj < 2; ++bj) { f32x4 v0 = acc[ai][bj][m][0] * rs, v1 = acc[ai][bj][m][1] * rs;
;                     if (ACT == 1) {
; #pragma unroll
;                         for (int e = 0; e < 4; ++e) { const float a0 = fmaxf(v0[e], 0.f), a1 = fmaxf(v1[e], 0.f); v0[e] = a0 * a0; v1[e] = a1 * a1; } }
;                     u32x4 w; w.x = cvt_pk_bf16(v0[0], v0[1]); w.y = cvt_pk_bf16(v0[2], v0[3]); w.z = cvt_pk_bf16(v1[0], v1[1]); w.w = cvt_pk_bf16(v1[2], v1[3]);
;                     *(u32x4*)(rowp + bj * HALF) = w; } }
.LBB0_936:
	v_lshl_add_u32 v148, s0, 8, v152
	v_ashrrev_i32_e32 v149, 31, v148
	v_lshl_add_u64 v[146:147], v[148:149], 2, s[86:87]
	global_load_dword v158, v[146:147], off
	v_lshl_or_b32 v144, s1, 8, v154
	v_ashrrev_i32_e32 v145, 31, v144
	v_lshlrev_b64 v[160:161], 14, v[148:149]
	v_lshlrev_b64 v[150:151], 1, v[144:145]
	v_lshl_add_u64 v[144:145], s[74:75], 0, v[160:161]
	v_lshl_add_u64 v[144:145], v[144:145], 0, v[150:151]
	s_waitcnt vmcnt(0)
	v_mul_f32_e32 v126, v126, v158
	v_mul_f32_e32 v127, v127, v158
	v_mul_f32_e32 v124, v124, v158
	v_mul_f32_e32 v125, v125, v158
	v_mul_f32_e32 v122, v122, v158
	v_mul_f32_e32 v123, v123, v158
	v_mul_f32_e32 v120, v120, v158
	v_mul_f32_e32 v121, v121, v158
	v_mul_f32_e32 v114, v114, v158
	v_mul_f32_e32 v115, v115, v158
	v_mul_f32_e32 v112, v112, v158
	v_mul_f32_e32 v113, v113, v158
	v_mul_f32_e32 v118, v118, v158
	v_mul_f32_e32 v119, v119, v158
	v_mul_f32_e32 v116, v116, v158
	v_mul_f32_e32 v117, v117, v158
	v_max_f32_e32 v124, 0, v124
	v_max_f32_e32 v120, 0, v120
	v_max_f32_e32 v125, 0, v125
	v_max_f32_e32 v121, 0, v121
	v_max_f32_e32 v126, 0, v126
	v_max_f32_e32 v122, 0, v122
	v_max_f32_e32 v127, 0, v127
	v_max_f32_e32 v123, 0, v123
	v_max_f32_e32 v112, 0, v112
	v_max_f32_e32 v113, 0, v113
	v_max_f32_e32 v114, 0, v114
	v_max_f32_e32 v115, 0, v115
	v_max_f32_e32 v116, 0, v116
	v_max_f32_e32 v117, 0, v117
	v_max_f32_e32 v118, 0, v118
	v_max_f32_e32 v119, 0, v119
	v_mul_f32_e32 v124, v124, v124
	v_mul_f32_e32 v120, v120, v120
	v_mul_f32_e32 v125, v125, v125
	v_mul_f32_e32 v121, v121, v121
	v_mul_f32_e32 v126, v126, v126
	v_mul_f32_e32 v122, v122, v122
	v_mul_f32_e32 v127, v127, v127
	v_mul_f32_e32 v123, v123, v123
	v_mul_f32_e32 v149, v112, v112
	v_mul_f32_e32 v158, v113, v113
	v_mul_f32_e32 v159, v114, v114
	v_mul_f32_e32 v160, v115, v115
	v_cvt_pk_bf16_f32 v112, v124, v125
	v_cvt_pk_bf16_f32 v113, v126, v127
	v_cvt_pk_bf16_f32 v114, v120, v121
	v_cvt_pk_bf16_f32 v115, v122, v123
	v_mul_f32_e32 v116, v116, v116
	v_mul_f32_e32 v117, v117, v117
	v_mul_f32_e32 v118, v118, v118
	v_mul_f32_e32 v119, v119, v119
	global_store_dwordx4 v[144:145], v[112:115], off
	s_nop 1
	v_cvt_pk_bf16_f32 v112, v116, v117
	v_cvt_pk_bf16_f32 v113, v118, v119
	v_cvt_pk_bf16_f32 v114, v149, v158
	v_cvt_pk_bf16_f32 v115, v159, v160
	global_store_dwordx4 v[144:145], v[112:115], off offset:256
	global_load_dword v112, v[146:147], off offset:64
	s_waitcnt vmcnt(0)
	v_mul_f32_e32 v110, v110, v112
	v_mul_f32_e32 v111, v111, v112
	v_or_b32_e32 v114, 16, v148
	v_ashrrev_i32_e32 v115, 31, v114
	v_lshlrev_b64 v[114:115], 14, v[114:115]
	v_mul_f32_e32 v108, v108, v112
	v_mul_f32_e32 v109, v109, v112
	v_mul_f32_e32 v106, v106, v112
	v_mul_f32_e32 v107, v107, v112
	v_mul_f32_e32 v104, v104, v112
	v_mul_f32_e32 v105, v105, v112
	v_mul_f32_e32 v98, v98, v112
	v_mul_f32_e32 v99, v99, v112
	v_mul_f32_e32 v96, v96, v112
	v_mul_f32_e32 v97, v97, v112
	v_lshl_add_u64 v[114:115], s[74:75], 0, v[114:115]
	v_mul_f32_e32 v102, v102, v112
	v_mul_f32_e32 v103, v103, v112
	v_mul_f32_e32 v100, v100, v112
	v_mul_f32_e32 v101, v101, v112
	v_max_f32_e32 v108, 0, v108
	v_max_f32_e32 v104, 0, v104
	v_max_f32_e32 v109, 0, v109
	v_max_f32_e32 v105, 0, v105
	v_max_f32_e32 v110, 0, v110
	v_max_f32_e32 v106, 0, v106
	v_max_f32_e32 v111, 0, v111
	v_max_f32_e32 v107, 0, v107
	v_max_f32_e32 v96, 0, v96
	v_max_f32_e32 v97, 0, v97
	v_max_f32_e32 v98, 0, v98
	v_max_f32_e32 v99, 0, v99
	v_lshl_add_u64 v[114:115], v[114:115], 0, v[150:151]
	v_max_f32_e32 v100, 0, v100
	v_max_f32_e32 v101, 0, v101
	v_max_f32_e32 v102, 0, v102
	v_max_f32_e32 v103, 0, v103
	v_mul_f32_e32 v108, v108, v108
	v_mul_f32_e32 v104, v104, v104
	v_mul_f32_e32 v109, v109, v109
	v_mul_f32_e32 v105, v105, v105
	v_mul_f32_e32 v110, v110, v110
	v_mul_f32_e32 v106, v106, v106
	v_mul_f32_e32 v111, v111, v111
	v_mul_f32_e32 v107, v107, v107
	v_mul_f32_e32 v112, v96, v96
	v_mul_f32_e32 v113, v97, v97
	v_mul_f32_e32 v116, v98, v98
	v_mul_f32_e32 v117, v99, v99
	v_cvt_pk_bf16_f32 v96, v108, v109
	v_cvt_pk_bf16_f32 v97, v110, v111
	v_cvt_pk_bf16_f32 v98, v104, v105
	v_cvt_pk_bf16_f32 v99, v106, v107
	v_mul_f32_e32 v100, v100, v100
	v_mul_f32_e32 v101, v101, v101
	v_mul_f32_e32 v102, v102, v102
	v_mul_f32_e32 v103, v103, v103
	global_store_dwordx4 v[114:115], v[96:99], off
	s_nop 1
	v_cvt_pk_bf16_f32 v96, v100, v101
	v_cvt_pk_bf16_f32 v97, v102, v103
	v_cvt_pk_bf16_f32 v98, v112, v113
	v_cvt_pk_bf16_f32 v99, v116, v117
	global_store_dwordx4 v[114:115], v[96:99], off offset:256
	global_load_dword v96, v[146:147], off offset:128
	s_waitcnt vmcnt(0)
	v_mul_f32_e32 v94, v94, v96
	v_mul_f32_e32 v95, v95, v96
	v_or_b32_e32 v98, 32, v148
	v_ashrrev_i32_e32 v99, 31, v98
	v_lshlrev_b64 v[98:99], 14, v[98:99]
	v_mul_f32_e32 v92, v92, v96
	v_mul_f32_e32 v93, v93, v96
	v_mul_f32_e32 v90, v90, v96
	v_mul_f32_e32 v91, v91, v96
	v_mul_f32_e32 v88, v88, v96
	v_mul_f32_e32 v89, v89, v96
	v_mul_f32_e32 v82, v82, v96
	v_mul_f32_e32 v83, v83, v96
	v_mul_f32_e32 v80, v80, v96
	v_mul_f32_e32 v81, v81, v96
	v_lshl_add_u64 v[98:99], s[74:75], 0, v[98:99]
	v_mul_f32_e32 v86, v86, v96
	v_mul_f32_e32 v87, v87, v96
	v_mul_f32_e32 v84, v84, v96
	v_mul_f32_e32 v85, v85, v96
	v_max_f32_e32 v92, 0, v92
	v_max_f32_e32 v88, 0, v88
	v_max_f32_e32 v93, 0, v93
	v_max_f32_e32 v89, 0, v89
	v_max_f32_e32 v94, 0, v94
	v_max_f32_e32 v90, 0, v90
	v_max_f32_e32 v95, 0, v95
	v_max_f32_e32 v91, 0, v91
	v_max_f32_e32 v80, 0, v80
	v_max_f32_e32 v81, 0, v81
	v_max_f32_e32 v82, 0, v82
	v_max_f32_e32 v83, 0, v83
	v_lshl_add_u64 v[98:99], v[98:99], 0, v[150:151]
	v_max_f32_e32 v84, 0, v84
	v_max_f32_e32 v85, 0, v85
	v_max_f32_e32 v86, 0, v86
	v_max_f32_e32 v87, 0, v87
	v_mul_f32_e32 v92, v92, v92
	v_mul_f32_e32 v88, v88, v88
	v_mul_f32_e32 v93, v93, v93
	v_mul_f32_e32 v89, v89, v89
	v_mul_f32_e32 v94, v94, v94
	v_mul_f32_e32 v90, v90, v90
	v_mul_f32_e32 v95, v95, v95
	v_mul_f32_e32 v91, v91, v91
	v_mul_f32_e32 v96, v80, v80
	v_mul_f32_e32 v97, v81, v81
	v_mul_f32_e32 v100, v82, v82
	v_mul_f32_e32 v101, v83, v83
	v_cvt_pk_bf16_f32 v80, v92, v93
	v_cvt_pk_bf16_f32 v81, v94, v95
	v_cvt_pk_bf16_f32 v82, v88, v89
	v_cvt_pk_bf16_f32 v83, v90, v91
	v_mul_f32_e32 v84, v84, v84
	v_mul_f32_e32 v85, v85, v85
	v_mul_f32_e32 v86, v86, v86
	v_mul_f32_e32 v87, v87, v87
	global_store_dwordx4 v[98:99], v[80:83], off
	s_nop 1
	v_cvt_pk_bf16_f32 v80, v84, v85
	v_cvt_pk_bf16_f32 v81, v86, v87
	v_cvt_pk_bf16_f32 v82, v96, v97
	v_cvt_pk_bf16_f32 v83, v100, v101
	global_store_dwordx4 v[98:99], v[80:83], off offset:256
	global_load_dword v80, v[146:147], off offset:192
	s_waitcnt vmcnt(0)
; __device__ __forceinline__ unsigned cvt_pk_bf16(float lo, float hi) { unsigned r; asm volatile("v_cvt_pk_bf16_f32 %0, %1, %2" : "=v"(r) : "v"(lo), "v"(hi)); return r; }
;     __device__ __forceinline__ void operator()(const f32x4 (&acc)[2][2][4][2], const Unit& u, int wr, int wc, int fr, int fq) const {
;         const int row0 = u.pm * BM + wr * 64 + fr, col0 = u.pn * BM + wc * 32 + 8 * fq;
; #pragma unroll
;         for (int ai = 0; ai < 2; ++ai)
; #pragma unroll
;             for (int m = 0; m < 4; ++m) { const int row = row0 + ai * HALF + m * 16; const float rs = ACT == 1 ? ss[row] : 1.0f;
;                 bf16_t* rowp = O + (size_t)row * ldc + col0;
; #pragma unroll
;                 for (int bj = 0; bj < 2; ++bj) { f32x4 v0 = acc[ai][bj][m][0] * rs, v1 = acc[ai][bj][m][1] * rs;
;                     if (ACT == 1) {
; #pragma unroll
;                         for (int e = 0; e < 4; ++e) { const float a0 = fmaxf(v0[e], 0.f), a1 = fmaxf(v1[e], 0.f); v0[e] = a0 * a0; v1[e] = a1 * a1; } }
;                     u32x4 w; w.x = cvt_pk_bf16(v0[0], v0[1]); w.y = cvt_pk_bf16(v0[2], v0[3]); w.z = cvt_pk_bf16(v1[0], v1[1]); w.w = cvt_pk_bf16(v1[2], v1[3]);
;                     *(u32x4*)(rowp + bj * HALF) = w; } }
	v_mul_f32_e32 v78, v78, v80
	v_mul_f32_e32 v79, v79, v80
	v_or_b32_e32 v82, 48, v148
	v_ashrrev_i32_e32 v83, 31, v82
	v_lshlrev_b64 v[82:83], 14, v[82:83]
	v_mul_f32_e32 v76, v76, v80
	v_mul_f32_e32 v77, v77, v80
	v_mul_f32_e32 v74, v74, v80
	v_mul_f32_e32 v75, v75, v80
	v_mul_f32_e32 v72, v72, v80
	v_mul_f32_e32 v73, v73, v80
	v_mul_f32_e32 v66, v66, v80
	v_mul_f32_e32 v67, v67, v80
	v_mul_f32_e32 v64, v64, v80
	v_mul_f32_e32 v65, v65, v80
	v_lshl_add_u64 v[82:83], s[74:75], 0, v[82:83]
	v_mul_f32_e32 v70, v70, v80
	v_mul_f32_e32 v71, v71, v80
	v_mul_f32_e32 v68, v68, v80
	v_mul_f32_e32 v69, v69, v80
	v_max_f32_e32 v76, 0, v76
	v_max_f32_e32 v72, 0, v72
	v_max_f32_e32 v77, 0, v77
	v_max_f32_e32 v73, 0, v73
	v_max_f32_e32 v78, 0, v78
	v_max_f32_e32 v74, 0, v74
	v_max_f32_e32 v79, 0, v79
	v_max_f32_e32 v75, 0, v75
	v_max_f32_e32 v64, 0, v64
	v_max_f32_e32 v65, 0, v65
	v_max_f32_e32 v66, 0, v66
	v_max_f32_e32 v67, 0, v67
	v_lshl_add_u64 v[82:83], v[82:83], 0, v[150:151]
	v_max_f32_e32 v68, 0, v68
	v_max_f32_e32 v69, 0, v69
	v_max_f32_e32 v70, 0, v70
	v_max_f32_e32 v71, 0, v71
	v_mul_f32_e32 v76, v76, v76
	v_mul_f32_e32 v72, v72, v72
	v_mul_f32_e32 v77, v77, v77
	v_mul_f32_e32 v73, v73, v73
	v_mul_f32_e32 v78, v78, v78
	v_mul_f32_e32 v74, v74, v74
	v_mul_f32_e32 v79, v79, v79
	v_mul_f32_e32 v75, v75, v75
	v_mul_f32_e32 v80, v64, v64
	v_mul_f32_e32 v81, v65, v65
	v_mul_f32_e32 v84, v66, v66
	v_mul_f32_e32 v85, v67, v67
	v_cvt_pk_bf16_f32 v64, v76, v77
	v_cvt_pk_bf16_f32 v65, v78, v79
	v_cvt_pk_bf16_f32 v66, v72, v73
	v_cvt_pk_bf16_f32 v67, v74, v75
	v_mul_f32_e32 v68, v68, v68
	v_mul_f32_e32 v69, v69, v69
	v_mul_f32_e32 v70, v70, v70
	v_mul_f32_e32 v71, v71, v71
	global_store_dwordx4 v[82:83], v[64:67], off
	s_nop 1
	v_cvt_pk_bf16_f32 v64, v68, v69
	v_cvt_pk_bf16_f32 v65, v70, v71
	v_cvt_pk_bf16_f32 v66, v80, v81
	v_cvt_pk_bf16_f32 v67, v84, v85
	global_store_dwordx4 v[82:83], v[64:67], off offset:256
	global_load_dword v64, v[146:147], off offset:512
	v_add_co_u32_e32 v68, vcc, s52, v144
	v_lshl_add_u64 v[66:67], v[144:145], 0, s[16:17]
	s_nop 0
	v_addc_co_u32_e32 v69, vcc, 0, v145, vcc
	s_waitcnt vmcnt(0)
	v_mul_f32_e32 v62, v62, v64
	v_mul_f32_e32 v63, v63, v64
	v_mul_f32_e32 v60, v60, v64
	v_mul_f32_e32 v61, v61, v64
	v_mul_f32_e32 v58, v58, v64
	v_mul_f32_e32 v59, v59, v64
	v_mul_f32_e32 v56, v56, v64
	v_mul_f32_e32 v57, v57, v64
	v_mul_f32_e32 v50, v50, v64
	v_mul_f32_e32 v51, v51, v64
	v_mul_f32_e32 v48, v48, v64
	v_mul_f32_e32 v49, v49, v64
	v_mul_f32_e32 v54, v54, v64
	v_mul_f32_e32 v55, v55, v64
	v_mul_f32_e32 v52, v52, v64
	v_mul_f32_e32 v53, v53, v64
	v_max_f32_e32 v60, 0, v60
	v_max_f32_e32 v56, 0, v56
	v_max_f32_e32 v61, 0, v61
	v_max_f32_e32 v57, 0, v57
	v_max_f32_e32 v62, 0, v62
	v_max_f32_e32 v58, 0, v58
	v_max_f32_e32 v63, 0, v63
	v_max_f32_e32 v59, 0, v59
	v_max_f32_e32 v48, 0, v48
	v_max_f32_e32 v49, 0, v49
	v_max_f32_e32 v50, 0, v50
	v_max_f32_e32 v51, 0, v51
	v_max_f32_e32 v52, 0, v52
	v_max_f32_e32 v53, 0, v53
	v_max_f32_e32 v54, 0, v54
	v_max_f32_e32 v55, 0, v55
	v_mul_f32_e32 v60, v60, v60
	v_mul_f32_e32 v56, v56, v56
	v_mul_f32_e32 v61, v61, v61
	v_mul_f32_e32 v57, v57, v57
	v_mul_f32_e32 v62, v62, v62
	v_mul_f32_e32 v58, v58, v58
	v_mul_f32_e32 v63, v63, v63
	v_mul_f32_e32 v59, v59, v59
	v_mul_f32_e32 v64, v48, v48
	v_mul_f32_e32 v65, v49, v49
	v_mul_f32_e32 v70, v50, v50
	v_mul_f32_e32 v71, v51, v51
	v_cvt_pk_bf16_f32 v48, v60, v61
	v_cvt_pk_bf16_f32 v49, v62, v63
	v_cvt_pk_bf16_f32 v50, v56, v57
	v_cvt_pk_bf16_f32 v51, v58, v59
	v_mul_f32_e32 v52, v52, v52
	v_mul_f32_e32 v53, v53, v53
	v_mul_f32_e32 v54, v54, v54
	v_mul_f32_e32 v55, v55, v55
	global_store_dwordx4 v[68:69], v[48:51], off
	s_nop 1
	v_cvt_pk_bf16_f32 v48, v52, v53
	v_cvt_pk_bf16_f32 v49, v54, v55
	v_cvt_pk_bf16_f32 v50, v64, v65
	v_cvt_pk_bf16_f32 v51, v70, v71
	global_store_dwordx4 v[66:67], v[48:51], off offset:256
	global_load_dword v48, v[146:147], off offset:576
	v_add_co_u32_e32 v52, vcc, s53, v144
	v_lshl_add_u64 v[50:51], v[144:145], 0, s[18:19]
	s_nop 0
	v_addc_co_u32_e32 v53, vcc, 0, v145, vcc
	s_waitcnt vmcnt(0)
; __device__ __forceinline__ unsigned cvt_pk_bf16(float lo, float hi) { unsigned r; asm volatile("v_cvt_pk_bf16_f32 %0, %1, %2" : "=v"(r) : "v"(lo), "v"(hi)); return r; }
;     __device__ __forceinline__ void operator()(const f32x4 (&acc)[2][2][4][2], const Unit& u, int wr, int wc, int fr, int fq) const {
;         const int row0 = u.pm * BM + wr * 64 + fr, col0 = u.pn * BM + wc * 32 + 8 * fq;
; #pragma unroll
;         for (int ai = 0; ai < 2; ++ai)
; #pragma unroll
;             for (int m = 0; m < 4; ++m) { const int row = row0 + ai * HALF + m * 16; const float rs = ACT == 1 ? ss[row] : 1.0f;
;                 bf16_t* rowp = O + (size_t)row * ldc + col0;
; #pragma unroll
;                 for (int bj = 0; bj < 2; ++bj) { f32x4 v0 = acc[ai][bj][m][0] * rs, v1 = acc[ai][bj][m][1] * rs;
;                     if (ACT == 1) {
; #pragma unroll
;                         for (int e = 0; e < 4; ++e) { const float a0 = fmaxf(v0[e], 0.f), a1 = fmaxf(v1[e], 0.f); v0[e] = a0 * a0; v1[e] = a1 * a1; } }
;                     u32x4 w; w.x = cvt_pk_bf16(v0[0], v0[1]); w.y = cvt_pk_bf16(v0[2], v0[3]); w.z = cvt_pk_bf16(v1[0], v1[1]); w.w = cvt_pk_bf16(v1[2], v1[3]);
;                     *(u32x4*)(rowp + bj * HALF) = w; } }
	v_mul_f32_e32 v46, v46, v48
	v_mul_f32_e32 v47, v47, v48
	v_mul_f32_e32 v44, v44, v48
	v_mul_f32_e32 v45, v45, v48
	v_mul_f32_e32 v42, v42, v48
	v_mul_f32_e32 v43, v43, v48
	v_mul_f32_e32 v40, v40, v48
	v_mul_f32_e32 v41, v41, v48
	v_mul_f32_e32 v34, v34, v48
	v_mul_f32_e32 v35, v35, v48
	v_mul_f32_e32 v32, v32, v48
	v_mul_f32_e32 v33, v33, v48
	v_mul_f32_e32 v38, v38, v48
	v_mul_f32_e32 v39, v39, v48
	v_mul_f32_e32 v36, v36, v48
	v_mul_f32_e32 v37, v37, v48
	v_max_f32_e32 v44, 0, v44
	v_max_f32_e32 v40, 0, v40
	v_max_f32_e32 v45, 0, v45
	v_max_f32_e32 v41, 0, v41
	v_max_f32_e32 v46, 0, v46
	v_max_f32_e32 v42, 0, v42
	v_max_f32_e32 v47, 0, v47
	v_max_f32_e32 v43, 0, v43
	v_max_f32_e32 v32, 0, v32
	v_max_f32_e32 v33, 0, v33
	v_max_f32_e32 v34, 0, v34
	v_max_f32_e32 v35, 0, v35
	v_max_f32_e32 v36, 0, v36
	v_max_f32_e32 v37, 0, v37
	v_max_f32_e32 v38, 0, v38
	v_max_f32_e32 v39, 0, v39
	v_mul_f32_e32 v44, v44, v44
	v_mul_f32_e32 v40, v40, v40
	v_mul_f32_e32 v45, v45, v45
	v_mul_f32_e32 v41, v41, v41
	v_mul_f32_e32 v46, v46, v46
	v_mul_f32_e32 v42, v42, v42
	v_mul_f32_e32 v47, v47, v47
	v_mul_f32_e32 v43, v43, v43
	v_mul_f32_e32 v48, v32, v32
	v_mul_f32_e32 v49, v33, v33
	v_mul_f32_e32 v54, v34, v34
	v_mul_f32_e32 v55, v35, v35
	v_cvt_pk_bf16_f32 v32, v44, v45
	v_cvt_pk_bf16_f32 v33, v46, v47
	v_cvt_pk_bf16_f32 v34, v40, v41
	v_cvt_pk_bf16_f32 v35, v42, v43
	v_mul_f32_e32 v36, v36, v36
	v_mul_f32_e32 v37, v37, v37
	v_mul_f32_e32 v38, v38, v38
	v_mul_f32_e32 v39, v39, v39
	global_store_dwordx4 v[52:53], v[32:35], off
	s_nop 1
	v_cvt_pk_bf16_f32 v32, v36, v37
	v_cvt_pk_bf16_f32 v33, v38, v39
	v_cvt_pk_bf16_f32 v34, v48, v49
	v_cvt_pk_bf16_f32 v35, v54, v55
	global_store_dwordx4 v[50:51], v[32:35], off offset:256
	global_load_dword v32, v[146:147], off offset:640
	v_add_co_u32_e32 v36, vcc, s54, v144
	v_lshl_add_u64 v[34:35], v[144:145], 0, s[20:21]
	s_nop 0
	v_addc_co_u32_e32 v37, vcc, 0, v145, vcc
	s_andn2_b64 vcc, exec, s[4:5]
	s_waitcnt vmcnt(0)
	v_mul_f32_e32 v30, v30, v32
	v_mul_f32_e32 v31, v31, v32
	v_mul_f32_e32 v28, v28, v32
	v_mul_f32_e32 v29, v29, v32
	v_mul_f32_e32 v26, v26, v32
	v_mul_f32_e32 v27, v27, v32
	v_mul_f32_e32 v24, v24, v32
	v_mul_f32_e32 v25, v25, v32
	v_mul_f32_e32 v18, v18, v32
	v_mul_f32_e32 v19, v19, v32
	v_mul_f32_e32 v16, v16, v32
	v_mul_f32_e32 v17, v17, v32
	v_mul_f32_e32 v22, v22, v32
	v_mul_f32_e32 v23, v23, v32
	v_mul_f32_e32 v20, v20, v32
	v_mul_f32_e32 v21, v21, v32
	v_max_f32_e32 v28, 0, v28
	v_max_f32_e32 v24, 0, v24
	v_max_f32_e32 v29, 0, v29
	v_max_f32_e32 v25, 0, v25
	v_max_f32_e32 v30, 0, v30
	v_max_f32_e32 v26, 0, v26
	v_max_f32_e32 v31, 0, v31
	v_max_f32_e32 v27, 0, v27
	v_max_f32_e32 v16, 0, v16
	v_max_f32_e32 v17, 0, v17
	v_max_f32_e32 v18, 0, v18
	v_max_f32_e32 v19, 0, v19
	v_max_f32_e32 v20, 0, v20
	v_max_f32_e32 v21, 0, v21
	v_max_f32_e32 v22, 0, v22
	v_max_f32_e32 v23, 0, v23
	v_mul_f32_e32 v28, v28, v28
	v_mul_f32_e32 v24, v24, v24
	v_mul_f32_e32 v29, v29, v29
	v_mul_f32_e32 v25, v25, v25
	v_mul_f32_e32 v30, v30, v30
	v_mul_f32_e32 v26, v26, v26
	v_mul_f32_e32 v31, v31, v31
	v_mul_f32_e32 v27, v27, v27
	v_mul_f32_e32 v32, v16, v16
	v_mul_f32_e32 v33, v17, v17
	v_mul_f32_e32 v38, v18, v18
	v_mul_f32_e32 v39, v19, v19
	v_cvt_pk_bf16_f32 v16, v28, v29
	v_cvt_pk_bf16_f32 v17, v30, v31
	v_cvt_pk_bf16_f32 v18, v24, v25
	v_cvt_pk_bf16_f32 v19, v26, v27
	v_mul_f32_e32 v20, v20, v20
	v_mul_f32_e32 v21, v21, v21
	v_mul_f32_e32 v22, v22, v22
	v_mul_f32_e32 v23, v23, v23
	global_store_dwordx4 v[36:37], v[16:19], off
	s_nop 1
	v_cvt_pk_bf16_f32 v16, v20, v21
	v_cvt_pk_bf16_f32 v17, v22, v23
	v_cvt_pk_bf16_f32 v18, v32, v33
	v_cvt_pk_bf16_f32 v19, v38, v39
	global_store_dwordx4 v[34:35], v[16:19], off offset:256
	global_load_dword v16, v[146:147], off offset:704
	v_add_co_u32_e64 v20, s[0:1], s55, v144
	v_lshl_add_u64 v[18:19], v[144:145], 0, s[22:23]
	s_nop 0
	v_addc_co_u32_e64 v21, s[0:1], 0, v145, s[0:1]
	s_mov_b64 s[0:1], -1
	s_waitcnt vmcnt(0)
	v_mul_f32_e32 v14, v14, v16
	v_mul_f32_e32 v15, v15, v16
	v_mul_f32_e32 v12, v12, v16
	v_mul_f32_e32 v13, v13, v16
	v_mul_f32_e32 v10, v10, v16
	v_mul_f32_e32 v11, v11, v16
	v_mul_f32_e32 v8, v8, v16
	v_mul_f32_e32 v9, v9, v16
	v_mul_f32_e32 v2, v2, v16
	v_mul_f32_e32 v3, v3, v16
	v_mul_f32_e32 v0, v0, v16
	v_mul_f32_e32 v1, v1, v16
	v_mul_f32_e32 v6, v6, v16
	v_mul_f32_e32 v7, v7, v16
	v_mul_f32_e32 v4, v4, v16
	v_mul_f32_e32 v5, v5, v16
	v_max_f32_e32 v12, 0, v12
	v_max_f32_e32 v8, 0, v8
	v_max_f32_e32 v13, 0, v13
	v_max_f32_e32 v9, 0, v9
	v_max_f32_e32 v14, 0, v14
	v_max_f32_e32 v10, 0, v10
	v_max_f32_e32 v15, 0, v15
	v_max_f32_e32 v11, 0, v11
	v_max_f32_e32 v0, 0, v0
	v_max_f32_e32 v1, 0, v1
	v_max_f32_e32 v2, 0, v2
	v_max_f32_e32 v3, 0, v3
	v_max_f32_e32 v4, 0, v4
	v_max_f32_e32 v5, 0, v5
	v_max_f32_e32 v6, 0, v6
	v_max_f32_e32 v7, 0, v7
	v_mul_f32_e32 v12, v12, v12
	v_mul_f32_e32 v8, v8, v8
	v_mul_f32_e32 v13, v13, v13
	v_mul_f32_e32 v9, v9, v9
	v_mul_f32_e32 v14, v14, v14
	v_mul_f32_e32 v10, v10, v10
	v_mul_f32_e32 v15, v15, v15
	v_mul_f32_e32 v11, v11, v11
	v_mul_f32_e32 v16, v0, v0
	v_mul_f32_e32 v17, v1, v1
	v_mul_f32_e32 v22, v2, v2
	v_mul_f32_e32 v23, v3, v3
	v_cvt_pk_bf16_f32 v0, v12, v13
	v_cvt_pk_bf16_f32 v1, v14, v15
	v_cvt_pk_bf16_f32 v2, v8, v9
	v_cvt_pk_bf16_f32 v3, v10, v11
	v_mul_f32_e32 v4, v4, v4
	v_mul_f32_e32 v5, v5, v5
	v_mul_f32_e32 v6, v6, v6
	v_mul_f32_e32 v7, v7, v7
	global_store_dwordx4 v[20:21], v[0:3], off
	s_nop 1
	v_cvt_pk_bf16_f32 v0, v4, v5
	v_cvt_pk_bf16_f32 v1, v6, v7
	v_cvt_pk_bf16_f32 v2, v16, v17
	v_cvt_pk_bf16_f32 v3, v22, v23
	global_store_dwordx4 v[18:19], v[0:3], off offset:256
	s_cbranch_vccnz .LBB0_929
	s_andn2_b64 vcc, exec, s[8:9]
	s_cbranch_vccnz .LBB0_928
	s_barrier
	s_branch .LBB0_928

; __device__ __forceinline__ void unpack8(const u32x4& w, float (&f)[8]) { f[0] = bflo(w.x); f[1] = bfhi(w.x); f[2] = bflo(w.y); f[3] = bfhi(w.y); f[4] = bflo(w.z); f[5] = bfhi(w.z); f[6] = bflo(w.w); f[7] = bfhi(w.w); }
; __global__ void __launch_bounds__(512, 2) hybrid_fwd(Args a) {
;     ...
;         for (int m = gw; m < M; m += NGW) { const float sf_ = wave_sum(lane < 32 ? SSF[(size_t)m * 32 + lane] : 0.f); const float rs = rsqrtf(sf_ * (1.0f / DM) + EPS);
;             const u32x4* xb = (const u32x4*)(Y + (size_t)m * DM); f32x4* yr = (f32x4*)(a.out + (size_t)m * DM); u32x4 xw[4];
; #pragma unroll
;             for (int j = 0; j < 4; ++j) xw[j] = xb[lane + 64 * j];
; #pragma unroll
;             for (int j = 0; j < 4; ++j) { float f[8]; pg8::unpack8(xw[j], f); const int c = (lane + 64 * j) * 8; const f32x4 w0 = *(const f32x4*)(a.fnorm + c), w1 = *(const f32x4*)(a.fnorm + c + 4);
;                 yr[(lane + 64 * j) * 2] = (f32x4){f[0] * rs * w0[0], f[1] * rs * w0[1], f[2] * rs * w0[2], f[3] * rs * w0[3]}; yr[(lane + 64 * j) * 2 + 1] = (f32x4){f[4] * rs * w1[0], f[5] * rs * w1[1], f[6] * rs * w1[2], f[7] * rs * w1[3]}; } }
.LBB0_1107:
	s_or_b64 exec, exec, s[0:1]
	v_lshl_add_u64 v[22:23], s[86:87], 0, v[8:9]
	v_add_co_u32_e64 v46, s[0:1], s11, v22
	s_waitcnt vmcnt(0)
	ds_bpermute_b32 v34, v14, v21
	v_addc_co_u32_e64 v47, s[0:1], 0, v23, s[0:1]
	global_load_dwordx4 v[22:25], v[46:47], off nt
	global_load_dwordx4 v[26:29], v[0:1], off nt
	global_load_dwordx4 v[30:33], v[0:1], off offset:16 nt
	v_add_u32_e32 v184, s88, v184
	s_waitcnt lgkmcnt(0)
	v_add_f32_e32 v21, v21, v34
	ds_bpermute_b32 v34, v15, v21
	v_lshl_add_u64 v[8:9], v[8:9], 0, s[2:3]
	v_lshl_add_u64 v[12:13], v[12:13], 0, s[6:7]
	s_waitcnt lgkmcnt(0)
	v_add_f32_e32 v21, v21, v34
	ds_bpermute_b32 v34, v16, v21
	s_waitcnt lgkmcnt(0)
	v_add_f32_e32 v21, v21, v34
	ds_bpermute_b32 v34, v17, v21
	s_waitcnt lgkmcnt(0)
	v_add_f32_e32 v21, v21, v34
	ds_bpermute_b32 v34, v18, v21
	s_waitcnt lgkmcnt(0)
	v_add_f32_e32 v21, v21, v34
	ds_bpermute_b32 v34, v19, v21
	s_waitcnt lgkmcnt(0)
	v_add_f32_e32 v21, v21, v34
	v_fmamk_f32 v21, v21, 0x3a000000, v20
	v_mul_f32_e32 v34, 0x4b800000, v21
	v_cmp_gt_f32_e64 s[0:1], s10, v21
	s_waitcnt vmcnt(2)
	v_lshlrev_b32_e32 v48, 16, v22
	v_cndmask_b32_e64 v21, v21, v34, s[0:1]
	v_rsq_f32_e32 v21, v21
	global_load_dwordx4 v[34:37], v[46:47], off offset:1024 nt
	global_load_dwordx4 v[38:41], v[46:47], off offset:2048 nt
	global_load_dwordx4 v[42:45], v[46:47], off offset:3072 nt
	v_and_b32_e32 v49, 0xffff0000, v22
	v_lshlrev_b32_e32 v22, 16, v23
	v_mul_f32_e32 v46, 0x45800000, v21
	v_cndmask_b32_e64 v46, v21, v46, s[0:1]
	v_and_b32_e32 v23, 0xffff0000, v23
	v_lshlrev_b32_e32 v50, 16, v24
	v_and_b32_e32 v51, 0xffff0000, v24
	v_lshlrev_b32_e32 v24, 16, v25
	v_and_b32_e32 v25, 0xffff0000, v25
	v_mul_f32_e32 v48, v46, v48
	v_mul_f32_e32 v49, v46, v49
	v_mul_f32_e32 v52, v46, v22
	v_mul_f32_e32 v53, v46, v23
	v_mul_f32_e32 v50, v46, v50
	v_mul_f32_e32 v51, v46, v51
	v_mul_f32_e32 v54, v46, v24
	v_mul_f32_e32 v55, v46, v25
	s_waitcnt vmcnt(4)
	v_mul_f32_e32 v22, v26, v48
	v_mul_f32_e32 v23, v27, v49
	v_mul_f32_e32 v24, v28, v52
	v_mul_f32_e32 v25, v29, v53
	s_waitcnt vmcnt(3)
	v_mul_f32_e32 v26, v30, v50
	v_mul_f32_e32 v27, v31, v51
	v_mul_f32_e32 v28, v32, v54
	v_mul_f32_e32 v29, v33, v55
	global_store_dwordx4 v[10:11], v[22:25], off offset:-4096 nt
	global_store_dwordx4 v[10:11], v[26:29], off offset:-4080 nt
	global_load_dwordx4 v[22:25], v[2:3], off nt
	s_nop 0
	global_load_dwordx4 v[26:29], v[2:3], off offset:16 nt
	v_cmp_lt_i32_e64 s[0:1], s12, v184
	s_or_b64 s[8:9], s[0:1], s[8:9]
	s_waitcnt vmcnt(6)
	v_lshlrev_b32_e32 v30, 16, v34
	v_and_b32_e32 v31, 0xffff0000, v34
	v_lshlrev_b32_e32 v32, 16, v35
	v_and_b32_e32 v33, 0xffff0000, v35
	v_lshlrev_b32_e32 v34, 16, v36
	v_and_b32_e32 v35, 0xffff0000, v36
	v_lshlrev_b32_e32 v36, 16, v37
	v_and_b32_e32 v37, 0xffff0000, v37
	v_mul_f32_e32 v30, v46, v30
	v_mul_f32_e32 v31, v46, v31
	v_mul_f32_e32 v32, v46, v32
	v_mul_f32_e32 v33, v46, v33
	v_mul_f32_e32 v34, v46, v34
	v_mul_f32_e32 v35, v46, v35
	v_mul_f32_e32 v36, v46, v36
	v_mul_f32_e32 v37, v46, v37
	s_waitcnt vmcnt(1)
	v_mul_f32_e32 v22, v22, v30
	v_mul_f32_e32 v23, v23, v31
	v_mul_f32_e32 v24, v24, v32
	v_mul_f32_e32 v25, v25, v33
	s_waitcnt vmcnt(0)
	v_mul_f32_e32 v26, v26, v34
	v_mul_f32_e32 v27, v27, v35
	v_mul_f32_e32 v28, v28, v36
	v_mul_f32_e32 v29, v29, v37
	global_store_dwordx4 v[10:11], v[22:25], off offset:-2048 nt
	global_store_dwordx4 v[10:11], v[26:29], off offset:-2032 nt
	global_load_dwordx4 v[22:25], v[4:5], off nt
	s_nop 0
	global_load_dwordx4 v[26:29], v[4:5], off offset:16 nt
	v_lshlrev_b32_e32 v30, 16, v38
	v_and_b32_e32 v31, 0xffff0000, v38
	v_lshlrev_b32_e32 v32, 16, v39
	v_and_b32_e32 v33, 0xffff0000, v39
	v_lshlrev_b32_e32 v34, 16, v40
	v_and_b32_e32 v35, 0xffff0000, v40
	v_lshlrev_b32_e32 v36, 16, v41
	v_and_b32_e32 v37, 0xffff0000, v41
	v_mul_f32_e32 v30, v46, v30
	v_mul_f32_e32 v31, v46, v31
	v_mul_f32_e32 v32, v46, v32
	v_mul_f32_e32 v33, v46, v33
	v_mul_f32_e32 v34, v46, v34
	v_mul_f32_e32 v35, v46, v35
	v_mul_f32_e32 v36, v46, v36
	v_mul_f32_e32 v37, v46, v37
	s_waitcnt vmcnt(1)
	v_mul_f32_e32 v22, v22, v30
	v_mul_f32_e32 v23, v23, v31
	v_mul_f32_e32 v24, v24, v32
	v_mul_f32_e32 v25, v25, v33
	s_waitcnt vmcnt(0)
	v_mul_f32_e32 v26, v26, v34
	v_mul_f32_e32 v27, v27, v35
	v_mul_f32_e32 v28, v28, v36
	v_mul_f32_e32 v29, v29, v37
	global_store_dwordx4 v[10:11], v[22:25], off nt
	global_store_dwordx4 v[10:11], v[26:29], off offset:16 nt
	global_load_dwordx4 v[22:25], v[6:7], off nt
	s_nop 0
	global_load_dwordx4 v[26:29], v[6:7], off offset:16 nt
	v_lshlrev_b32_e32 v30, 16, v42
	v_and_b32_e32 v31, 0xffff0000, v42
	v_lshlrev_b32_e32 v32, 16, v43
	v_and_b32_e32 v33, 0xffff0000, v43
	v_lshlrev_b32_e32 v34, 16, v44
	v_and_b32_e32 v35, 0xffff0000, v44
	v_lshlrev_b32_e32 v36, 16, v45
	v_and_b32_e32 v37, 0xffff0000, v45
	v_mul_f32_e32 v30, v46, v30
	v_mul_f32_e32 v31, v46, v31
	v_mul_f32_e32 v32, v46, v32
	v_mul_f32_e32 v33, v46, v33
	v_mul_f32_e32 v34, v46, v34
	v_mul_f32_e32 v35, v46, v35
	v_mul_f32_e32 v36, v46, v36
	v_mul_f32_e32 v37, v46, v37
	s_waitcnt vmcnt(1)
	v_mul_f32_e32 v22, v22, v30
	v_mul_f32_e32 v23, v23, v31
	v_mul_f32_e32 v24, v24, v32
	v_mul_f32_e32 v25, v25, v33
	s_waitcnt vmcnt(0)
	v_mul_f32_e32 v26, v26, v34
	v_mul_f32_e32 v27, v27, v35
	v_mul_f32_e32 v28, v28, v36
	v_mul_f32_e32 v29, v29, v37
	global_store_dwordx4 v[10:11], v[22:25], off offset:2048 nt
	global_store_dwordx4 v[10:11], v[26:29], off offset:2064 nt
	v_lshl_add_u64 v[10:11], v[10:11], 0, s[4:5]
	s_andn2_b64 exec, exec, s[8:9]
	s_cbranch_execz .LBB0_1110
